# loop-edge edits (asm guide 7.11): in 7 GEMM K-loops the counter/pointer update block moved in front of the loop-back barrier and the next-unit pointer selects moved behind the first load segment's LDS
# baseline (speedup 1.0000x reference)
; #define PG8_STAGE(bufoff, gbase, voff) do { _Pragma("unroll") for (int _i = 0; _i < 2; ++_i) \
;         __builtin_amdgcn_global_load_lds((const unsigned*)((const char*)(gbase) + (voff)[_i]), (PG8_LAS unsigned*)(lds + (bufoff) + ldsw + _i * 8192), 16, 0, 0); } while (0)
; #define PG8_LDA(dst, b, h) do { _Pragma("unroll") for (int m = 0; m < 4; ++m) _Pragma("unroll") for (int k = 0; k < 2; ++k) dst[m][k] = *(const PG8_LAS bf16x8*)(lds + PG8_SA(b, h) + aoff + m * 2048 + k * 1024); } while (0)
; #define PG8_LDB(dst, b, h) do { _Pragma("unroll") for (int n = 0; n < 2; ++n) _Pragma("unroll") for (int k = 0; k < 2; ++k) dst[n][k] = *(const PG8_LAS bf16x8*)(lds + PG8_SB(b, h) + boff + n * 2048 + k * 1024); } while (0)
; #define PG8_MMA(ai, bj, At, Bt) do { __builtin_amdgcn_s_setprio(1); _Pragma("unroll") for (int m = 0; m < 4; ++m) _Pragma("unroll") for (int n = 0; n < 2; ++n) _Pragma("unroll") for (int k = 0; k < 2; ++k) \
;         acc[ai][bj][m][n] = __builtin_amdgcn_mfma_f32_16x16x32_bf16(Bt[n][k], At[m][k], acc[ai][bj][m][n], 0, 0, 0); __builtin_amdgcn_s_setprio(0); } while (0)
; #define PG8_WAIT_V(n) asm volatile("s_waitcnt vmcnt(" #n ")" ::: "memory")
; #define PG8_WAIT_L(n) asm volatile("s_waitcnt lgkmcnt(" #n ")" ::: "memory")
; #define PG8_BAR __builtin_amdgcn_s_barrier()
; #define PG8_SCHED __builtin_amdgcn_sched_barrier(0)
; template <class Epi, class Sched, bool ALIGN_EPI = true, bool SP2 = true, bool GS = false>
; __device__ __forceinline__ void gemm_phase(PG8_LAS unsigned char* lds, const Gemm g, const Sched& S, const Epi& E, const float* gs_ss = nullptr) {
;     ...
;         for (int t = 0; t < nt; t += 2) {
;             const bool last = (t == nt - 2);
;             const char* a1 = cA + (size_t)(t + 1) * kstep;
;             const char* a2 = last ? nA : cA + (size_t)(t + 2) * kstep; const char* b2 = last ? nB : cB + (size_t)(t + 2) * kstep;
;             const char* a3 = a2 + kstep; const char* b3 = b2 + kstep;
;             if constexpr (SP2) {
;             PG8_LDB(B0, 0, 0); PG8_LDB(B1, 0, 1); PG8_SCHED; PG8_LDA(At, 0, 0); PG8_STAGE(PG8_SA(1, 1), a1 + hstep, voffA);
;             PG8_WAIT_V(8); PG8_WAIT_L(0); PG8_BAR; PG8_MMA(0, 0, At, B0); PG8_MMA(0, 1, At, B1); PG8_BAR; PG8_SCHED;
;             PG8_LDA(At, 0, 1); PG8_STAGE(PG8_SB(0, 0), b2, voffB); PG8_STAGE(PG8_SB(0, 1), b2 + hstep, voffB); PG8_STAGE(PG8_SA(0, 0), a2, voffA);
.LBB0_151:
	s_add_i32 s67, 0, 0x10000
	v_add_u32_e32 v0, s67, v167
	s_add_i32 s69, 0, 0x14000
	ds_read_b128 v[146:149], v0
	ds_read_b128 v[150:153], v0 offset:1024
	ds_read_b128 v[154:157], v0 offset:2048
	ds_read_b128 v[158:161], v0 offset:3072
	v_add_u32_e32 v0, s69, v167
	ds_read_b128 v[162:165], v0
	ds_read_b128 v[172:175], v0 offset:1024
	ds_read_b128 v[180:183], v0 offset:2048
	ds_read_b128 v[184:187], v0 offset:3072
	v_lshl_add_u64 v[176:177], s[40:41], 0, v[142:143]
	s_add_i32 m0, s24, 0xc000
	ds_read_b128 v[188:191], v171
	ds_read_b128 v[192:195], v171 offset:1024
	ds_read_b128 v[196:199], v171 offset:2048
	ds_read_b128 v[200:203], v171 offset:3072
	ds_read_b128 v[204:207], v171 offset:4096
	ds_read_b128 v[208:211], v171 offset:5120
	ds_read_b128 v[212:215], v171 offset:6144
	ds_read_b128 v[216:219], v171 offset:7168
	global_load_lds_dwordx4 v[176:177], off
	v_lshl_add_u64 v[176:177], s[40:41], 0, v[144:145]
	s_add_i32 m0, s24, 0xe000
	s_nop 0
	global_load_lds_dwordx4 v[176:177], off
	s_add_u32 s2, s40, 0xfff80080
	s_addc_u32 s3, s41, -1
	s_cmp_eq_u32 s65, 28
	s_cselect_b32 s21, s13, s3
	s_cselect_b32 s20, s53, s2
	s_cselect_b32 s3, s51, s43
	s_cselect_b32 s2, s64, s42
	s_waitcnt vmcnt(8)
	s_waitcnt lgkmcnt(0)
	s_barrier
	s_setprio 1
	s_waitcnt lgkmcnt(0)
	v_mfma_f32_16x16x32_bf16 v[126:129], v[146:149], v[188:191], v[126:129]
	v_mfma_f32_16x16x32_bf16 v[122:125], v[154:157], v[188:191], v[122:125]
	v_mfma_f32_16x16x32_bf16 v[110:113], v[146:149], v[196:199], v[110:113]
	v_mfma_f32_16x16x32_bf16 v[106:109], v[154:157], v[196:199], v[106:109]
	v_mfma_f32_16x16x32_bf16 v[94:97], v[146:149], v[204:207], v[94:97]
	v_mfma_f32_16x16x32_bf16 v[90:93], v[154:157], v[204:207], v[90:93]
	v_mfma_f32_16x16x32_bf16 v[78:81], v[146:149], v[212:215], v[78:81]
	v_mfma_f32_16x16x32_bf16 v[74:77], v[154:157], v[212:215], v[74:77]
	v_mfma_f32_16x16x32_bf16 v[126:129], v[150:153], v[192:195], v[126:129]
	v_mfma_f32_16x16x32_bf16 v[122:125], v[158:161], v[192:195], v[122:125]
	v_mfma_f32_16x16x32_bf16 v[110:113], v[150:153], v[200:203], v[110:113]
	v_mfma_f32_16x16x32_bf16 v[106:109], v[158:161], v[200:203], v[106:109]
	v_mfma_f32_16x16x32_bf16 v[94:97], v[150:153], v[208:211], v[94:97]
	v_mfma_f32_16x16x32_bf16 v[90:93], v[158:161], v[208:211], v[90:93]
	v_mfma_f32_16x16x32_bf16 v[78:81], v[150:153], v[216:219], v[78:81]
	v_mfma_f32_16x16x32_bf16 v[74:77], v[158:161], v[216:219], v[74:77]
	s_setprio 0
	s_setprio 1
	v_mfma_f32_16x16x32_bf16 v[118:121], v[162:165], v[188:191], v[118:121]
	v_mfma_f32_16x16x32_bf16 v[114:117], v[180:183], v[188:191], v[114:117]
	v_mfma_f32_16x16x32_bf16 v[102:105], v[162:165], v[196:199], v[102:105]
	v_mfma_f32_16x16x32_bf16 v[98:101], v[180:183], v[196:199], v[98:101]
	v_mfma_f32_16x16x32_bf16 v[86:89], v[162:165], v[204:207], v[86:89]
	v_mfma_f32_16x16x32_bf16 v[82:85], v[180:183], v[204:207], v[82:85]
	v_mfma_f32_16x16x32_bf16 v[70:73], v[162:165], v[212:215], v[70:73]
	v_mfma_f32_16x16x32_bf16 v[66:69], v[180:183], v[212:215], v[66:69]
	v_mfma_f32_16x16x32_bf16 v[118:121], v[172:175], v[192:195], v[118:121]
	v_mfma_f32_16x16x32_bf16 v[114:117], v[184:187], v[192:195], v[114:117]
	v_mfma_f32_16x16x32_bf16 v[102:105], v[172:175], v[200:203], v[102:105]
	v_mfma_f32_16x16x32_bf16 v[98:101], v[184:187], v[200:203], v[98:101]
	v_mfma_f32_16x16x32_bf16 v[86:89], v[172:175], v[208:211], v[86:89]
	v_mfma_f32_16x16x32_bf16 v[82:85], v[184:187], v[208:211], v[82:85]
	v_mfma_f32_16x16x32_bf16 v[70:73], v[172:175], v[216:219], v[70:73]
	v_mfma_f32_16x16x32_bf16 v[66:69], v[184:187], v[216:219], v[66:69]
	s_setprio 0
	s_barrier
	s_add_i32 s67, s67, s23
	v_lshl_add_u64 v[176:177], s[2:3], 0, v[132:133]
	s_mov_b32 m0, s67
	ds_read_b128 v[188:191], v171 offset:16384
	ds_read_b128 v[192:195], v171 offset:17408
	ds_read_b128 v[196:199], v171 offset:18432
	ds_read_b128 v[200:203], v171 offset:19456
	ds_read_b128 v[204:207], v171 offset:20480
	ds_read_b128 v[208:211], v171 offset:21504
	ds_read_b128 v[212:215], v171 offset:22528
	ds_read_b128 v[216:219], v171 offset:23552
	global_load_lds_dwordx4 v[176:177], off
	s_add_i32 m0, s67, 0x2000
	s_add_u32 s70, s2, 0x80000
	v_lshl_add_u64 v[220:221], s[2:3], 0, v[136:137]
	s_addc_u32 s71, s3, 0
	s_add_i32 s67, s69, s23
	global_load_lds_dwordx4 v[220:221], off
	v_lshl_add_u64 v[236:237], s[70:71], 0, v[132:133]
	s_mov_b32 m0, s67
	v_lshl_add_u64 v[238:239], s[20:21], 0, v[134:135]
	global_load_lds_dwordx4 v[236:237], off
	v_lshl_add_u64 v[236:237], s[70:71], 0, v[136:137]
	s_add_i32 m0, s67, 0x2000
	s_nop 0
	global_load_lds_dwordx4 v[236:237], off
	v_lshl_add_u64 v[236:237], s[20:21], 0, v[130:131]
	s_mov_b32 m0, s24
	s_nop 0
	global_load_lds_dwordx4 v[236:237], off
	s_mov_b32 m0, s25
	s_nop 0
	global_load_lds_dwordx4 v[238:239], off
	s_waitcnt vmcnt(8)
	s_waitcnt lgkmcnt(0)
	s_barrier
; #define PG8_STAGE(bufoff, gbase, voff) do { _Pragma("unroll") for (int _i = 0; _i < 2; ++_i) \
;         __builtin_amdgcn_global_load_lds((const unsigned*)((const char*)(gbase) + (voff)[_i]), (PG8_LAS unsigned*)(lds + (bufoff) + ldsw + _i * 8192), 16, 0, 0); } while (0)
; #define PG8_LDA(dst, b, h) do { _Pragma("unroll") for (int m = 0; m < 4; ++m) _Pragma("unroll") for (int k = 0; k < 2; ++k) dst[m][k] = *(const PG8_LAS bf16x8*)(lds + PG8_SA(b, h) + aoff + m * 2048 + k * 1024); } while (0)
; #define PG8_LDB(dst, b, h) do { _Pragma("unroll") for (int n = 0; n < 2; ++n) _Pragma("unroll") for (int k = 0; k < 2; ++k) dst[n][k] = *(const PG8_LAS bf16x8*)(lds + PG8_SB(b, h) + boff + n * 2048 + k * 1024); } while (0)
; #define PG8_MMA(ai, bj, At, Bt) do { __builtin_amdgcn_s_setprio(1); _Pragma("unroll") for (int m = 0; m < 4; ++m) _Pragma("unroll") for (int n = 0; n < 2; ++n) _Pragma("unroll") for (int k = 0; k < 2; ++k) \
;         acc[ai][bj][m][n] = __builtin_amdgcn_mfma_f32_16x16x32_bf16(Bt[n][k], At[m][k], acc[ai][bj][m][n], 0, 0, 0); __builtin_amdgcn_s_setprio(0); } while (0)
; #define PG8_WAIT_V(n) asm volatile("s_waitcnt vmcnt(" #n ")" ::: "memory")
; #define PG8_WAIT_L(n) asm volatile("s_waitcnt lgkmcnt(" #n ")" ::: "memory")
; #define PG8_BAR __builtin_amdgcn_s_barrier()
; #define PG8_SCHED __builtin_amdgcn_sched_barrier(0)
; template <class Epi, class Sched, bool ALIGN_EPI = true, bool SP2 = true, bool GS = false>
; __device__ __forceinline__ void gemm_phase(PG8_LAS unsigned char* lds, const Gemm g, const Sched& S, const Epi& E, const float* gs_ss = nullptr) {
;     ...
;             PG8_LDA(At, 0, 1); PG8_STAGE(PG8_SB(0, 0), b2, voffB); PG8_STAGE(PG8_SB(0, 1), b2 + hstep, voffB); PG8_STAGE(PG8_SA(0, 0), a2, voffA);
;             PG8_WAIT_V(8); PG8_WAIT_L(0); PG8_BAR; PG8_MMA(1, 0, At, B0); PG8_MMA(1, 1, At, B1); PG8_BAR; PG8_SCHED;
;             PG8_LDB(B0, 1, 0); PG8_LDB(B1, 1, 1); PG8_SCHED; PG8_LDA(At, 1, 0); PG8_STAGE(PG8_SA(0, 1), a2 + hstep, voffA);
;             PG8_WAIT_V(8); PG8_WAIT_L(0); PG8_BAR; PG8_MMA(0, 0, At, B0); PG8_MMA(0, 1, At, B1); PG8_BAR; PG8_SCHED;
	s_setprio 1
	s_waitcnt lgkmcnt(0)
	v_mfma_f32_16x16x32_bf16 v[62:65], v[146:149], v[188:191], v[62:65]
	v_mfma_f32_16x16x32_bf16 v[58:61], v[154:157], v[188:191], v[58:61]
	v_mfma_f32_16x16x32_bf16 v[46:49], v[146:149], v[196:199], v[46:49]
	v_mfma_f32_16x16x32_bf16 v[42:45], v[154:157], v[196:199], v[42:45]
	v_mfma_f32_16x16x32_bf16 v[30:33], v[146:149], v[204:207], v[30:33]
	v_mfma_f32_16x16x32_bf16 v[26:29], v[154:157], v[204:207], v[26:29]
	v_mfma_f32_16x16x32_bf16 v[14:17], v[146:149], v[212:215], v[14:17]
	v_mfma_f32_16x16x32_bf16 v[10:13], v[154:157], v[212:215], v[10:13]
	v_mfma_f32_16x16x32_bf16 v[62:65], v[150:153], v[192:195], v[62:65]
	v_mfma_f32_16x16x32_bf16 v[58:61], v[158:161], v[192:195], v[58:61]
	v_mfma_f32_16x16x32_bf16 v[46:49], v[150:153], v[200:203], v[46:49]
	v_mfma_f32_16x16x32_bf16 v[42:45], v[158:161], v[200:203], v[42:45]
	v_mfma_f32_16x16x32_bf16 v[30:33], v[150:153], v[208:211], v[30:33]
	v_mfma_f32_16x16x32_bf16 v[26:29], v[158:161], v[208:211], v[26:29]
	v_mfma_f32_16x16x32_bf16 v[14:17], v[150:153], v[216:219], v[14:17]
	v_mfma_f32_16x16x32_bf16 v[10:13], v[158:161], v[216:219], v[10:13]
	s_setprio 0
	s_setprio 1
	v_mfma_f32_16x16x32_bf16 v[54:57], v[162:165], v[188:191], v[54:57]
	v_mfma_f32_16x16x32_bf16 v[50:53], v[180:183], v[188:191], v[50:53]
	v_mfma_f32_16x16x32_bf16 v[38:41], v[162:165], v[196:199], v[38:41]
	v_mfma_f32_16x16x32_bf16 v[34:37], v[180:183], v[196:199], v[34:37]
	v_mfma_f32_16x16x32_bf16 v[22:25], v[162:165], v[204:207], v[22:25]
	v_mfma_f32_16x16x32_bf16 v[18:21], v[180:183], v[204:207], v[18:21]
	v_mfma_f32_16x16x32_bf16 v[6:9], v[162:165], v[212:215], v[6:9]
	v_mfma_f32_16x16x32_bf16 v[2:5], v[180:183], v[212:215], v[2:5]
	v_mfma_f32_16x16x32_bf16 v[54:57], v[172:175], v[192:195], v[54:57]
	v_mfma_f32_16x16x32_bf16 v[50:53], v[184:187], v[192:195], v[50:53]
	v_mfma_f32_16x16x32_bf16 v[38:41], v[172:175], v[200:203], v[38:41]
	v_mfma_f32_16x16x32_bf16 v[34:37], v[184:187], v[200:203], v[34:37]
	v_mfma_f32_16x16x32_bf16 v[22:25], v[172:175], v[208:211], v[22:25]
	v_mfma_f32_16x16x32_bf16 v[18:21], v[184:187], v[208:211], v[18:21]
	v_mfma_f32_16x16x32_bf16 v[6:9], v[172:175], v[216:219], v[6:9]
	v_mfma_f32_16x16x32_bf16 v[2:5], v[184:187], v[216:219], v[2:5]
	s_setprio 0
	s_barrier
	s_add_i32 s67, 0, 0x18000
	v_add_u32_e32 v0, s67, v167
	s_add_i32 s69, 0, 0x1c000
	ds_read_b128 v[146:149], v0
	ds_read_b128 v[150:153], v0 offset:1024
	ds_read_b128 v[154:157], v0 offset:2048
	ds_read_b128 v[158:161], v0 offset:3072
	v_add_u32_e32 v0, s69, v167
	ds_read_b128 v[162:165], v0
	ds_read_b128 v[172:175], v0 offset:1024
	ds_read_b128 v[180:183], v0 offset:2048
	ds_read_b128 v[184:187], v0 offset:3072
	s_add_u32 s20, s20, 0x80000
	s_addc_u32 s21, s21, 0
	s_mov_b32 m0, s30
	v_lshl_add_u64 v[240:241], s[20:21], 0, v[130:131]
	ds_read_b128 v[188:191], v171 offset:32768
	ds_read_b128 v[192:195], v171 offset:33792
	ds_read_b128 v[196:199], v171 offset:34816
	ds_read_b128 v[200:203], v171 offset:35840
	ds_read_b128 v[204:207], v171 offset:36864
	ds_read_b128 v[208:211], v171 offset:37888
	ds_read_b128 v[212:215], v171 offset:38912
	ds_read_b128 v[216:219], v171 offset:39936
	global_load_lds_dwordx4 v[240:241], off
	v_lshl_add_u64 v[240:241], s[20:21], 0, v[134:135]
	s_mov_b32 m0, s35
	s_nop 0
	global_load_lds_dwordx4 v[240:241], off
	s_waitcnt vmcnt(8)
	s_waitcnt lgkmcnt(0)
	s_barrier
	s_setprio 1
	s_waitcnt lgkmcnt(0)
	v_mfma_f32_16x16x32_bf16 v[126:129], v[146:149], v[188:191], v[126:129]
	v_mfma_f32_16x16x32_bf16 v[122:125], v[154:157], v[188:191], v[122:125]
	v_mfma_f32_16x16x32_bf16 v[110:113], v[146:149], v[196:199], v[110:113]
	v_mfma_f32_16x16x32_bf16 v[106:109], v[154:157], v[196:199], v[106:109]
	v_mfma_f32_16x16x32_bf16 v[94:97], v[146:149], v[204:207], v[94:97]
	v_mfma_f32_16x16x32_bf16 v[90:93], v[154:157], v[204:207], v[90:93]
	v_mfma_f32_16x16x32_bf16 v[78:81], v[146:149], v[212:215], v[78:81]
	v_mfma_f32_16x16x32_bf16 v[74:77], v[154:157], v[212:215], v[74:77]
	v_mfma_f32_16x16x32_bf16 v[126:129], v[150:153], v[192:195], v[126:129]
	v_mfma_f32_16x16x32_bf16 v[122:125], v[158:161], v[192:195], v[122:125]
	v_mfma_f32_16x16x32_bf16 v[110:113], v[150:153], v[200:203], v[110:113]
	v_mfma_f32_16x16x32_bf16 v[106:109], v[158:161], v[200:203], v[106:109]
	v_mfma_f32_16x16x32_bf16 v[94:97], v[150:153], v[208:211], v[94:97]
	v_mfma_f32_16x16x32_bf16 v[90:93], v[158:161], v[208:211], v[90:93]
	v_mfma_f32_16x16x32_bf16 v[78:81], v[150:153], v[216:219], v[78:81]
	v_mfma_f32_16x16x32_bf16 v[74:77], v[158:161], v[216:219], v[74:77]
	s_setprio 0
	s_setprio 1
	v_mfma_f32_16x16x32_bf16 v[118:121], v[162:165], v[188:191], v[118:121]
	v_mfma_f32_16x16x32_bf16 v[114:117], v[180:183], v[188:191], v[114:117]
	v_mfma_f32_16x16x32_bf16 v[102:105], v[162:165], v[196:199], v[102:105]
	v_mfma_f32_16x16x32_bf16 v[98:101], v[180:183], v[196:199], v[98:101]
	v_mfma_f32_16x16x32_bf16 v[86:89], v[162:165], v[204:207], v[86:89]
	v_mfma_f32_16x16x32_bf16 v[82:85], v[180:183], v[204:207], v[82:85]
	v_mfma_f32_16x16x32_bf16 v[70:73], v[162:165], v[212:215], v[70:73]
	v_mfma_f32_16x16x32_bf16 v[66:69], v[180:183], v[212:215], v[66:69]
	v_mfma_f32_16x16x32_bf16 v[118:121], v[172:175], v[192:195], v[118:121]
	v_mfma_f32_16x16x32_bf16 v[114:117], v[184:187], v[192:195], v[114:117]
	v_mfma_f32_16x16x32_bf16 v[102:105], v[172:175], v[200:203], v[102:105]
	v_mfma_f32_16x16x32_bf16 v[98:101], v[184:187], v[200:203], v[98:101]
	v_mfma_f32_16x16x32_bf16 v[86:89], v[172:175], v[208:211], v[86:89]
	v_mfma_f32_16x16x32_bf16 v[82:85], v[184:187], v[208:211], v[82:85]
	v_mfma_f32_16x16x32_bf16 v[70:73], v[172:175], v[216:219], v[70:73]
	v_mfma_f32_16x16x32_bf16 v[66:69], v[184:187], v[216:219], v[66:69]
	s_setprio 0
	s_barrier
; #define PG8_STAGE(bufoff, gbase, voff) do { _Pragma("unroll") for (int _i = 0; _i < 2; ++_i) \
;         __builtin_amdgcn_global_load_lds((const unsigned*)((const char*)(gbase) + (voff)[_i]), (PG8_LAS unsigned*)(lds + (bufoff) + ldsw + _i * 8192), 16, 0, 0); } while (0)
; #define PG8_LDA(dst, b, h) do { _Pragma("unroll") for (int m = 0; m < 4; ++m) _Pragma("unroll") for (int k = 0; k < 2; ++k) dst[m][k] = *(const PG8_LAS bf16x8*)(lds + PG8_SA(b, h) + aoff + m * 2048 + k * 1024); } while (0)
; #define PG8_MMA(ai, bj, At, Bt) do { __builtin_amdgcn_s_setprio(1); _Pragma("unroll") for (int m = 0; m < 4; ++m) _Pragma("unroll") for (int n = 0; n < 2; ++n) _Pragma("unroll") for (int k = 0; k < 2; ++k) \
;         acc[ai][bj][m][n] = __builtin_amdgcn_mfma_f32_16x16x32_bf16(Bt[n][k], At[m][k], acc[ai][bj][m][n], 0, 0, 0); __builtin_amdgcn_s_setprio(0); } while (0)
; #define PG8_WAIT_V(n) asm volatile("s_waitcnt vmcnt(" #n ")" ::: "memory")
; #define PG8_WAIT_L(n) asm volatile("s_waitcnt lgkmcnt(" #n ")" ::: "memory")
; #define PG8_BAR __builtin_amdgcn_s_barrier()
; #define PG8_SCHED __builtin_amdgcn_sched_barrier(0)
; template <class Epi, class Sched, bool ALIGN_EPI = true, bool SP2 = true, bool GS = false>
; __device__ __forceinline__ void gemm_phase(PG8_LAS unsigned char* lds, const Gemm g, const Sched& S, const Epi& E, const float* gs_ss = nullptr) {
;     ...
;         for (int t = 0; t < nt; t += 2) {
;     ...
;             PG8_WAIT_V(8); PG8_WAIT_L(0); PG8_BAR; PG8_MMA(0, 0, At, B0); PG8_MMA(0, 1, At, B1); PG8_BAR; PG8_SCHED;
;             PG8_LDA(At, 1, 1); PG8_STAGE(PG8_SB(1, 0), b3, voffB); PG8_STAGE(PG8_SB(1, 1), b3 + hstep, voffB); PG8_STAGE(PG8_SA(1, 0), a3, voffA);
;             PG8_WAIT_V(8); PG8_WAIT_L(0); PG8_BAR; PG8_MMA(1, 0, At, B0); PG8_MMA(1, 1, At, B1); PG8_BAR; PG8_SCHED;
	s_add_i32 s20, s67, s23
	v_lshl_add_u64 v[176:177], v[176:177], 0, s[26:27]
	s_mov_b32 m0, s20
	ds_read_b128 v[188:191], v171 offset:49152
	ds_read_b128 v[192:195], v171 offset:50176
	ds_read_b128 v[196:199], v171 offset:51200
	ds_read_b128 v[200:203], v171 offset:52224
	ds_read_b128 v[204:207], v171 offset:53248
	ds_read_b128 v[208:211], v171 offset:54272
	ds_read_b128 v[212:215], v171 offset:55296
	ds_read_b128 v[216:219], v171 offset:56320
	global_load_lds_dwordx4 v[176:177], off
	s_add_i32 m0, s20, 0x2000
	s_add_u32 s2, s2, 0x80080
	v_lshl_add_u64 v[176:177], v[220:221], 0, s[26:27]
	s_addc_u32 s3, s3, 0
	s_add_i32 s20, s69, s23
	global_load_lds_dwordx4 v[176:177], off
	v_lshl_add_u64 v[176:177], s[2:3], 0, v[132:133]
	s_mov_b32 m0, s20
	s_nop 0
	global_load_lds_dwordx4 v[176:177], off
	v_lshl_add_u64 v[176:177], s[2:3], 0, v[136:137]
	s_add_i32 m0, s20, 0x2000
	s_nop 0
	global_load_lds_dwordx4 v[176:177], off
	v_lshl_add_u64 v[176:177], v[236:237], 0, s[26:27]
	s_mov_b32 m0, s59
	s_nop 0
	global_load_lds_dwordx4 v[176:177], off
	v_lshl_add_u64 v[176:177], v[238:239], 0, s[26:27]
	s_mov_b32 m0, s60
	s_nop 0
	global_load_lds_dwordx4 v[176:177], off
	s_waitcnt vmcnt(8)
	s_waitcnt lgkmcnt(0)
	s_barrier
	s_setprio 1
	s_waitcnt lgkmcnt(0)
	v_mfma_f32_16x16x32_bf16 v[62:65], v[146:149], v[188:191], v[62:65]
	v_mfma_f32_16x16x32_bf16 v[58:61], v[154:157], v[188:191], v[58:61]
	v_mfma_f32_16x16x32_bf16 v[46:49], v[146:149], v[196:199], v[46:49]
	v_mfma_f32_16x16x32_bf16 v[42:45], v[154:157], v[196:199], v[42:45]
	v_mfma_f32_16x16x32_bf16 v[30:33], v[146:149], v[204:207], v[30:33]
	v_mfma_f32_16x16x32_bf16 v[26:29], v[154:157], v[204:207], v[26:29]
	v_mfma_f32_16x16x32_bf16 v[14:17], v[146:149], v[212:215], v[14:17]
	v_mfma_f32_16x16x32_bf16 v[10:13], v[154:157], v[212:215], v[10:13]
	v_mfma_f32_16x16x32_bf16 v[62:65], v[150:153], v[192:195], v[62:65]
	v_mfma_f32_16x16x32_bf16 v[58:61], v[158:161], v[192:195], v[58:61]
	v_mfma_f32_16x16x32_bf16 v[46:49], v[150:153], v[200:203], v[46:49]
	v_mfma_f32_16x16x32_bf16 v[42:45], v[158:161], v[200:203], v[42:45]
	v_mfma_f32_16x16x32_bf16 v[30:33], v[150:153], v[208:211], v[30:33]
	v_mfma_f32_16x16x32_bf16 v[26:29], v[158:161], v[208:211], v[26:29]
	v_mfma_f32_16x16x32_bf16 v[14:17], v[150:153], v[216:219], v[14:17]
	v_mfma_f32_16x16x32_bf16 v[10:13], v[158:161], v[216:219], v[10:13]
	s_setprio 0
	s_setprio 1
	v_mfma_f32_16x16x32_bf16 v[54:57], v[162:165], v[188:191], v[54:57]
	v_mfma_f32_16x16x32_bf16 v[50:53], v[180:183], v[188:191], v[50:53]
	v_mfma_f32_16x16x32_bf16 v[38:41], v[162:165], v[196:199], v[38:41]
	v_mfma_f32_16x16x32_bf16 v[34:37], v[180:183], v[196:199], v[34:37]
	v_mfma_f32_16x16x32_bf16 v[22:25], v[162:165], v[204:207], v[22:25]
	v_mfma_f32_16x16x32_bf16 v[18:21], v[180:183], v[204:207], v[18:21]
	v_mfma_f32_16x16x32_bf16 v[6:9], v[162:165], v[212:215], v[6:9]
	v_mfma_f32_16x16x32_bf16 v[2:5], v[180:183], v[212:215], v[2:5]
	v_mfma_f32_16x16x32_bf16 v[54:57], v[172:175], v[192:195], v[54:57]
	v_mfma_f32_16x16x32_bf16 v[50:53], v[184:187], v[192:195], v[50:53]
	v_mfma_f32_16x16x32_bf16 v[38:41], v[172:175], v[200:203], v[38:41]
	v_mfma_f32_16x16x32_bf16 v[34:37], v[184:187], v[200:203], v[34:37]
	v_mfma_f32_16x16x32_bf16 v[22:25], v[172:175], v[208:211], v[22:25]
	v_mfma_f32_16x16x32_bf16 v[18:21], v[184:187], v[208:211], v[18:21]
	v_mfma_f32_16x16x32_bf16 v[6:9], v[172:175], v[216:219], v[6:9]
	v_mfma_f32_16x16x32_bf16 v[2:5], v[184:187], v[216:219], v[2:5]
	s_setprio 0
	s_add_i32 s65, s65, 2
	s_add_u32 s40, s40, 0x100
	s_addc_u32 s41, s41, 0
	s_add_u32 s42, s42, 0x100
	s_addc_u32 s43, s43, 0
	s_cmp_gt_u32 s65, 29
	s_barrier
	s_cbranch_scc0 .LBB0_151
	s_and_b64 vcc, exec, s[46:47]
	s_cbranch_vccz .LBB0_154
	s_barrier

; #define PG8_STAGE(bufoff, gbase, voff) do { _Pragma("unroll") for (int _i = 0; _i < 2; ++_i) \
;         __builtin_amdgcn_global_load_lds((const unsigned*)((const char*)(gbase) + (voff)[_i]), (PG8_LAS unsigned*)(lds + (bufoff) + ldsw + _i * 8192), 16, 0, 0); } while (0)
; #define PG8_LDA(dst, b, h) do { _Pragma("unroll") for (int m = 0; m < 4; ++m) _Pragma("unroll") for (int k = 0; k < 2; ++k) dst[m][k] = *(const PG8_LAS bf16x8*)(lds + PG8_SA(b, h) + aoff + m * 2048 + k * 1024); } while (0)
; #define PG8_LDB(dst, b, h) do { _Pragma("unroll") for (int n = 0; n < 2; ++n) _Pragma("unroll") for (int k = 0; k < 2; ++k) dst[n][k] = *(const PG8_LAS bf16x8*)(lds + PG8_SB(b, h) + boff + n * 2048 + k * 1024); } while (0)
; #define PG8_MMA(ai, bj, At, Bt) do { __builtin_amdgcn_s_setprio(1); _Pragma("unroll") for (int m = 0; m < 4; ++m) _Pragma("unroll") for (int n = 0; n < 2; ++n) _Pragma("unroll") for (int k = 0; k < 2; ++k) \
;         acc[ai][bj][m][n] = __builtin_amdgcn_mfma_f32_16x16x32_bf16(Bt[n][k], At[m][k], acc[ai][bj][m][n], 0, 0, 0); __builtin_amdgcn_s_setprio(0); } while (0)
; #define PG8_WAIT_V(n) asm volatile("s_waitcnt vmcnt(" #n ")" ::: "memory")
; #define PG8_WAIT_L(n) asm volatile("s_waitcnt lgkmcnt(" #n ")" ::: "memory")
; #define PG8_BAR __builtin_amdgcn_s_barrier()
; #define PG8_SCHED __builtin_amdgcn_sched_barrier(0)
; template <class Epi, class Sched, bool ALIGN_EPI = true, bool SP2 = true, bool GS = false>
; __device__ __forceinline__ void gemm_phase(PG8_LAS unsigned char* lds, const Gemm g, const Sched& S, const Epi& E, const float* gs_ss = nullptr) {
;     ...
;         for (int t = 0; t < nt; t += 2) {
;             const bool last = (t == nt - 2);
;             const char* a1 = cA + (size_t)(t + 1) * kstep;
;             const char* a2 = last ? nA : cA + (size_t)(t + 2) * kstep; const char* b2 = last ? nB : cB + (size_t)(t + 2) * kstep;
;             const char* a3 = a2 + kstep; const char* b3 = b2 + kstep;
;             if constexpr (SP2) {
;             PG8_LDB(B0, 0, 0); PG8_LDB(B1, 0, 1); PG8_SCHED; PG8_LDA(At, 0, 0); PG8_STAGE(PG8_SA(1, 1), a1 + hstep, voffA);
;             PG8_WAIT_V(8); PG8_WAIT_L(0); PG8_BAR; PG8_MMA(0, 0, At, B0); PG8_MMA(0, 1, At, B1); PG8_BAR; PG8_SCHED;
;             PG8_LDA(At, 0, 1); PG8_STAGE(PG8_SB(0, 0), b2, voffB); PG8_STAGE(PG8_SB(0, 1), b2 + hstep, voffB); PG8_STAGE(PG8_SA(0, 0), a2, voffA);
.LBB0_314:
	s_add_i32 s64, 0, 0x10000
	v_add_u32_e32 v0, s64, v173
	s_add_i32 s67, 0, 0x14000
	ds_read_b128 v[130:133], v0
	ds_read_b128 v[150:153], v0 offset:1024
	ds_read_b128 v[154:157], v0 offset:2048
	ds_read_b128 v[158:161], v0 offset:3072
	v_add_u32_e32 v0, s67, v173
	ds_read_b128 v[162:165], v0
	ds_read_b128 v[166:169], v0 offset:1024
	ds_read_b128 v[188:191], v0 offset:2048
	ds_read_b128 v[192:195], v0 offset:3072
	v_lshl_add_u64 v[170:171], s[38:39], 0, v[146:147]
	s_add_i32 m0, s24, 0xc000
	ds_read_b128 v[196:199], v177
	ds_read_b128 v[200:203], v177 offset:1024
	ds_read_b128 v[204:207], v177 offset:2048
	ds_read_b128 v[208:211], v177 offset:3072
	ds_read_b128 v[212:215], v177 offset:4096
	ds_read_b128 v[216:219], v177 offset:5120
	ds_read_b128 v[236:239], v177 offset:6144
	ds_read_b128 v[240:243], v177 offset:7168
	global_load_lds_dwordx4 v[170:171], off
	v_lshl_add_u64 v[170:171], s[38:39], 0, v[148:149]
	s_add_i32 m0, s24, 0xe000
	s_nop 0
	global_load_lds_dwordx4 v[170:171], off
	s_add_u32 s2, s38, 0xfff80080
	s_addc_u32 s3, s39, -1
	s_cmp_eq_u32 s51, 28
	s_cselect_b32 s21, s13, s3
	s_cselect_b32 s20, s16, s2
	s_cselect_b32 s3, s17, s41
	s_cselect_b32 s2, s49, s40
	s_waitcnt vmcnt(8)
	s_waitcnt lgkmcnt(0)
	s_barrier
	s_setprio 1
	s_waitcnt lgkmcnt(0)
	v_mfma_f32_16x16x32_bf16 v[126:129], v[130:133], v[196:199], v[126:129]
	v_mfma_f32_16x16x32_bf16 v[122:125], v[154:157], v[196:199], v[122:125]
	v_mfma_f32_16x16x32_bf16 v[118:121], v[130:133], v[204:207], v[118:121]
	v_mfma_f32_16x16x32_bf16 v[110:113], v[154:157], v[204:207], v[110:113]
	v_mfma_f32_16x16x32_bf16 v[102:105], v[130:133], v[212:215], v[102:105]
	v_mfma_f32_16x16x32_bf16 v[94:97], v[154:157], v[212:215], v[94:97]
	v_mfma_f32_16x16x32_bf16 v[86:89], v[130:133], v[236:239], v[86:89]
	v_mfma_f32_16x16x32_bf16 v[78:81], v[154:157], v[236:239], v[78:81]
	v_mfma_f32_16x16x32_bf16 v[126:129], v[150:153], v[200:203], v[126:129]
	v_mfma_f32_16x16x32_bf16 v[122:125], v[158:161], v[200:203], v[122:125]
	v_mfma_f32_16x16x32_bf16 v[118:121], v[150:153], v[208:211], v[118:121]
	v_mfma_f32_16x16x32_bf16 v[110:113], v[158:161], v[208:211], v[110:113]
	v_mfma_f32_16x16x32_bf16 v[102:105], v[150:153], v[216:219], v[102:105]
	v_mfma_f32_16x16x32_bf16 v[94:97], v[158:161], v[216:219], v[94:97]
	v_mfma_f32_16x16x32_bf16 v[86:89], v[150:153], v[240:243], v[86:89]
	v_mfma_f32_16x16x32_bf16 v[78:81], v[158:161], v[240:243], v[78:81]
	s_setprio 0
	s_setprio 1
	v_mfma_f32_16x16x32_bf16 v[114:117], v[162:165], v[196:199], v[114:117]
	v_mfma_f32_16x16x32_bf16 v[106:109], v[188:191], v[196:199], v[106:109]
	v_mfma_f32_16x16x32_bf16 v[98:101], v[162:165], v[204:207], v[98:101]
	v_mfma_f32_16x16x32_bf16 v[90:93], v[188:191], v[204:207], v[90:93]
	v_mfma_f32_16x16x32_bf16 v[82:85], v[162:165], v[212:215], v[82:85]
	v_mfma_f32_16x16x32_bf16 v[74:77], v[188:191], v[212:215], v[74:77]
	v_mfma_f32_16x16x32_bf16 v[70:73], v[162:165], v[236:239], v[70:73]
	v_mfma_f32_16x16x32_bf16 v[66:69], v[188:191], v[236:239], v[66:69]
	v_mfma_f32_16x16x32_bf16 v[114:117], v[166:169], v[200:203], v[114:117]
	v_mfma_f32_16x16x32_bf16 v[106:109], v[192:195], v[200:203], v[106:109]
	v_mfma_f32_16x16x32_bf16 v[98:101], v[166:169], v[208:211], v[98:101]
	v_mfma_f32_16x16x32_bf16 v[90:93], v[192:195], v[208:211], v[90:93]
	v_mfma_f32_16x16x32_bf16 v[82:85], v[166:169], v[216:219], v[82:85]
	v_mfma_f32_16x16x32_bf16 v[74:77], v[192:195], v[216:219], v[74:77]
	v_mfma_f32_16x16x32_bf16 v[70:73], v[166:169], v[240:243], v[70:73]
	v_mfma_f32_16x16x32_bf16 v[66:69], v[192:195], v[240:243], v[66:69]
	s_setprio 0
	s_barrier
	s_add_i32 s64, s64, s23
	v_lshl_add_u64 v[170:171], s[2:3], 0, v[136:137]
	s_mov_b32 m0, s64
	ds_read_b128 v[196:199], v177 offset:16384
	ds_read_b128 v[200:203], v177 offset:17408
	ds_read_b128 v[204:207], v177 offset:18432
	ds_read_b128 v[208:211], v177 offset:19456
	ds_read_b128 v[212:215], v177 offset:20480
	ds_read_b128 v[216:219], v177 offset:21504
	ds_read_b128 v[236:239], v177 offset:22528
	ds_read_b128 v[240:243], v177 offset:23552
	global_load_lds_dwordx4 v[170:171], off
	s_add_i32 m0, s64, 0x2000
	s_add_u32 s64, s2, 0x80000
	v_lshl_add_u64 v[180:181], s[2:3], 0, v[140:141]
	s_addc_u32 s65, s3, 0
	s_add_i32 s67, s67, s23
	global_load_lds_dwordx4 v[180:181], off
	v_lshl_add_u64 v[182:183], s[64:65], 0, v[136:137]
	s_mov_b32 m0, s67
	v_lshl_add_u64 v[184:185], s[20:21], 0, v[138:139]
	global_load_lds_dwordx4 v[182:183], off
	v_lshl_add_u64 v[182:183], s[64:65], 0, v[140:141]
	s_add_i32 m0, s67, 0x2000
	s_nop 0
	global_load_lds_dwordx4 v[182:183], off
	v_lshl_add_u64 v[182:183], s[20:21], 0, v[134:135]
	s_mov_b32 m0, s24
	s_nop 0
	global_load_lds_dwordx4 v[182:183], off
	s_mov_b32 m0, s25
	s_nop 0
	global_load_lds_dwordx4 v[184:185], off
	s_waitcnt vmcnt(8)
	s_waitcnt lgkmcnt(0)
	s_barrier
; #define PG8_STAGE(bufoff, gbase, voff) do { _Pragma("unroll") for (int _i = 0; _i < 2; ++_i) \
;         __builtin_amdgcn_global_load_lds((const unsigned*)((const char*)(gbase) + (voff)[_i]), (PG8_LAS unsigned*)(lds + (bufoff) + ldsw + _i * 8192), 16, 0, 0); } while (0)
; #define PG8_LDA(dst, b, h) do { _Pragma("unroll") for (int m = 0; m < 4; ++m) _Pragma("unroll") for (int k = 0; k < 2; ++k) dst[m][k] = *(const PG8_LAS bf16x8*)(lds + PG8_SA(b, h) + aoff + m * 2048 + k * 1024); } while (0)
; #define PG8_LDB(dst, b, h) do { _Pragma("unroll") for (int n = 0; n < 2; ++n) _Pragma("unroll") for (int k = 0; k < 2; ++k) dst[n][k] = *(const PG8_LAS bf16x8*)(lds + PG8_SB(b, h) + boff + n * 2048 + k * 1024); } while (0)
; #define PG8_MMA(ai, bj, At, Bt) do { __builtin_amdgcn_s_setprio(1); _Pragma("unroll") for (int m = 0; m < 4; ++m) _Pragma("unroll") for (int n = 0; n < 2; ++n) _Pragma("unroll") for (int k = 0; k < 2; ++k) \
;         acc[ai][bj][m][n] = __builtin_amdgcn_mfma_f32_16x16x32_bf16(Bt[n][k], At[m][k], acc[ai][bj][m][n], 0, 0, 0); __builtin_amdgcn_s_setprio(0); } while (0)
; #define PG8_WAIT_V(n) asm volatile("s_waitcnt vmcnt(" #n ")" ::: "memory")
; #define PG8_WAIT_L(n) asm volatile("s_waitcnt lgkmcnt(" #n ")" ::: "memory")
; #define PG8_BAR __builtin_amdgcn_s_barrier()
; #define PG8_SCHED __builtin_amdgcn_sched_barrier(0)
; template <class Epi, class Sched, bool ALIGN_EPI = true, bool SP2 = true, bool GS = false>
; __device__ __forceinline__ void gemm_phase(PG8_LAS unsigned char* lds, const Gemm g, const Sched& S, const Epi& E, const float* gs_ss = nullptr) {
;     ...
;             PG8_LDA(At, 0, 1); PG8_STAGE(PG8_SB(0, 0), b2, voffB); PG8_STAGE(PG8_SB(0, 1), b2 + hstep, voffB); PG8_STAGE(PG8_SA(0, 0), a2, voffA);
;             PG8_WAIT_V(8); PG8_WAIT_L(0); PG8_BAR; PG8_MMA(1, 0, At, B0); PG8_MMA(1, 1, At, B1); PG8_BAR; PG8_SCHED;
;             PG8_LDB(B0, 1, 0); PG8_LDB(B1, 1, 1); PG8_SCHED; PG8_LDA(At, 1, 0); PG8_STAGE(PG8_SA(0, 1), a2 + hstep, voffA);
;             PG8_WAIT_V(8); PG8_WAIT_L(0); PG8_BAR; PG8_MMA(0, 0, At, B0); PG8_MMA(0, 1, At, B1); PG8_BAR; PG8_SCHED;
	s_setprio 1
	s_waitcnt lgkmcnt(0)
	v_mfma_f32_16x16x32_bf16 v[62:65], v[130:133], v[196:199], v[62:65]
	v_mfma_f32_16x16x32_bf16 v[58:61], v[154:157], v[196:199], v[58:61]
	v_mfma_f32_16x16x32_bf16 v[54:57], v[130:133], v[204:207], v[54:57]
	v_mfma_f32_16x16x32_bf16 v[46:49], v[154:157], v[204:207], v[46:49]
	v_mfma_f32_16x16x32_bf16 v[38:41], v[130:133], v[212:215], v[38:41]
	v_mfma_f32_16x16x32_bf16 v[30:33], v[154:157], v[212:215], v[30:33]
	v_mfma_f32_16x16x32_bf16 v[22:25], v[130:133], v[236:239], v[22:25]
	v_mfma_f32_16x16x32_bf16 v[14:17], v[154:157], v[236:239], v[14:17]
	v_mfma_f32_16x16x32_bf16 v[62:65], v[150:153], v[200:203], v[62:65]
	v_mfma_f32_16x16x32_bf16 v[58:61], v[158:161], v[200:203], v[58:61]
	v_mfma_f32_16x16x32_bf16 v[54:57], v[150:153], v[208:211], v[54:57]
	v_mfma_f32_16x16x32_bf16 v[46:49], v[158:161], v[208:211], v[46:49]
	v_mfma_f32_16x16x32_bf16 v[38:41], v[150:153], v[216:219], v[38:41]
	v_mfma_f32_16x16x32_bf16 v[30:33], v[158:161], v[216:219], v[30:33]
	v_mfma_f32_16x16x32_bf16 v[22:25], v[150:153], v[240:243], v[22:25]
	v_mfma_f32_16x16x32_bf16 v[14:17], v[158:161], v[240:243], v[14:17]
	s_setprio 0
	s_setprio 1
	v_mfma_f32_16x16x32_bf16 v[50:53], v[162:165], v[196:199], v[50:53]
	v_mfma_f32_16x16x32_bf16 v[42:45], v[188:191], v[196:199], v[42:45]
	v_mfma_f32_16x16x32_bf16 v[34:37], v[162:165], v[204:207], v[34:37]
	v_mfma_f32_16x16x32_bf16 v[26:29], v[188:191], v[204:207], v[26:29]
	v_mfma_f32_16x16x32_bf16 v[18:21], v[162:165], v[212:215], v[18:21]
	v_mfma_f32_16x16x32_bf16 v[10:13], v[188:191], v[212:215], v[10:13]
	v_mfma_f32_16x16x32_bf16 v[6:9], v[162:165], v[236:239], v[6:9]
	v_mfma_f32_16x16x32_bf16 v[2:5], v[188:191], v[236:239], v[2:5]
	v_mfma_f32_16x16x32_bf16 v[50:53], v[166:169], v[200:203], v[50:53]
	v_mfma_f32_16x16x32_bf16 v[42:45], v[192:195], v[200:203], v[42:45]
	v_mfma_f32_16x16x32_bf16 v[34:37], v[166:169], v[208:211], v[34:37]
	v_mfma_f32_16x16x32_bf16 v[26:29], v[192:195], v[208:211], v[26:29]
	v_mfma_f32_16x16x32_bf16 v[18:21], v[166:169], v[216:219], v[18:21]
	v_mfma_f32_16x16x32_bf16 v[10:13], v[192:195], v[216:219], v[10:13]
	v_mfma_f32_16x16x32_bf16 v[6:9], v[166:169], v[240:243], v[6:9]
	v_mfma_f32_16x16x32_bf16 v[2:5], v[192:195], v[240:243], v[2:5]
	s_setprio 0
	s_barrier
	s_add_i32 s64, 0, 0x18000
	v_add_u32_e32 v0, s64, v173
	s_add_i32 s65, 0, 0x1c000
	ds_read_b128 v[130:133], v0
	ds_read_b128 v[150:153], v0 offset:1024
	ds_read_b128 v[154:157], v0 offset:2048
	ds_read_b128 v[158:161], v0 offset:3072
	v_add_u32_e32 v0, s65, v173
	ds_read_b128 v[162:165], v0
	ds_read_b128 v[166:169], v0 offset:1024
	ds_read_b128 v[188:191], v0 offset:2048
	ds_read_b128 v[192:195], v0 offset:3072
	s_add_u32 s20, s20, 0x80000
	s_addc_u32 s21, s21, 0
	s_mov_b32 m0, s30
	v_lshl_add_u64 v[186:187], s[20:21], 0, v[134:135]
	ds_read_b128 v[196:199], v177 offset:32768
	ds_read_b128 v[200:203], v177 offset:33792
	ds_read_b128 v[204:207], v177 offset:34816
	ds_read_b128 v[208:211], v177 offset:35840
	ds_read_b128 v[212:215], v177 offset:36864
	ds_read_b128 v[216:219], v177 offset:37888
	ds_read_b128 v[236:239], v177 offset:38912
	ds_read_b128 v[240:243], v177 offset:39936
	global_load_lds_dwordx4 v[186:187], off
	v_lshl_add_u64 v[186:187], s[20:21], 0, v[138:139]
	s_mov_b32 m0, s36
	s_nop 0
	global_load_lds_dwordx4 v[186:187], off
	s_waitcnt vmcnt(8)
	s_waitcnt lgkmcnt(0)
	s_barrier
	s_setprio 1
	s_waitcnt lgkmcnt(0)
	v_mfma_f32_16x16x32_bf16 v[126:129], v[130:133], v[196:199], v[126:129]
	v_mfma_f32_16x16x32_bf16 v[122:125], v[154:157], v[196:199], v[122:125]
	v_mfma_f32_16x16x32_bf16 v[118:121], v[130:133], v[204:207], v[118:121]
	v_mfma_f32_16x16x32_bf16 v[110:113], v[154:157], v[204:207], v[110:113]
	v_mfma_f32_16x16x32_bf16 v[102:105], v[130:133], v[212:215], v[102:105]
	v_mfma_f32_16x16x32_bf16 v[94:97], v[154:157], v[212:215], v[94:97]
	v_mfma_f32_16x16x32_bf16 v[86:89], v[130:133], v[236:239], v[86:89]
	v_mfma_f32_16x16x32_bf16 v[78:81], v[154:157], v[236:239], v[78:81]
	v_mfma_f32_16x16x32_bf16 v[126:129], v[150:153], v[200:203], v[126:129]
	v_mfma_f32_16x16x32_bf16 v[122:125], v[158:161], v[200:203], v[122:125]
	v_mfma_f32_16x16x32_bf16 v[118:121], v[150:153], v[208:211], v[118:121]
	v_mfma_f32_16x16x32_bf16 v[110:113], v[158:161], v[208:211], v[110:113]
	v_mfma_f32_16x16x32_bf16 v[102:105], v[150:153], v[216:219], v[102:105]
	v_mfma_f32_16x16x32_bf16 v[94:97], v[158:161], v[216:219], v[94:97]
	v_mfma_f32_16x16x32_bf16 v[86:89], v[150:153], v[240:243], v[86:89]
	v_mfma_f32_16x16x32_bf16 v[78:81], v[158:161], v[240:243], v[78:81]
	s_setprio 0
	s_setprio 1
	v_mfma_f32_16x16x32_bf16 v[114:117], v[162:165], v[196:199], v[114:117]
	v_mfma_f32_16x16x32_bf16 v[106:109], v[188:191], v[196:199], v[106:109]
	v_mfma_f32_16x16x32_bf16 v[98:101], v[162:165], v[204:207], v[98:101]
	v_mfma_f32_16x16x32_bf16 v[90:93], v[188:191], v[204:207], v[90:93]
	v_mfma_f32_16x16x32_bf16 v[82:85], v[162:165], v[212:215], v[82:85]
	v_mfma_f32_16x16x32_bf16 v[74:77], v[188:191], v[212:215], v[74:77]
	v_mfma_f32_16x16x32_bf16 v[70:73], v[162:165], v[236:239], v[70:73]
	v_mfma_f32_16x16x32_bf16 v[66:69], v[188:191], v[236:239], v[66:69]
	v_mfma_f32_16x16x32_bf16 v[114:117], v[166:169], v[200:203], v[114:117]
	v_mfma_f32_16x16x32_bf16 v[106:109], v[192:195], v[200:203], v[106:109]
	v_mfma_f32_16x16x32_bf16 v[98:101], v[166:169], v[208:211], v[98:101]
	v_mfma_f32_16x16x32_bf16 v[90:93], v[192:195], v[208:211], v[90:93]
	v_mfma_f32_16x16x32_bf16 v[82:85], v[166:169], v[216:219], v[82:85]
	v_mfma_f32_16x16x32_bf16 v[74:77], v[192:195], v[216:219], v[74:77]
	v_mfma_f32_16x16x32_bf16 v[70:73], v[166:169], v[240:243], v[70:73]
	v_mfma_f32_16x16x32_bf16 v[66:69], v[192:195], v[240:243], v[66:69]
	s_setprio 0
	s_barrier
; #define PG8_STAGE(bufoff, gbase, voff) do { _Pragma("unroll") for (int _i = 0; _i < 2; ++_i) \
;         __builtin_amdgcn_global_load_lds((const unsigned*)((const char*)(gbase) + (voff)[_i]), (PG8_LAS unsigned*)(lds + (bufoff) + ldsw + _i * 8192), 16, 0, 0); } while (0)
; #define PG8_LDA(dst, b, h) do { _Pragma("unroll") for (int m = 0; m < 4; ++m) _Pragma("unroll") for (int k = 0; k < 2; ++k) dst[m][k] = *(const PG8_LAS bf16x8*)(lds + PG8_SA(b, h) + aoff + m * 2048 + k * 1024); } while (0)
; #define PG8_MMA(ai, bj, At, Bt) do { __builtin_amdgcn_s_setprio(1); _Pragma("unroll") for (int m = 0; m < 4; ++m) _Pragma("unroll") for (int n = 0; n < 2; ++n) _Pragma("unroll") for (int k = 0; k < 2; ++k) \
;         acc[ai][bj][m][n] = __builtin_amdgcn_mfma_f32_16x16x32_bf16(Bt[n][k], At[m][k], acc[ai][bj][m][n], 0, 0, 0); __builtin_amdgcn_s_setprio(0); } while (0)
; #define PG8_WAIT_V(n) asm volatile("s_waitcnt vmcnt(" #n ")" ::: "memory")
; #define PG8_WAIT_L(n) asm volatile("s_waitcnt lgkmcnt(" #n ")" ::: "memory")
; #define PG8_BAR __builtin_amdgcn_s_barrier()
; #define PG8_SCHED __builtin_amdgcn_sched_barrier(0)
; template <class Epi, class Sched, bool ALIGN_EPI = true, bool SP2 = true, bool GS = false>
; __device__ __forceinline__ void gemm_phase(PG8_LAS unsigned char* lds, const Gemm g, const Sched& S, const Epi& E, const float* gs_ss = nullptr) {
;     ...
;         for (int t = 0; t < nt; t += 2) {
;     ...
;             PG8_WAIT_V(8); PG8_WAIT_L(0); PG8_BAR; PG8_MMA(0, 0, At, B0); PG8_MMA(0, 1, At, B1); PG8_BAR; PG8_SCHED;
;             PG8_LDA(At, 1, 1); PG8_STAGE(PG8_SB(1, 0), b3, voffB); PG8_STAGE(PG8_SB(1, 1), b3 + hstep, voffB); PG8_STAGE(PG8_SA(1, 0), a3, voffA);
;             PG8_WAIT_V(8); PG8_WAIT_L(0); PG8_BAR; PG8_MMA(1, 0, At, B0); PG8_MMA(1, 1, At, B1); PG8_BAR; PG8_SCHED;
	s_add_i32 s20, s64, s23
	v_lshl_add_u64 v[170:171], v[170:171], 0, s[26:27]
	s_mov_b32 m0, s20
	ds_read_b128 v[196:199], v177 offset:49152
	ds_read_b128 v[200:203], v177 offset:50176
	ds_read_b128 v[204:207], v177 offset:51200
	ds_read_b128 v[208:211], v177 offset:52224
	ds_read_b128 v[212:215], v177 offset:53248
	ds_read_b128 v[216:219], v177 offset:54272
	ds_read_b128 v[236:239], v177 offset:55296
	ds_read_b128 v[240:243], v177 offset:56320
	global_load_lds_dwordx4 v[170:171], off
	s_add_i32 m0, s20, 0x2000
	s_add_u32 s2, s2, 0x80080
	v_lshl_add_u64 v[170:171], v[180:181], 0, s[26:27]
	s_addc_u32 s3, s3, 0
	s_add_i32 s20, s65, s23
	global_load_lds_dwordx4 v[170:171], off
	v_lshl_add_u64 v[170:171], s[2:3], 0, v[136:137]
	s_mov_b32 m0, s20
	s_nop 0
	global_load_lds_dwordx4 v[170:171], off
	v_lshl_add_u64 v[170:171], s[2:3], 0, v[140:141]
	s_add_i32 m0, s20, 0x2000
	s_nop 0
	global_load_lds_dwordx4 v[170:171], off
	v_lshl_add_u64 v[170:171], v[182:183], 0, s[26:27]
	s_mov_b32 m0, s59
	s_nop 0
	global_load_lds_dwordx4 v[170:171], off
	v_lshl_add_u64 v[170:171], v[184:185], 0, s[26:27]
	s_mov_b32 m0, s60
	s_nop 0
	global_load_lds_dwordx4 v[170:171], off
	s_waitcnt vmcnt(8)
	s_waitcnt lgkmcnt(0)
	s_barrier
	s_setprio 1
	s_waitcnt lgkmcnt(0)
	v_mfma_f32_16x16x32_bf16 v[62:65], v[130:133], v[196:199], v[62:65]
	v_mfma_f32_16x16x32_bf16 v[58:61], v[154:157], v[196:199], v[58:61]
	v_mfma_f32_16x16x32_bf16 v[54:57], v[130:133], v[204:207], v[54:57]
	v_mfma_f32_16x16x32_bf16 v[46:49], v[154:157], v[204:207], v[46:49]
	v_mfma_f32_16x16x32_bf16 v[38:41], v[130:133], v[212:215], v[38:41]
	v_mfma_f32_16x16x32_bf16 v[30:33], v[154:157], v[212:215], v[30:33]
	v_mfma_f32_16x16x32_bf16 v[22:25], v[130:133], v[236:239], v[22:25]
	v_mfma_f32_16x16x32_bf16 v[14:17], v[154:157], v[236:239], v[14:17]
	v_mfma_f32_16x16x32_bf16 v[62:65], v[150:153], v[200:203], v[62:65]
	v_mfma_f32_16x16x32_bf16 v[58:61], v[158:161], v[200:203], v[58:61]
	v_mfma_f32_16x16x32_bf16 v[54:57], v[150:153], v[208:211], v[54:57]
	v_mfma_f32_16x16x32_bf16 v[46:49], v[158:161], v[208:211], v[46:49]
	v_mfma_f32_16x16x32_bf16 v[38:41], v[150:153], v[216:219], v[38:41]
	v_mfma_f32_16x16x32_bf16 v[30:33], v[158:161], v[216:219], v[30:33]
	v_mfma_f32_16x16x32_bf16 v[22:25], v[150:153], v[240:243], v[22:25]
	v_mfma_f32_16x16x32_bf16 v[14:17], v[158:161], v[240:243], v[14:17]
	s_setprio 0
	s_setprio 1
	v_mfma_f32_16x16x32_bf16 v[50:53], v[162:165], v[196:199], v[50:53]
	v_mfma_f32_16x16x32_bf16 v[42:45], v[188:191], v[196:199], v[42:45]
	v_mfma_f32_16x16x32_bf16 v[34:37], v[162:165], v[204:207], v[34:37]
	v_mfma_f32_16x16x32_bf16 v[26:29], v[188:191], v[204:207], v[26:29]
	v_mfma_f32_16x16x32_bf16 v[18:21], v[162:165], v[212:215], v[18:21]
	v_mfma_f32_16x16x32_bf16 v[10:13], v[188:191], v[212:215], v[10:13]
	v_mfma_f32_16x16x32_bf16 v[6:9], v[162:165], v[236:239], v[6:9]
	v_mfma_f32_16x16x32_bf16 v[2:5], v[188:191], v[236:239], v[2:5]
	v_mfma_f32_16x16x32_bf16 v[50:53], v[166:169], v[200:203], v[50:53]
	v_mfma_f32_16x16x32_bf16 v[42:45], v[192:195], v[200:203], v[42:45]
	v_mfma_f32_16x16x32_bf16 v[34:37], v[166:169], v[208:211], v[34:37]
	v_mfma_f32_16x16x32_bf16 v[26:29], v[192:195], v[208:211], v[26:29]
	v_mfma_f32_16x16x32_bf16 v[18:21], v[166:169], v[216:219], v[18:21]
	v_mfma_f32_16x16x32_bf16 v[10:13], v[192:195], v[216:219], v[10:13]
	v_mfma_f32_16x16x32_bf16 v[6:9], v[166:169], v[240:243], v[6:9]
	v_mfma_f32_16x16x32_bf16 v[2:5], v[192:195], v[240:243], v[2:5]
	s_setprio 0
	s_add_i32 s51, s51, 2
	s_add_u32 s38, s38, 0x100
	s_addc_u32 s39, s39, 0
	s_add_u32 s40, s40, 0x100
	s_addc_u32 s41, s41, 0
	s_cmp_gt_u32 s51, 29
	s_barrier
	s_cbranch_scc0 .LBB0_314
	s_and_b64 vcc, exec, s[42:43]
	s_cbranch_vccz .LBB0_319
	s_barrier
	s_lshl_b32 s16, s12, 8
	s_cmp_lt_i32 s46, 14
	s_mov_b64 s[2:3], -1
	s_cbranch_scc1 .LBB0_320

; #define PG8_STAGE(bufoff, gbase, voff) do { _Pragma("unroll") for (int _i = 0; _i < 2; ++_i) \
;         __builtin_amdgcn_global_load_lds((const unsigned*)((const char*)(gbase) + (voff)[_i]), (PG8_LAS unsigned*)(lds + (bufoff) + ldsw + _i * 8192), 16, 0, 0); } while (0)
; #define PG8_LDA(dst, b, h) do { _Pragma("unroll") for (int m = 0; m < 4; ++m) _Pragma("unroll") for (int k = 0; k < 2; ++k) dst[m][k] = *(const PG8_LAS bf16x8*)(lds + PG8_SA(b, h) + aoff + m * 2048 + k * 1024); } while (0)
; #define PG8_LDB(dst, b, h) do { _Pragma("unroll") for (int n = 0; n < 2; ++n) _Pragma("unroll") for (int k = 0; k < 2; ++k) dst[n][k] = *(const PG8_LAS bf16x8*)(lds + PG8_SB(b, h) + boff + n * 2048 + k * 1024); } while (0)
; #define PG8_MMA(ai, bj, At, Bt) do { __builtin_amdgcn_s_setprio(1); _Pragma("unroll") for (int m = 0; m < 4; ++m) _Pragma("unroll") for (int n = 0; n < 2; ++n) _Pragma("unroll") for (int k = 0; k < 2; ++k) \
;         acc[ai][bj][m][n] = __builtin_amdgcn_mfma_f32_16x16x32_bf16(Bt[n][k], At[m][k], acc[ai][bj][m][n], 0, 0, 0); __builtin_amdgcn_s_setprio(0); } while (0)
; #define PG8_WAIT_V(n) asm volatile("s_waitcnt vmcnt(" #n ")" ::: "memory")
; #define PG8_WAIT_L(n) asm volatile("s_waitcnt lgkmcnt(" #n ")" ::: "memory")
; #define PG8_BAR __builtin_amdgcn_s_barrier()
; #define PG8_SCHED __builtin_amdgcn_sched_barrier(0)
; template <class Epi, class Sched, bool ALIGN_EPI = true, bool SP2 = true, bool GS = false>
; __device__ __forceinline__ void gemm_phase(PG8_LAS unsigned char* lds, const Gemm g, const Sched& S, const Epi& E, const float* gs_ss = nullptr) {
;     ...
;         for (int t = 0; t < nt; t += 2) {
;             const bool last = (t == nt - 2);
;             const char* a1 = cA + (size_t)(t + 1) * kstep;
;             const char* a2 = last ? nA : cA + (size_t)(t + 2) * kstep; const char* b2 = last ? nB : cB + (size_t)(t + 2) * kstep;
;             const char* a3 = a2 + kstep; const char* b3 = b2 + kstep;
;             if constexpr (SP2) {
;             PG8_LDB(B0, 0, 0); PG8_LDB(B1, 0, 1); PG8_SCHED; PG8_LDA(At, 0, 0); PG8_STAGE(PG8_SA(1, 1), a1 + hstep, voffA);
;             PG8_WAIT_V(8); PG8_WAIT_L(0); PG8_BAR; PG8_MMA(0, 0, At, B0); PG8_MMA(0, 1, At, B1); PG8_BAR; PG8_SCHED;
;             PG8_LDA(At, 0, 1); PG8_STAGE(PG8_SB(0, 0), b2, voffB); PG8_STAGE(PG8_SB(0, 1), b2 + hstep, voffB); PG8_STAGE(PG8_SA(0, 0), a2, voffA);
.LBB0_788:
	s_add_i32 s42, 0, 0x10000
	v_add_u32_e32 v0, s42, v183
	s_add_i32 s57, 0, 0x14000
	ds_read_b128 v[18:21], v0
	ds_read_b128 v[26:29], v0 offset:1024
	ds_read_b128 v[30:33], v0 offset:2048
	ds_read_b128 v[38:41], v0 offset:3072
	v_add_u32_e32 v0, s57, v183
	ds_read_b128 v[42:45], v0
	ds_read_b128 v[46:49], v0 offset:1024
	ds_read_b128 v[58:61], v0 offset:2048
	ds_read_b128 v[70:73], v0 offset:3072
	v_lshl_add_u64 v[180:181], s[34:35], 0, v[196:197]
	s_add_i32 m0, s37, 0xc000
	ds_read_b128 v[82:85], v219
	ds_read_b128 v[94:97], v219 offset:1024
	ds_read_b128 v[106:109], v219 offset:2048
	ds_read_b128 v[118:121], v219 offset:3072
	ds_read_b128 v[184:187], v219 offset:4096
	ds_read_b128 v[200:203], v219 offset:5120
	ds_read_b128 v[204:207], v219 offset:6144
	ds_read_b128 v[208:211], v219 offset:7168
	global_load_lds_dwordx4 v[180:181], off
	v_lshl_add_u64 v[180:181], s[34:35], 0, v[198:199]
	s_add_i32 m0, s37, 0xe000
	s_nop 0
	global_load_lds_dwordx4 v[180:181], off
	s_add_u32 s2, s34, 0xfffe0080
	s_addc_u32 s3, s35, -1
	s_cmp_eq_u32 s41, 4
	s_cselect_b32 s21, s16, s3
	s_cselect_b32 s20, s17, s2
	s_cselect_b32 s3, s13, s40
	s_cselect_b32 s2, s18, s29
	s_waitcnt vmcnt(8)
	s_waitcnt lgkmcnt(0)
	s_barrier
	s_setprio 1
	s_waitcnt lgkmcnt(0)
	v_mfma_f32_16x16x32_bf16 v[174:177], v[18:21], v[82:85], v[174:177]
	v_mfma_f32_16x16x32_bf16 v[170:173], v[30:33], v[82:85], v[170:173]
	v_mfma_f32_16x16x32_bf16 v[158:161], v[18:21], v[106:109], v[158:161]
	v_mfma_f32_16x16x32_bf16 v[154:157], v[30:33], v[106:109], v[154:157]
	v_mfma_f32_16x16x32_bf16 v[142:145], v[18:21], v[184:187], v[142:145]
	v_mfma_f32_16x16x32_bf16 v[138:141], v[30:33], v[184:187], v[138:141]
	v_mfma_f32_16x16x32_bf16 v[126:129], v[18:21], v[204:207], v[126:129]
	v_mfma_f32_16x16x32_bf16 v[122:125], v[30:33], v[204:207], v[122:125]
	v_mfma_f32_16x16x32_bf16 v[174:177], v[26:29], v[94:97], v[174:177]
	v_mfma_f32_16x16x32_bf16 v[170:173], v[38:41], v[94:97], v[170:173]
	v_mfma_f32_16x16x32_bf16 v[158:161], v[26:29], v[118:121], v[158:161]
	v_mfma_f32_16x16x32_bf16 v[154:157], v[38:41], v[118:121], v[154:157]
	v_mfma_f32_16x16x32_bf16 v[142:145], v[26:29], v[200:203], v[142:145]
	v_mfma_f32_16x16x32_bf16 v[138:141], v[38:41], v[200:203], v[138:141]
	v_mfma_f32_16x16x32_bf16 v[126:129], v[26:29], v[208:211], v[126:129]
	v_mfma_f32_16x16x32_bf16 v[122:125], v[38:41], v[208:211], v[122:125]
	s_setprio 0
	s_setprio 1
	v_mfma_f32_16x16x32_bf16 v[166:169], v[42:45], v[82:85], v[166:169]
	v_mfma_f32_16x16x32_bf16 v[82:85], v[58:61], v[82:85], v[162:165]
	v_mfma_f32_16x16x32_bf16 v[166:169], v[46:49], v[94:97], v[166:169]
	v_mfma_f32_16x16x32_bf16 v[82:85], v[70:73], v[94:97], v[82:85]
	v_mfma_f32_16x16x32_bf16 v[94:97], v[42:45], v[106:109], v[150:153]
	v_mfma_f32_16x16x32_bf16 v[106:109], v[58:61], v[106:109], v[146:149]
	v_mfma_f32_16x16x32_bf16 v[130:133], v[58:61], v[184:187], v[130:133]
	v_mfma_f32_16x16x32_bf16 v[114:117], v[42:45], v[204:207], v[114:117]
	v_mfma_f32_16x16x32_bf16 v[110:113], v[58:61], v[204:207], v[110:113]
	v_mfma_f32_16x16x32_bf16 v[94:97], v[46:49], v[118:121], v[94:97]
	v_mfma_f32_16x16x32_bf16 v[106:109], v[70:73], v[118:121], v[106:109]
	v_mfma_f32_16x16x32_bf16 v[118:121], v[42:45], v[184:187], v[134:137]
	v_mfma_f32_16x16x32_bf16 v[130:133], v[70:73], v[200:203], v[130:133]
	v_mfma_f32_16x16x32_bf16 v[114:117], v[46:49], v[208:211], v[114:117]
	v_mfma_f32_16x16x32_bf16 v[110:113], v[70:73], v[208:211], v[110:113]
	v_mfma_f32_16x16x32_bf16 v[118:121], v[46:49], v[200:203], v[118:121]
	s_setprio 0
	s_barrier
	s_add_i32 s42, s42, s25
	v_lshl_add_u64 v[180:181], s[2:3], 0, v[190:191]
	s_mov_b32 m0, s42
	ds_read_b128 v[134:137], v219 offset:16384
	ds_read_b128 v[146:149], v219 offset:17408
	ds_read_b128 v[150:153], v219 offset:18432
	ds_read_b128 v[162:165], v219 offset:19456
	ds_read_b128 v[184:187], v219 offset:20480
	ds_read_b128 v[200:203], v219 offset:21504
	ds_read_b128 v[204:207], v219 offset:22528
	ds_read_b128 v[208:211], v219 offset:23552
	global_load_lds_dwordx4 v[180:181], off
	s_add_i32 m0, s42, 0x2000
	s_add_u32 s42, s2, 0x20000
	v_lshl_add_u64 v[216:217], s[2:3], 0, v[194:195]
	s_addc_u32 s43, s3, 0
	s_add_i32 s57, s57, s25
	global_load_lds_dwordx4 v[216:217], off
	v_lshl_add_u64 v[212:213], s[42:43], 0, v[190:191]
	s_mov_b32 m0, s57
	v_lshl_add_u64 v[220:221], s[20:21], 0, v[188:189]
	global_load_lds_dwordx4 v[212:213], off
	v_lshl_add_u64 v[212:213], s[42:43], 0, v[194:195]
	s_add_i32 m0, s57, 0x2000
	v_lshl_add_u64 v[244:245], s[20:21], 0, v[192:193]
	global_load_lds_dwordx4 v[212:213], off
	s_mov_b32 m0, s37
	s_nop 0
	global_load_lds_dwordx4 v[220:221], off
	s_mov_b32 m0, s59
	s_nop 0
	global_load_lds_dwordx4 v[244:245], off
	s_waitcnt vmcnt(8)
	s_waitcnt lgkmcnt(0)
	s_barrier
; #define PG8_STAGE(bufoff, gbase, voff) do { _Pragma("unroll") for (int _i = 0; _i < 2; ++_i) \
;         __builtin_amdgcn_global_load_lds((const unsigned*)((const char*)(gbase) + (voff)[_i]), (PG8_LAS unsigned*)(lds + (bufoff) + ldsw + _i * 8192), 16, 0, 0); } while (0)
; #define PG8_LDA(dst, b, h) do { _Pragma("unroll") for (int m = 0; m < 4; ++m) _Pragma("unroll") for (int k = 0; k < 2; ++k) dst[m][k] = *(const PG8_LAS bf16x8*)(lds + PG8_SA(b, h) + aoff + m * 2048 + k * 1024); } while (0)
; #define PG8_LDB(dst, b, h) do { _Pragma("unroll") for (int n = 0; n < 2; ++n) _Pragma("unroll") for (int k = 0; k < 2; ++k) dst[n][k] = *(const PG8_LAS bf16x8*)(lds + PG8_SB(b, h) + boff + n * 2048 + k * 1024); } while (0)
; #define PG8_MMA(ai, bj, At, Bt) do { __builtin_amdgcn_s_setprio(1); _Pragma("unroll") for (int m = 0; m < 4; ++m) _Pragma("unroll") for (int n = 0; n < 2; ++n) _Pragma("unroll") for (int k = 0; k < 2; ++k) \
;         acc[ai][bj][m][n] = __builtin_amdgcn_mfma_f32_16x16x32_bf16(Bt[n][k], At[m][k], acc[ai][bj][m][n], 0, 0, 0); __builtin_amdgcn_s_setprio(0); } while (0)
; #define PG8_WAIT_V(n) asm volatile("s_waitcnt vmcnt(" #n ")" ::: "memory")
; #define PG8_WAIT_L(n) asm volatile("s_waitcnt lgkmcnt(" #n ")" ::: "memory")
; #define PG8_BAR __builtin_amdgcn_s_barrier()
; #define PG8_SCHED __builtin_amdgcn_sched_barrier(0)
; template <class Epi, class Sched, bool ALIGN_EPI = true, bool SP2 = true, bool GS = false>
; __device__ __forceinline__ void gemm_phase(PG8_LAS unsigned char* lds, const Gemm g, const Sched& S, const Epi& E, const float* gs_ss = nullptr) {
;     ...
;             PG8_LDA(At, 0, 1); PG8_STAGE(PG8_SB(0, 0), b2, voffB); PG8_STAGE(PG8_SB(0, 1), b2 + hstep, voffB); PG8_STAGE(PG8_SA(0, 0), a2, voffA);
;             PG8_WAIT_V(8); PG8_WAIT_L(0); PG8_BAR; PG8_MMA(1, 0, At, B0); PG8_MMA(1, 1, At, B1); PG8_BAR; PG8_SCHED;
;             PG8_LDB(B0, 1, 0); PG8_LDB(B1, 1, 1); PG8_SCHED; PG8_LDA(At, 1, 0); PG8_STAGE(PG8_SA(0, 1), a2 + hstep, voffA);
;             PG8_WAIT_V(8); PG8_WAIT_L(0); PG8_BAR; PG8_MMA(0, 0, At, B0); PG8_MMA(0, 1, At, B1); PG8_BAR; PG8_SCHED;
	s_setprio 1
	s_waitcnt lgkmcnt(0)
	v_mfma_f32_16x16x32_bf16 v[102:105], v[18:21], v[134:137], v[102:105]
	v_mfma_f32_16x16x32_bf16 v[98:101], v[30:33], v[134:137], v[98:101]
	v_mfma_f32_16x16x32_bf16 v[78:81], v[18:21], v[150:153], v[78:81]
	v_mfma_f32_16x16x32_bf16 v[74:77], v[30:33], v[150:153], v[74:77]
	v_mfma_f32_16x16x32_bf16 v[54:57], v[18:21], v[184:187], v[54:57]
	v_mfma_f32_16x16x32_bf16 v[50:53], v[30:33], v[184:187], v[50:53]
	v_mfma_f32_16x16x32_bf16 v[14:17], v[18:21], v[204:207], v[14:17]
	v_mfma_f32_16x16x32_bf16 v[10:13], v[30:33], v[204:207], v[10:13]
	v_mfma_f32_16x16x32_bf16 v[102:105], v[26:29], v[146:149], v[102:105]
	v_mfma_f32_16x16x32_bf16 v[98:101], v[38:41], v[146:149], v[98:101]
	v_mfma_f32_16x16x32_bf16 v[78:81], v[26:29], v[162:165], v[78:81]
	v_mfma_f32_16x16x32_bf16 v[74:77], v[38:41], v[162:165], v[74:77]
	v_mfma_f32_16x16x32_bf16 v[54:57], v[26:29], v[200:203], v[54:57]
	v_mfma_f32_16x16x32_bf16 v[50:53], v[38:41], v[200:203], v[50:53]
	v_mfma_f32_16x16x32_bf16 v[14:17], v[26:29], v[208:211], v[14:17]
	v_mfma_f32_16x16x32_bf16 v[10:13], v[38:41], v[208:211], v[10:13]
	s_setprio 0
	s_setprio 1
	v_mfma_f32_16x16x32_bf16 v[34:37], v[42:45], v[184:187], v[34:37]
	v_mfma_f32_16x16x32_bf16 v[22:25], v[58:61], v[184:187], v[22:25]
	v_mfma_f32_16x16x32_bf16 v[6:9], v[42:45], v[204:207], v[6:9]
	v_mfma_f32_16x16x32_bf16 v[2:5], v[58:61], v[204:207], v[2:5]
	v_mfma_f32_16x16x32_bf16 v[18:21], v[42:45], v[134:137], v[90:93]
	v_mfma_f32_16x16x32_bf16 v[26:29], v[58:61], v[134:137], v[86:89]
	v_mfma_f32_16x16x32_bf16 v[30:33], v[42:45], v[150:153], v[66:69]
	v_mfma_f32_16x16x32_bf16 v[38:41], v[58:61], v[150:153], v[62:65]
	v_mfma_f32_16x16x32_bf16 v[34:37], v[46:49], v[200:203], v[34:37]
	v_mfma_f32_16x16x32_bf16 v[22:25], v[70:73], v[200:203], v[22:25]
	v_mfma_f32_16x16x32_bf16 v[6:9], v[46:49], v[208:211], v[6:9]
	v_mfma_f32_16x16x32_bf16 v[2:5], v[70:73], v[208:211], v[2:5]
	v_mfma_f32_16x16x32_bf16 v[18:21], v[46:49], v[146:149], v[18:21]
	v_mfma_f32_16x16x32_bf16 v[26:29], v[70:73], v[146:149], v[26:29]
	v_mfma_f32_16x16x32_bf16 v[30:33], v[46:49], v[162:165], v[30:33]
	v_mfma_f32_16x16x32_bf16 v[38:41], v[70:73], v[162:165], v[38:41]
	s_setprio 0
	s_barrier
	s_add_i32 s42, 0, 0x18000
	v_add_u32_e32 v0, s42, v183
	s_add_i32 s43, 0, 0x1c000
	ds_read_b128 v[42:45], v0
	ds_read_b128 v[46:49], v0 offset:1024
	ds_read_b128 v[58:61], v0 offset:2048
	ds_read_b128 v[62:65], v0 offset:3072
	v_add_u32_e32 v0, s43, v183
	ds_read_b128 v[70:73], v0
	ds_read_b128 v[184:187], v0 offset:1024
	ds_read_b128 v[200:203], v0 offset:2048
	ds_read_b128 v[204:207], v0 offset:3072
	s_add_u32 s20, s20, 0x20000
	s_addc_u32 s21, s21, 0
	s_mov_b32 m0, s69
	v_lshl_add_u64 v[146:147], s[20:21], 0, v[188:189]
	ds_read_b128 v[66:69], v219 offset:32768
	ds_read_b128 v[86:89], v219 offset:33792
	ds_read_b128 v[90:93], v219 offset:34816
	ds_read_b128 v[134:137], v219 offset:35840
	ds_read_b128 v[208:211], v219 offset:36864
	ds_read_b128 v[212:215], v219 offset:37888
	ds_read_b128 v[236:239], v219 offset:38912
	ds_read_b128 v[240:243], v219 offset:39936
	global_load_lds_dwordx4 v[146:147], off
	v_lshl_add_u64 v[146:147], s[20:21], 0, v[192:193]
	s_mov_b32 m0, s64
	s_nop 0
	global_load_lds_dwordx4 v[146:147], off
	s_waitcnt vmcnt(8)
	s_waitcnt lgkmcnt(0)
	s_barrier
	s_setprio 1
	s_waitcnt lgkmcnt(0)
	v_mfma_f32_16x16x32_bf16 v[146:149], v[42:45], v[66:69], v[174:177]
	v_mfma_f32_16x16x32_bf16 v[174:177], v[46:49], v[86:89], v[146:149]
	v_mfma_f32_16x16x32_bf16 v[146:149], v[58:61], v[66:69], v[170:173]
	v_mfma_f32_16x16x32_bf16 v[170:173], v[62:65], v[86:89], v[146:149]
	v_mfma_f32_16x16x32_bf16 v[146:149], v[42:45], v[90:93], v[158:161]
	v_mfma_f32_16x16x32_bf16 v[158:161], v[46:49], v[134:137], v[146:149]
	v_mfma_f32_16x16x32_bf16 v[146:149], v[58:61], v[90:93], v[154:157]
	v_mfma_f32_16x16x32_bf16 v[142:145], v[42:45], v[208:211], v[142:145]
	v_mfma_f32_16x16x32_bf16 v[138:141], v[58:61], v[208:211], v[138:141]
	v_mfma_f32_16x16x32_bf16 v[126:129], v[42:45], v[236:239], v[126:129]
	v_mfma_f32_16x16x32_bf16 v[122:125], v[58:61], v[236:239], v[122:125]
	v_mfma_f32_16x16x32_bf16 v[154:157], v[62:65], v[134:137], v[146:149]
	v_mfma_f32_16x16x32_bf16 v[142:145], v[46:49], v[212:215], v[142:145]
	v_mfma_f32_16x16x32_bf16 v[138:141], v[62:65], v[212:215], v[138:141]
	v_mfma_f32_16x16x32_bf16 v[126:129], v[46:49], v[240:243], v[126:129]
	v_mfma_f32_16x16x32_bf16 v[122:125], v[62:65], v[240:243], v[122:125]
	s_setprio 0
	s_setprio 1
	v_mfma_f32_16x16x32_bf16 v[146:149], v[70:73], v[66:69], v[166:169]
	v_mfma_f32_16x16x32_bf16 v[66:69], v[200:203], v[66:69], v[82:85]
	v_mfma_f32_16x16x32_bf16 v[162:165], v[204:207], v[86:89], v[66:69]
	v_mfma_f32_16x16x32_bf16 v[66:69], v[70:73], v[90:93], v[94:97]
	v_mfma_f32_16x16x32_bf16 v[150:153], v[184:187], v[134:137], v[66:69]
	v_mfma_f32_16x16x32_bf16 v[66:69], v[200:203], v[90:93], v[106:109]
	v_mfma_f32_16x16x32_bf16 v[166:169], v[184:187], v[86:89], v[146:149]
	v_mfma_f32_16x16x32_bf16 v[146:149], v[204:207], v[134:137], v[66:69]
	v_mfma_f32_16x16x32_bf16 v[66:69], v[70:73], v[208:211], v[118:121]
	v_mfma_f32_16x16x32_bf16 v[134:137], v[184:187], v[212:215], v[66:69]
	v_mfma_f32_16x16x32_bf16 v[66:69], v[200:203], v[208:211], v[130:133]
	v_mfma_f32_16x16x32_bf16 v[130:133], v[204:207], v[212:215], v[66:69]
	v_mfma_f32_16x16x32_bf16 v[66:69], v[70:73], v[236:239], v[114:117]
	v_mfma_f32_16x16x32_bf16 v[114:117], v[184:187], v[240:243], v[66:69]
	v_mfma_f32_16x16x32_bf16 v[66:69], v[200:203], v[236:239], v[110:113]
	v_mfma_f32_16x16x32_bf16 v[110:113], v[204:207], v[240:243], v[66:69]
	s_setprio 0
	s_barrier
; #define PG8_STAGE(bufoff, gbase, voff) do { _Pragma("unroll") for (int _i = 0; _i < 2; ++_i) \
;         __builtin_amdgcn_global_load_lds((const unsigned*)((const char*)(gbase) + (voff)[_i]), (PG8_LAS unsigned*)(lds + (bufoff) + ldsw + _i * 8192), 16, 0, 0); } while (0)
; #define PG8_LDA(dst, b, h) do { _Pragma("unroll") for (int m = 0; m < 4; ++m) _Pragma("unroll") for (int k = 0; k < 2; ++k) dst[m][k] = *(const PG8_LAS bf16x8*)(lds + PG8_SA(b, h) + aoff + m * 2048 + k * 1024); } while (0)
; #define PG8_MMA(ai, bj, At, Bt) do { __builtin_amdgcn_s_setprio(1); _Pragma("unroll") for (int m = 0; m < 4; ++m) _Pragma("unroll") for (int n = 0; n < 2; ++n) _Pragma("unroll") for (int k = 0; k < 2; ++k) \
;         acc[ai][bj][m][n] = __builtin_amdgcn_mfma_f32_16x16x32_bf16(Bt[n][k], At[m][k], acc[ai][bj][m][n], 0, 0, 0); __builtin_amdgcn_s_setprio(0); } while (0)
; #define PG8_WAIT_V(n) asm volatile("s_waitcnt vmcnt(" #n ")" ::: "memory")
; #define PG8_WAIT_L(n) asm volatile("s_waitcnt lgkmcnt(" #n ")" ::: "memory")
; #define PG8_BAR __builtin_amdgcn_s_barrier()
; #define PG8_SCHED __builtin_amdgcn_sched_barrier(0)
; template <class Epi, class Sched, bool ALIGN_EPI = true, bool SP2 = true, bool GS = false>
; __device__ __forceinline__ void gemm_phase(PG8_LAS unsigned char* lds, const Gemm g, const Sched& S, const Epi& E, const float* gs_ss = nullptr) {
;     ...
;         for (int t = 0; t < nt; t += 2) {
;     ...
;             PG8_WAIT_V(8); PG8_WAIT_L(0); PG8_BAR; PG8_MMA(0, 0, At, B0); PG8_MMA(0, 1, At, B1); PG8_BAR; PG8_SCHED;
;             PG8_LDA(At, 1, 1); PG8_STAGE(PG8_SB(1, 0), b3, voffB); PG8_STAGE(PG8_SB(1, 1), b3 + hstep, voffB); PG8_STAGE(PG8_SA(1, 0), a3, voffA);
;             PG8_WAIT_V(8); PG8_WAIT_L(0); PG8_BAR; PG8_MMA(1, 0, At, B0); PG8_MMA(1, 1, At, B1); PG8_BAR; PG8_SCHED;
	s_add_i32 s20, s42, s25
	v_lshl_add_u64 v[86:87], v[180:181], 0, s[26:27]
	s_mov_b32 m0, s20
	s_nop 1
	ds_read_b128 v[66:69], v219 offset:49152
	ds_read_b128 v[82:85], v219 offset:50176
	ds_read_b128 v[94:97], v219 offset:51200
	ds_read_b128 v[106:109], v219 offset:52224
	ds_read_b128 v[118:121], v219 offset:53248
	ds_read_b128 v[208:211], v219 offset:54272
	ds_read_b128 v[212:215], v219 offset:55296
	ds_read_b128 v[236:239], v219 offset:56320
	global_load_lds_dwordx4 v[86:87], off
	s_add_i32 m0, s20, 0x2000
	s_add_u32 s2, s2, 0x20080
	v_lshl_add_u64 v[86:87], v[216:217], 0, s[26:27]
	s_addc_u32 s3, s3, 0
	s_add_i32 s20, s43, s25
	global_load_lds_dwordx4 v[86:87], off
	v_lshl_add_u64 v[86:87], s[2:3], 0, v[190:191]
	s_mov_b32 m0, s20
	s_nop 0
	global_load_lds_dwordx4 v[86:87], off
	v_lshl_add_u64 v[86:87], s[2:3], 0, v[194:195]
	s_add_i32 m0, s20, 0x2000
	s_nop 0
	global_load_lds_dwordx4 v[86:87], off
	v_lshl_add_u64 v[86:87], v[220:221], 0, s[26:27]
	s_mov_b32 m0, s30
	s_nop 0
	global_load_lds_dwordx4 v[86:87], off
	v_lshl_add_u64 v[86:87], v[244:245], 0, s[26:27]
	s_mov_b32 m0, s14
	s_nop 0
	global_load_lds_dwordx4 v[86:87], off
	s_waitcnt vmcnt(8)
	s_waitcnt lgkmcnt(0)
	s_barrier
	s_setprio 1
	s_waitcnt lgkmcnt(0)
	v_mfma_f32_16x16x32_bf16 v[86:89], v[42:45], v[66:69], v[102:105]
	v_mfma_f32_16x16x32_bf16 v[102:105], v[46:49], v[82:85], v[86:89]
	v_mfma_f32_16x16x32_bf16 v[86:89], v[58:61], v[66:69], v[98:101]
	v_mfma_f32_16x16x32_bf16 v[78:81], v[42:45], v[94:97], v[78:81]
	v_mfma_f32_16x16x32_bf16 v[74:77], v[58:61], v[94:97], v[74:77]
	v_mfma_f32_16x16x32_bf16 v[54:57], v[42:45], v[118:121], v[54:57]
	v_mfma_f32_16x16x32_bf16 v[50:53], v[58:61], v[118:121], v[50:53]
	v_mfma_f32_16x16x32_bf16 v[14:17], v[42:45], v[212:215], v[14:17]
	v_mfma_f32_16x16x32_bf16 v[10:13], v[58:61], v[212:215], v[10:13]
	v_mfma_f32_16x16x32_bf16 v[98:101], v[62:65], v[82:85], v[86:89]
	v_mfma_f32_16x16x32_bf16 v[78:81], v[46:49], v[106:109], v[78:81]
	v_mfma_f32_16x16x32_bf16 v[74:77], v[62:65], v[106:109], v[74:77]
	v_mfma_f32_16x16x32_bf16 v[54:57], v[46:49], v[208:211], v[54:57]
	v_mfma_f32_16x16x32_bf16 v[50:53], v[62:65], v[208:211], v[50:53]
	v_mfma_f32_16x16x32_bf16 v[14:17], v[46:49], v[236:239], v[14:17]
	v_mfma_f32_16x16x32_bf16 v[10:13], v[62:65], v[236:239], v[10:13]
	s_setprio 0
	s_setprio 1
	v_mfma_f32_16x16x32_bf16 v[18:21], v[70:73], v[66:69], v[18:21]
	v_mfma_f32_16x16x32_bf16 v[90:93], v[184:187], v[82:85], v[18:21]
	v_mfma_f32_16x16x32_bf16 v[18:21], v[200:203], v[66:69], v[26:29]
	v_mfma_f32_16x16x32_bf16 v[86:89], v[204:207], v[82:85], v[18:21]
	v_mfma_f32_16x16x32_bf16 v[18:21], v[70:73], v[94:97], v[30:33]
	v_mfma_f32_16x16x32_bf16 v[66:69], v[184:187], v[106:109], v[18:21]
	v_mfma_f32_16x16x32_bf16 v[18:21], v[200:203], v[94:97], v[38:41]
	v_mfma_f32_16x16x32_bf16 v[62:65], v[204:207], v[106:109], v[18:21]
	v_mfma_f32_16x16x32_bf16 v[18:21], v[70:73], v[118:121], v[34:37]
	v_mfma_f32_16x16x32_bf16 v[34:37], v[184:187], v[208:211], v[18:21]
	v_mfma_f32_16x16x32_bf16 v[18:21], v[200:203], v[118:121], v[22:25]
	v_mfma_f32_16x16x32_bf16 v[6:9], v[70:73], v[212:215], v[6:9]
	v_mfma_f32_16x16x32_bf16 v[2:5], v[200:203], v[212:215], v[2:5]
	v_mfma_f32_16x16x32_bf16 v[22:25], v[204:207], v[208:211], v[18:21]
	v_mfma_f32_16x16x32_bf16 v[6:9], v[184:187], v[236:239], v[6:9]
	v_mfma_f32_16x16x32_bf16 v[2:5], v[204:207], v[236:239], v[2:5]
	s_setprio 0
	s_add_i32 s41, s41, 2
	s_add_u32 s34, s34, 0x100
	s_addc_u32 s35, s35, 0
	s_add_u32 s29, s29, 0x100
	s_addc_u32 s40, s40, 0
	s_cmp_gt_u32 s41, 5
	s_barrier
	s_cbranch_scc0 .LBB0_788
	s_and_b64 vcc, exec, s[54:55]
	s_cbranch_vccz .LBB0_791
	s_barrier

; #define PG8_STAGE(bufoff, gbase, voff) do { _Pragma("unroll") for (int _i = 0; _i < 2; ++_i) \
;         __builtin_amdgcn_global_load_lds((const unsigned*)((const char*)(gbase) + (voff)[_i]), (PG8_LAS unsigned*)(lds + (bufoff) + ldsw + _i * 8192), 16, 0, 0); } while (0)
; #define PG8_LDA(dst, b, h) do { _Pragma("unroll") for (int m = 0; m < 4; ++m) _Pragma("unroll") for (int k = 0; k < 2; ++k) dst[m][k] = *(const PG8_LAS bf16x8*)(lds + PG8_SA(b, h) + aoff + m * 2048 + k * 1024); } while (0)
; #define PG8_LDB(dst, b, h) do { _Pragma("unroll") for (int n = 0; n < 2; ++n) _Pragma("unroll") for (int k = 0; k < 2; ++k) dst[n][k] = *(const PG8_LAS bf16x8*)(lds + PG8_SB(b, h) + boff + n * 2048 + k * 1024); } while (0)
; #define PG8_MMA(ai, bj, At, Bt) do { __builtin_amdgcn_s_setprio(1); _Pragma("unroll") for (int m = 0; m < 4; ++m) _Pragma("unroll") for (int n = 0; n < 2; ++n) _Pragma("unroll") for (int k = 0; k < 2; ++k) \
;         acc[ai][bj][m][n] = __builtin_amdgcn_mfma_f32_16x16x32_bf16(Bt[n][k], At[m][k], acc[ai][bj][m][n], 0, 0, 0); __builtin_amdgcn_s_setprio(0); } while (0)
; #define PG8_WAIT_V(n) asm volatile("s_waitcnt vmcnt(" #n ")" ::: "memory")
; #define PG8_WAIT_L(n) asm volatile("s_waitcnt lgkmcnt(" #n ")" ::: "memory")
; #define PG8_BAR __builtin_amdgcn_s_barrier()
; #define PG8_SCHED __builtin_amdgcn_sched_barrier(0)
; template <class Epi, class Sched, bool ALIGN_EPI = true, bool SP2 = true, bool GS = false>
; __device__ __forceinline__ void gemm_phase(PG8_LAS unsigned char* lds, const Gemm g, const Sched& S, const Epi& E, const float* gs_ss = nullptr) {
;     ...
;         for (int t = 0; t < nt; t += 2) {
;             const bool last = (t == nt - 2);
;             const char* a1 = cA + (size_t)(t + 1) * kstep;
;             const char* a2 = last ? nA : cA + (size_t)(t + 2) * kstep; const char* b2 = last ? nB : cB + (size_t)(t + 2) * kstep;
;             const char* a3 = a2 + kstep; const char* b3 = b2 + kstep;
;             if constexpr (SP2) {
;             PG8_LDB(B0, 0, 0); PG8_LDB(B1, 0, 1); PG8_SCHED; PG8_LDA(At, 0, 0); PG8_STAGE(PG8_SA(1, 1), a1 + hstep, voffA);
;             PG8_WAIT_V(8); PG8_WAIT_L(0); PG8_BAR; PG8_MMA(0, 0, At, B0); PG8_MMA(0, 1, At, B1); PG8_BAR; PG8_SCHED;
;             PG8_LDA(At, 0, 1); PG8_STAGE(PG8_SB(0, 0), b2, voffB); PG8_STAGE(PG8_SB(0, 1), b2 + hstep, voffB); PG8_STAGE(PG8_SA(0, 0), a2, voffA);
.LBB0_1119:
	s_add_i32 s59, 0, 0x10000
	v_add_u32_e32 v0, s59, v145
	s_add_i32 s62, 0, 0x14000
	ds_read_b128 v[148:151], v0
	ds_read_b128 v[152:155], v0 offset:1024
	ds_read_b128 v[156:159], v0 offset:2048
	ds_read_b128 v[160:163], v0 offset:3072
	v_add_u32_e32 v0, s62, v145
	ds_read_b128 v[164:167], v0
	ds_read_b128 v[168:171], v0 offset:1024
	ds_read_b128 v[172:175], v0 offset:2048
	ds_read_b128 v[180:183], v0 offset:3072
	v_lshl_add_u64 v[142:143], s[44:45], 0, v[138:139]
	s_add_i32 m0, s9, 0xc000
	ds_read_b128 v[184:187], v147
	ds_read_b128 v[188:191], v147 offset:1024
	ds_read_b128 v[192:195], v147 offset:2048
	ds_read_b128 v[196:199], v147 offset:3072
	ds_read_b128 v[200:203], v147 offset:4096
	ds_read_b128 v[204:207], v147 offset:5120
	ds_read_b128 v[208:211], v147 offset:6144
	ds_read_b128 v[212:215], v147 offset:7168
	global_load_lds_dwordx4 v[142:143], off
	v_lshl_add_u64 v[142:143], s[44:45], 0, v[140:141]
	s_add_i32 m0, s9, 0xe000
	s_nop 0
	global_load_lds_dwordx4 v[142:143], off
	s_add_u32 s2, s44, 0xfff80080
	s_addc_u32 s3, s45, -1
	s_cmp_eq_u32 s58, 4
	s_cselect_b32 s21, s52, s3
	s_cselect_b32 s20, s53, s2
	s_cselect_b32 s3, s54, s57
	s_cselect_b32 s2, s55, s56
	s_waitcnt vmcnt(8)
	s_waitcnt lgkmcnt(0)
	s_barrier
	s_setprio 1
	s_waitcnt lgkmcnt(0)
	v_mfma_f32_16x16x32_bf16 v[126:129], v[148:151], v[184:187], v[126:129]
	v_mfma_f32_16x16x32_bf16 v[122:125], v[156:159], v[184:187], v[122:125]
	v_mfma_f32_16x16x32_bf16 v[118:121], v[148:151], v[192:195], v[118:121]
	v_mfma_f32_16x16x32_bf16 v[110:113], v[156:159], v[192:195], v[110:113]
	v_mfma_f32_16x16x32_bf16 v[102:105], v[148:151], v[200:203], v[102:105]
	v_mfma_f32_16x16x32_bf16 v[94:97], v[156:159], v[200:203], v[94:97]
	v_mfma_f32_16x16x32_bf16 v[86:89], v[148:151], v[208:211], v[86:89]
	v_mfma_f32_16x16x32_bf16 v[78:81], v[156:159], v[208:211], v[78:81]
	v_mfma_f32_16x16x32_bf16 v[126:129], v[152:155], v[188:191], v[126:129]
	v_mfma_f32_16x16x32_bf16 v[122:125], v[160:163], v[188:191], v[122:125]
	v_mfma_f32_16x16x32_bf16 v[118:121], v[152:155], v[196:199], v[118:121]
	v_mfma_f32_16x16x32_bf16 v[110:113], v[160:163], v[196:199], v[110:113]
	v_mfma_f32_16x16x32_bf16 v[102:105], v[152:155], v[204:207], v[102:105]
	v_mfma_f32_16x16x32_bf16 v[94:97], v[160:163], v[204:207], v[94:97]
	v_mfma_f32_16x16x32_bf16 v[86:89], v[152:155], v[212:215], v[86:89]
	v_mfma_f32_16x16x32_bf16 v[78:81], v[160:163], v[212:215], v[78:81]
	s_setprio 0
	s_setprio 1
	v_mfma_f32_16x16x32_bf16 v[114:117], v[164:167], v[184:187], v[114:117]
	v_mfma_f32_16x16x32_bf16 v[106:109], v[172:175], v[184:187], v[106:109]
	v_mfma_f32_16x16x32_bf16 v[98:101], v[164:167], v[192:195], v[98:101]
	v_mfma_f32_16x16x32_bf16 v[90:93], v[172:175], v[192:195], v[90:93]
	v_mfma_f32_16x16x32_bf16 v[82:85], v[164:167], v[200:203], v[82:85]
	v_mfma_f32_16x16x32_bf16 v[74:77], v[172:175], v[200:203], v[74:77]
	v_mfma_f32_16x16x32_bf16 v[70:73], v[164:167], v[208:211], v[70:73]
	v_mfma_f32_16x16x32_bf16 v[66:69], v[172:175], v[208:211], v[66:69]
	v_mfma_f32_16x16x32_bf16 v[114:117], v[168:171], v[188:191], v[114:117]
	v_mfma_f32_16x16x32_bf16 v[106:109], v[180:183], v[188:191], v[106:109]
	v_mfma_f32_16x16x32_bf16 v[98:101], v[168:171], v[196:199], v[98:101]
	v_mfma_f32_16x16x32_bf16 v[90:93], v[180:183], v[196:199], v[90:93]
	v_mfma_f32_16x16x32_bf16 v[82:85], v[168:171], v[204:207], v[82:85]
	v_mfma_f32_16x16x32_bf16 v[74:77], v[180:183], v[204:207], v[74:77]
	v_mfma_f32_16x16x32_bf16 v[70:73], v[168:171], v[212:215], v[70:73]
	v_mfma_f32_16x16x32_bf16 v[66:69], v[180:183], v[212:215], v[66:69]
	s_setprio 0
	s_barrier
	s_add_i32 s59, s59, s23
	v_lshl_add_u64 v[142:143], s[2:3], 0, v[134:135]
	s_mov_b32 m0, s59
	ds_read_b128 v[184:187], v147 offset:16384
	ds_read_b128 v[188:191], v147 offset:17408
	ds_read_b128 v[192:195], v147 offset:18432
	ds_read_b128 v[196:199], v147 offset:19456
	ds_read_b128 v[200:203], v147 offset:20480
	ds_read_b128 v[204:207], v147 offset:21504
	ds_read_b128 v[208:211], v147 offset:22528
	ds_read_b128 v[212:215], v147 offset:23552
	global_load_lds_dwordx4 v[142:143], off
	s_add_i32 m0, s59, 0x2000
	s_add_u32 s60, s2, 0x80000
	v_lshl_add_u64 v[176:177], s[2:3], 0, v[130:131]
	s_addc_u32 s61, s3, 0
	s_add_i32 s59, s62, s23
	global_load_lds_dwordx4 v[176:177], off
	v_lshl_add_u64 v[216:217], s[60:61], 0, v[134:135]
	s_mov_b32 m0, s59
	v_lshl_add_u64 v[218:219], s[20:21], 0, v[132:133]
	global_load_lds_dwordx4 v[216:217], off
	v_lshl_add_u64 v[216:217], s[60:61], 0, v[130:131]
	s_add_i32 m0, s59, 0x2000
	s_nop 0
	global_load_lds_dwordx4 v[216:217], off
	v_lshl_add_u64 v[216:217], s[20:21], 0, v[136:137]
	s_mov_b32 m0, s9
	s_nop 0
	global_load_lds_dwordx4 v[216:217], off
	s_mov_b32 m0, s25
	s_nop 0
	global_load_lds_dwordx4 v[218:219], off
	s_waitcnt vmcnt(8)
	s_waitcnt lgkmcnt(0)
	s_barrier
; #define PG8_STAGE(bufoff, gbase, voff) do { _Pragma("unroll") for (int _i = 0; _i < 2; ++_i) \
;         __builtin_amdgcn_global_load_lds((const unsigned*)((const char*)(gbase) + (voff)[_i]), (PG8_LAS unsigned*)(lds + (bufoff) + ldsw + _i * 8192), 16, 0, 0); } while (0)
; #define PG8_LDA(dst, b, h) do { _Pragma("unroll") for (int m = 0; m < 4; ++m) _Pragma("unroll") for (int k = 0; k < 2; ++k) dst[m][k] = *(const PG8_LAS bf16x8*)(lds + PG8_SA(b, h) + aoff + m * 2048 + k * 1024); } while (0)
; #define PG8_LDB(dst, b, h) do { _Pragma("unroll") for (int n = 0; n < 2; ++n) _Pragma("unroll") for (int k = 0; k < 2; ++k) dst[n][k] = *(const PG8_LAS bf16x8*)(lds + PG8_SB(b, h) + boff + n * 2048 + k * 1024); } while (0)
; #define PG8_MMA(ai, bj, At, Bt) do { __builtin_amdgcn_s_setprio(1); _Pragma("unroll") for (int m = 0; m < 4; ++m) _Pragma("unroll") for (int n = 0; n < 2; ++n) _Pragma("unroll") for (int k = 0; k < 2; ++k) \
;         acc[ai][bj][m][n] = __builtin_amdgcn_mfma_f32_16x16x32_bf16(Bt[n][k], At[m][k], acc[ai][bj][m][n], 0, 0, 0); __builtin_amdgcn_s_setprio(0); } while (0)
; #define PG8_WAIT_V(n) asm volatile("s_waitcnt vmcnt(" #n ")" ::: "memory")
; #define PG8_WAIT_L(n) asm volatile("s_waitcnt lgkmcnt(" #n ")" ::: "memory")
; #define PG8_BAR __builtin_amdgcn_s_barrier()
; #define PG8_SCHED __builtin_amdgcn_sched_barrier(0)
; template <class Epi, class Sched, bool ALIGN_EPI = true, bool SP2 = true, bool GS = false>
; __device__ __forceinline__ void gemm_phase(PG8_LAS unsigned char* lds, const Gemm g, const Sched& S, const Epi& E, const float* gs_ss = nullptr) {
;     ...
;             PG8_LDA(At, 0, 1); PG8_STAGE(PG8_SB(0, 0), b2, voffB); PG8_STAGE(PG8_SB(0, 1), b2 + hstep, voffB); PG8_STAGE(PG8_SA(0, 0), a2, voffA);
;             PG8_WAIT_V(8); PG8_WAIT_L(0); PG8_BAR; PG8_MMA(1, 0, At, B0); PG8_MMA(1, 1, At, B1); PG8_BAR; PG8_SCHED;
;             PG8_LDB(B0, 1, 0); PG8_LDB(B1, 1, 1); PG8_SCHED; PG8_LDA(At, 1, 0); PG8_STAGE(PG8_SA(0, 1), a2 + hstep, voffA);
;             PG8_WAIT_V(8); PG8_WAIT_L(0); PG8_BAR; PG8_MMA(0, 0, At, B0); PG8_MMA(0, 1, At, B1); PG8_BAR; PG8_SCHED;
	s_setprio 1
	s_waitcnt lgkmcnt(0)
	v_mfma_f32_16x16x32_bf16 v[62:65], v[148:151], v[184:187], v[62:65]
	v_mfma_f32_16x16x32_bf16 v[58:61], v[156:159], v[184:187], v[58:61]
	v_mfma_f32_16x16x32_bf16 v[54:57], v[148:151], v[192:195], v[54:57]
	v_mfma_f32_16x16x32_bf16 v[46:49], v[156:159], v[192:195], v[46:49]
	v_mfma_f32_16x16x32_bf16 v[38:41], v[148:151], v[200:203], v[38:41]
	v_mfma_f32_16x16x32_bf16 v[30:33], v[156:159], v[200:203], v[30:33]
	v_mfma_f32_16x16x32_bf16 v[22:25], v[148:151], v[208:211], v[22:25]
	v_mfma_f32_16x16x32_bf16 v[14:17], v[156:159], v[208:211], v[14:17]
	v_mfma_f32_16x16x32_bf16 v[62:65], v[152:155], v[188:191], v[62:65]
	v_mfma_f32_16x16x32_bf16 v[58:61], v[160:163], v[188:191], v[58:61]
	v_mfma_f32_16x16x32_bf16 v[54:57], v[152:155], v[196:199], v[54:57]
	v_mfma_f32_16x16x32_bf16 v[46:49], v[160:163], v[196:199], v[46:49]
	v_mfma_f32_16x16x32_bf16 v[38:41], v[152:155], v[204:207], v[38:41]
	v_mfma_f32_16x16x32_bf16 v[30:33], v[160:163], v[204:207], v[30:33]
	v_mfma_f32_16x16x32_bf16 v[22:25], v[152:155], v[212:215], v[22:25]
	v_mfma_f32_16x16x32_bf16 v[14:17], v[160:163], v[212:215], v[14:17]
	s_setprio 0
	s_setprio 1
	v_mfma_f32_16x16x32_bf16 v[50:53], v[164:167], v[184:187], v[50:53]
	v_mfma_f32_16x16x32_bf16 v[42:45], v[172:175], v[184:187], v[42:45]
	v_mfma_f32_16x16x32_bf16 v[34:37], v[164:167], v[192:195], v[34:37]
	v_mfma_f32_16x16x32_bf16 v[26:29], v[172:175], v[192:195], v[26:29]
	v_mfma_f32_16x16x32_bf16 v[18:21], v[164:167], v[200:203], v[18:21]
	v_mfma_f32_16x16x32_bf16 v[10:13], v[172:175], v[200:203], v[10:13]
	v_mfma_f32_16x16x32_bf16 v[6:9], v[164:167], v[208:211], v[6:9]
	v_mfma_f32_16x16x32_bf16 v[2:5], v[172:175], v[208:211], v[2:5]
	v_mfma_f32_16x16x32_bf16 v[50:53], v[168:171], v[188:191], v[50:53]
	v_mfma_f32_16x16x32_bf16 v[42:45], v[180:183], v[188:191], v[42:45]
	v_mfma_f32_16x16x32_bf16 v[34:37], v[168:171], v[196:199], v[34:37]
	v_mfma_f32_16x16x32_bf16 v[26:29], v[180:183], v[196:199], v[26:29]
	v_mfma_f32_16x16x32_bf16 v[18:21], v[168:171], v[204:207], v[18:21]
	v_mfma_f32_16x16x32_bf16 v[10:13], v[180:183], v[204:207], v[10:13]
	v_mfma_f32_16x16x32_bf16 v[6:9], v[168:171], v[212:215], v[6:9]
	v_mfma_f32_16x16x32_bf16 v[2:5], v[180:183], v[212:215], v[2:5]
	s_setprio 0
	s_barrier
	s_add_i32 s59, 0, 0x18000
	v_add_u32_e32 v0, s59, v145
	s_add_i32 s60, 0, 0x1c000
	ds_read_b128 v[148:151], v0
	ds_read_b128 v[152:155], v0 offset:1024
	ds_read_b128 v[156:159], v0 offset:2048
	ds_read_b128 v[160:163], v0 offset:3072
	v_add_u32_e32 v0, s60, v145
	ds_read_b128 v[164:167], v0
	ds_read_b128 v[168:171], v0 offset:1024
	ds_read_b128 v[172:175], v0 offset:2048
	ds_read_b128 v[180:183], v0 offset:3072
	s_add_u32 s20, s20, 0x80000
	s_addc_u32 s21, s21, 0
	s_mov_b32 m0, s30
	v_lshl_add_u64 v[220:221], s[20:21], 0, v[136:137]
	ds_read_b128 v[184:187], v147 offset:32768
	ds_read_b128 v[188:191], v147 offset:33792
	ds_read_b128 v[192:195], v147 offset:34816
	ds_read_b128 v[196:199], v147 offset:35840
	ds_read_b128 v[200:203], v147 offset:36864
	ds_read_b128 v[204:207], v147 offset:37888
	ds_read_b128 v[208:211], v147 offset:38912
	ds_read_b128 v[212:215], v147 offset:39936
	global_load_lds_dwordx4 v[220:221], off
	v_lshl_add_u64 v[220:221], s[20:21], 0, v[132:133]
	s_mov_b32 m0, s36
	s_nop 0
	global_load_lds_dwordx4 v[220:221], off
	s_waitcnt vmcnt(8)
	s_waitcnt lgkmcnt(0)
	s_barrier
	s_setprio 1
	s_waitcnt lgkmcnt(0)
	v_mfma_f32_16x16x32_bf16 v[126:129], v[148:151], v[184:187], v[126:129]
	v_mfma_f32_16x16x32_bf16 v[122:125], v[156:159], v[184:187], v[122:125]
	v_mfma_f32_16x16x32_bf16 v[118:121], v[148:151], v[192:195], v[118:121]
	v_mfma_f32_16x16x32_bf16 v[110:113], v[156:159], v[192:195], v[110:113]
	v_mfma_f32_16x16x32_bf16 v[102:105], v[148:151], v[200:203], v[102:105]
	v_mfma_f32_16x16x32_bf16 v[94:97], v[156:159], v[200:203], v[94:97]
	v_mfma_f32_16x16x32_bf16 v[86:89], v[148:151], v[208:211], v[86:89]
	v_mfma_f32_16x16x32_bf16 v[78:81], v[156:159], v[208:211], v[78:81]
	v_mfma_f32_16x16x32_bf16 v[126:129], v[152:155], v[188:191], v[126:129]
	v_mfma_f32_16x16x32_bf16 v[122:125], v[160:163], v[188:191], v[122:125]
	v_mfma_f32_16x16x32_bf16 v[118:121], v[152:155], v[196:199], v[118:121]
	v_mfma_f32_16x16x32_bf16 v[110:113], v[160:163], v[196:199], v[110:113]
	v_mfma_f32_16x16x32_bf16 v[102:105], v[152:155], v[204:207], v[102:105]
	v_mfma_f32_16x16x32_bf16 v[94:97], v[160:163], v[204:207], v[94:97]
	v_mfma_f32_16x16x32_bf16 v[86:89], v[152:155], v[212:215], v[86:89]
	v_mfma_f32_16x16x32_bf16 v[78:81], v[160:163], v[212:215], v[78:81]
	s_setprio 0
	s_setprio 1
	v_mfma_f32_16x16x32_bf16 v[114:117], v[164:167], v[184:187], v[114:117]
	v_mfma_f32_16x16x32_bf16 v[106:109], v[172:175], v[184:187], v[106:109]
	v_mfma_f32_16x16x32_bf16 v[98:101], v[164:167], v[192:195], v[98:101]
	v_mfma_f32_16x16x32_bf16 v[90:93], v[172:175], v[192:195], v[90:93]
	v_mfma_f32_16x16x32_bf16 v[82:85], v[164:167], v[200:203], v[82:85]
	v_mfma_f32_16x16x32_bf16 v[74:77], v[172:175], v[200:203], v[74:77]
	v_mfma_f32_16x16x32_bf16 v[70:73], v[164:167], v[208:211], v[70:73]
	v_mfma_f32_16x16x32_bf16 v[66:69], v[172:175], v[208:211], v[66:69]
	v_mfma_f32_16x16x32_bf16 v[114:117], v[168:171], v[188:191], v[114:117]
	v_mfma_f32_16x16x32_bf16 v[106:109], v[180:183], v[188:191], v[106:109]
	v_mfma_f32_16x16x32_bf16 v[98:101], v[168:171], v[196:199], v[98:101]
	v_mfma_f32_16x16x32_bf16 v[90:93], v[180:183], v[196:199], v[90:93]
	v_mfma_f32_16x16x32_bf16 v[82:85], v[168:171], v[204:207], v[82:85]
	v_mfma_f32_16x16x32_bf16 v[74:77], v[180:183], v[204:207], v[74:77]
	v_mfma_f32_16x16x32_bf16 v[70:73], v[168:171], v[212:215], v[70:73]
	v_mfma_f32_16x16x32_bf16 v[66:69], v[180:183], v[212:215], v[66:69]
	s_setprio 0
	s_barrier
; #define PG8_STAGE(bufoff, gbase, voff) do { _Pragma("unroll") for (int _i = 0; _i < 2; ++_i) \
;         __builtin_amdgcn_global_load_lds((const unsigned*)((const char*)(gbase) + (voff)[_i]), (PG8_LAS unsigned*)(lds + (bufoff) + ldsw + _i * 8192), 16, 0, 0); } while (0)
; #define PG8_LDA(dst, b, h) do { _Pragma("unroll") for (int m = 0; m < 4; ++m) _Pragma("unroll") for (int k = 0; k < 2; ++k) dst[m][k] = *(const PG8_LAS bf16x8*)(lds + PG8_SA(b, h) + aoff + m * 2048 + k * 1024); } while (0)
; #define PG8_MMA(ai, bj, At, Bt) do { __builtin_amdgcn_s_setprio(1); _Pragma("unroll") for (int m = 0; m < 4; ++m) _Pragma("unroll") for (int n = 0; n < 2; ++n) _Pragma("unroll") for (int k = 0; k < 2; ++k) \
;         acc[ai][bj][m][n] = __builtin_amdgcn_mfma_f32_16x16x32_bf16(Bt[n][k], At[m][k], acc[ai][bj][m][n], 0, 0, 0); __builtin_amdgcn_s_setprio(0); } while (0)
; #define PG8_WAIT_V(n) asm volatile("s_waitcnt vmcnt(" #n ")" ::: "memory")
; #define PG8_WAIT_L(n) asm volatile("s_waitcnt lgkmcnt(" #n ")" ::: "memory")
; #define PG8_BAR __builtin_amdgcn_s_barrier()
; #define PG8_SCHED __builtin_amdgcn_sched_barrier(0)
; template <class Epi, class Sched, bool ALIGN_EPI = true, bool SP2 = true, bool GS = false>
; __device__ __forceinline__ void gemm_phase(PG8_LAS unsigned char* lds, const Gemm g, const Sched& S, const Epi& E, const float* gs_ss = nullptr) {
;     ...
;         for (int t = 0; t < nt; t += 2) {
;     ...
;             PG8_WAIT_V(8); PG8_WAIT_L(0); PG8_BAR; PG8_MMA(0, 0, At, B0); PG8_MMA(0, 1, At, B1); PG8_BAR; PG8_SCHED;
;             PG8_LDA(At, 1, 1); PG8_STAGE(PG8_SB(1, 0), b3, voffB); PG8_STAGE(PG8_SB(1, 1), b3 + hstep, voffB); PG8_STAGE(PG8_SA(1, 0), a3, voffA);
;             PG8_WAIT_V(8); PG8_WAIT_L(0); PG8_BAR; PG8_MMA(1, 0, At, B0); PG8_MMA(1, 1, At, B1); PG8_BAR; PG8_SCHED;
	s_add_i32 s20, s59, s23
	v_lshl_add_u64 v[142:143], v[142:143], 0, s[26:27]
	s_mov_b32 m0, s20
	ds_read_b128 v[184:187], v147 offset:49152
	ds_read_b128 v[188:191], v147 offset:50176
	ds_read_b128 v[192:195], v147 offset:51200
	ds_read_b128 v[196:199], v147 offset:52224
	ds_read_b128 v[200:203], v147 offset:53248
	ds_read_b128 v[204:207], v147 offset:54272
	ds_read_b128 v[208:211], v147 offset:55296
	ds_read_b128 v[212:215], v147 offset:56320
	global_load_lds_dwordx4 v[142:143], off
	s_add_i32 m0, s20, 0x2000
	s_add_u32 s2, s2, 0x80080
	v_lshl_add_u64 v[142:143], v[176:177], 0, s[26:27]
	s_addc_u32 s3, s3, 0
	s_add_i32 s20, s60, s23
	global_load_lds_dwordx4 v[142:143], off
	v_lshl_add_u64 v[142:143], s[2:3], 0, v[134:135]
	s_mov_b32 m0, s20
	s_nop 0
	global_load_lds_dwordx4 v[142:143], off
	v_lshl_add_u64 v[142:143], s[2:3], 0, v[130:131]
	s_add_i32 m0, s20, 0x2000
	s_nop 0
	global_load_lds_dwordx4 v[142:143], off
	v_lshl_add_u64 v[142:143], v[216:217], 0, s[26:27]
	s_mov_b32 m0, s47
	s_nop 0
	global_load_lds_dwordx4 v[142:143], off
	v_lshl_add_u64 v[142:143], v[218:219], 0, s[26:27]
	s_mov_b32 m0, s48
	s_nop 0
	global_load_lds_dwordx4 v[142:143], off
	s_waitcnt vmcnt(8)
	s_waitcnt lgkmcnt(0)
	s_barrier
	s_setprio 1
	s_waitcnt lgkmcnt(0)
	v_mfma_f32_16x16x32_bf16 v[62:65], v[148:151], v[184:187], v[62:65]
	v_mfma_f32_16x16x32_bf16 v[58:61], v[156:159], v[184:187], v[58:61]
	v_mfma_f32_16x16x32_bf16 v[54:57], v[148:151], v[192:195], v[54:57]
	v_mfma_f32_16x16x32_bf16 v[46:49], v[156:159], v[192:195], v[46:49]
	v_mfma_f32_16x16x32_bf16 v[38:41], v[148:151], v[200:203], v[38:41]
	v_mfma_f32_16x16x32_bf16 v[30:33], v[156:159], v[200:203], v[30:33]
	v_mfma_f32_16x16x32_bf16 v[22:25], v[148:151], v[208:211], v[22:25]
	v_mfma_f32_16x16x32_bf16 v[14:17], v[156:159], v[208:211], v[14:17]
	v_mfma_f32_16x16x32_bf16 v[62:65], v[152:155], v[188:191], v[62:65]
	v_mfma_f32_16x16x32_bf16 v[58:61], v[160:163], v[188:191], v[58:61]
	v_mfma_f32_16x16x32_bf16 v[54:57], v[152:155], v[196:199], v[54:57]
	v_mfma_f32_16x16x32_bf16 v[46:49], v[160:163], v[196:199], v[46:49]
	v_mfma_f32_16x16x32_bf16 v[38:41], v[152:155], v[204:207], v[38:41]
	v_mfma_f32_16x16x32_bf16 v[30:33], v[160:163], v[204:207], v[30:33]
	v_mfma_f32_16x16x32_bf16 v[22:25], v[152:155], v[212:215], v[22:25]
	v_mfma_f32_16x16x32_bf16 v[14:17], v[160:163], v[212:215], v[14:17]
	s_setprio 0
	s_setprio 1
	v_mfma_f32_16x16x32_bf16 v[50:53], v[164:167], v[184:187], v[50:53]
	v_mfma_f32_16x16x32_bf16 v[42:45], v[172:175], v[184:187], v[42:45]
	v_mfma_f32_16x16x32_bf16 v[34:37], v[164:167], v[192:195], v[34:37]
	v_mfma_f32_16x16x32_bf16 v[26:29], v[172:175], v[192:195], v[26:29]
	v_mfma_f32_16x16x32_bf16 v[18:21], v[164:167], v[200:203], v[18:21]
	v_mfma_f32_16x16x32_bf16 v[10:13], v[172:175], v[200:203], v[10:13]
	v_mfma_f32_16x16x32_bf16 v[6:9], v[164:167], v[208:211], v[6:9]
	v_mfma_f32_16x16x32_bf16 v[2:5], v[172:175], v[208:211], v[2:5]
	v_mfma_f32_16x16x32_bf16 v[50:53], v[168:171], v[188:191], v[50:53]
	v_mfma_f32_16x16x32_bf16 v[42:45], v[180:183], v[188:191], v[42:45]
	v_mfma_f32_16x16x32_bf16 v[34:37], v[168:171], v[196:199], v[34:37]
	v_mfma_f32_16x16x32_bf16 v[26:29], v[180:183], v[196:199], v[26:29]
	v_mfma_f32_16x16x32_bf16 v[18:21], v[168:171], v[204:207], v[18:21]
	v_mfma_f32_16x16x32_bf16 v[10:13], v[180:183], v[204:207], v[10:13]
	v_mfma_f32_16x16x32_bf16 v[6:9], v[168:171], v[212:215], v[6:9]
	v_mfma_f32_16x16x32_bf16 v[2:5], v[180:183], v[212:215], v[2:5]
	s_setprio 0
	s_add_i32 s58, s58, 2
	s_add_u32 s44, s44, 0x100
	s_addc_u32 s45, s45, 0
	s_add_u32 s56, s56, 0x100
	s_addc_u32 s57, s57, 0
	s_cmp_gt_u32 s58, 5
	s_barrier
	s_cbranch_scc0 .LBB0_1119
	s_and_b64 vcc, exec, s[38:39]
	s_cbranch_vccz .LBB0_1122
	s_barrier

; #define PG8_STAGE(bufoff, gbase, voff) do { _Pragma("unroll") for (int _i = 0; _i < 2; ++_i) \
;         __builtin_amdgcn_global_load_lds((const unsigned*)((const char*)(gbase) + (voff)[_i]), (PG8_LAS unsigned*)(lds + (bufoff) + ldsw + _i * 8192), 16, 0, 0); } while (0)
; #define PG8_LDA(dst, b, h) do { _Pragma("unroll") for (int m = 0; m < 4; ++m) _Pragma("unroll") for (int k = 0; k < 2; ++k) dst[m][k] = *(const PG8_LAS bf16x8*)(lds + PG8_SA(b, h) + aoff + m * 2048 + k * 1024); } while (0)
; #define PG8_LDB(dst, b, h) do { _Pragma("unroll") for (int n = 0; n < 2; ++n) _Pragma("unroll") for (int k = 0; k < 2; ++k) dst[n][k] = *(const PG8_LAS bf16x8*)(lds + PG8_SB(b, h) + boff + n * 2048 + k * 1024); } while (0)
; #define PG8_MMA(ai, bj, At, Bt) do { __builtin_amdgcn_s_setprio(1); _Pragma("unroll") for (int m = 0; m < 4; ++m) _Pragma("unroll") for (int n = 0; n < 2; ++n) _Pragma("unroll") for (int k = 0; k < 2; ++k) \
;         acc[ai][bj][m][n] = __builtin_amdgcn_mfma_f32_16x16x32_bf16(Bt[n][k], At[m][k], acc[ai][bj][m][n], 0, 0, 0); __builtin_amdgcn_s_setprio(0); } while (0)
; #define PG8_WAIT_V(n) asm volatile("s_waitcnt vmcnt(" #n ")" ::: "memory")
; #define PG8_WAIT_L(n) asm volatile("s_waitcnt lgkmcnt(" #n ")" ::: "memory")
; #define PG8_BAR __builtin_amdgcn_s_barrier()
; #define PG8_SCHED __builtin_amdgcn_sched_barrier(0)
; template <class Epi, class Sched, bool ALIGN_EPI = true, bool SP2 = true, bool GS = false>
; __device__ __forceinline__ void gemm_phase(PG8_LAS unsigned char* lds, const Gemm g, const Sched& S, const Epi& E, const float* gs_ss = nullptr) {
;     ...
;         for (int t = 0; t < nt; t += 2) {
;             const bool last = (t == nt - 2);
;             const char* a1 = cA + (size_t)(t + 1) * kstep;
;             const char* a2 = last ? nA : cA + (size_t)(t + 2) * kstep; const char* b2 = last ? nB : cB + (size_t)(t + 2) * kstep;
;             const char* a3 = a2 + kstep; const char* b3 = b2 + kstep;
;             if constexpr (SP2) {
;             PG8_LDB(B0, 0, 0); PG8_LDB(B1, 0, 1); PG8_SCHED; PG8_LDA(At, 0, 0); PG8_STAGE(PG8_SA(1, 1), a1 + hstep, voffA);
;             PG8_WAIT_V(8); PG8_WAIT_L(0); PG8_BAR; PG8_MMA(0, 0, At, B0); PG8_MMA(0, 1, At, B1); PG8_BAR; PG8_SCHED;
;             PG8_LDA(At, 0, 1); PG8_STAGE(PG8_SB(0, 0), b2, voffB); PG8_STAGE(PG8_SB(0, 1), b2 + hstep, voffB); PG8_STAGE(PG8_SA(0, 0), a2, voffA);
.LBB0_1252:
	s_add_i32 s65, 0, 0x10000
	s_add_i32 s67, 0, 0x14000
	v_add_u32_e32 v142, s65, v183
	v_add_u32_e32 v168, s67, v183
	ds_read_b128 v[122:125], v142
	ds_read_b128 v[130:133], v142 offset:1024
	ds_read_b128 v[138:141], v142 offset:2048
	ds_read_b128 v[142:145], v142 offset:3072
	ds_read_b128 v[156:159], v168
	ds_read_b128 v[160:163], v168 offset:1024
	ds_read_b128 v[164:167], v168 offset:2048
	ds_read_b128 v[168:171], v168 offset:3072
	v_lshl_add_u64 v[176:177], s[56:57], 0, v[152:153]
	s_add_i32 m0, s9, 0xc000
	ds_read_b128 v[172:175], v197
	ds_read_b128 v[184:187], v197 offset:1024
	ds_read_b128 v[188:191], v197 offset:2048
	ds_read_b128 v[192:195], v197 offset:3072
	ds_read_b128 v[198:201], v197 offset:4096
	ds_read_b128 v[202:205], v197 offset:5120
	ds_read_b128 v[206:209], v197 offset:6144
	ds_read_b128 v[210:213], v197 offset:7168
	global_load_lds_dwordx4 v[176:177], off
	v_lshl_add_u64 v[176:177], s[56:57], 0, v[154:155]
	s_add_i32 m0, s9, 0xe000
	s_nop 0
	global_load_lds_dwordx4 v[176:177], off
	s_add_u32 s2, s56, 0xfffe0080
	s_addc_u32 s3, s57, -1
	s_cmp_eq_u32 s64, 4
	s_cselect_b32 s21, s18, s3
	s_cselect_b32 s20, s51, s2
	s_cselect_b32 s3, s49, s59
	s_cselect_b32 s2, s63, s58
	s_waitcnt vmcnt(8)
	s_waitcnt lgkmcnt(0)
	s_barrier
	s_setprio 1
	s_waitcnt lgkmcnt(0)
	v_mfma_f32_16x16x32_bf16 v[134:137], v[122:125], v[172:175], v[134:137]
	v_mfma_f32_16x16x32_bf16 v[126:129], v[138:141], v[172:175], v[126:129]
	v_mfma_f32_16x16x32_bf16 v[110:113], v[122:125], v[188:191], v[110:113]
	v_mfma_f32_16x16x32_bf16 v[106:109], v[138:141], v[188:191], v[106:109]
	v_mfma_f32_16x16x32_bf16 v[94:97], v[122:125], v[198:201], v[94:97]
	v_mfma_f32_16x16x32_bf16 v[90:93], v[138:141], v[198:201], v[90:93]
	v_mfma_f32_16x16x32_bf16 v[78:81], v[122:125], v[206:209], v[78:81]
	v_mfma_f32_16x16x32_bf16 v[74:77], v[138:141], v[206:209], v[74:77]
	v_mfma_f32_16x16x32_bf16 v[134:137], v[130:133], v[184:187], v[134:137]
	v_mfma_f32_16x16x32_bf16 v[126:129], v[142:145], v[184:187], v[126:129]
	v_mfma_f32_16x16x32_bf16 v[110:113], v[130:133], v[192:195], v[110:113]
	v_mfma_f32_16x16x32_bf16 v[106:109], v[142:145], v[192:195], v[106:109]
	v_mfma_f32_16x16x32_bf16 v[94:97], v[130:133], v[202:205], v[94:97]
	v_mfma_f32_16x16x32_bf16 v[90:93], v[142:145], v[202:205], v[90:93]
	v_mfma_f32_16x16x32_bf16 v[78:81], v[130:133], v[210:213], v[78:81]
	v_mfma_f32_16x16x32_bf16 v[74:77], v[142:145], v[210:213], v[74:77]
	s_setprio 0
	s_setprio 1
	v_mfma_f32_16x16x32_bf16 v[118:121], v[156:159], v[172:175], v[118:121]
	v_mfma_f32_16x16x32_bf16 v[114:117], v[164:167], v[172:175], v[114:117]
	v_mfma_f32_16x16x32_bf16 v[102:105], v[156:159], v[188:191], v[102:105]
	v_mfma_f32_16x16x32_bf16 v[98:101], v[164:167], v[188:191], v[98:101]
	v_mfma_f32_16x16x32_bf16 v[86:89], v[156:159], v[198:201], v[86:89]
	v_mfma_f32_16x16x32_bf16 v[82:85], v[164:167], v[198:201], v[82:85]
	v_mfma_f32_16x16x32_bf16 v[70:73], v[156:159], v[206:209], v[70:73]
	v_mfma_f32_16x16x32_bf16 v[66:69], v[164:167], v[206:209], v[66:69]
	v_mfma_f32_16x16x32_bf16 v[118:121], v[160:163], v[184:187], v[118:121]
	v_mfma_f32_16x16x32_bf16 v[114:117], v[168:171], v[184:187], v[114:117]
	v_mfma_f32_16x16x32_bf16 v[102:105], v[160:163], v[192:195], v[102:105]
	v_mfma_f32_16x16x32_bf16 v[98:101], v[168:171], v[192:195], v[98:101]
	v_mfma_f32_16x16x32_bf16 v[86:89], v[160:163], v[202:205], v[86:89]
	v_mfma_f32_16x16x32_bf16 v[82:85], v[168:171], v[202:205], v[82:85]
	v_mfma_f32_16x16x32_bf16 v[70:73], v[160:163], v[210:213], v[70:73]
	v_mfma_f32_16x16x32_bf16 v[66:69], v[168:171], v[210:213], v[66:69]
	s_setprio 0
	s_barrier
	s_add_i32 s65, s65, s24
	v_lshl_add_u64 v[176:177], s[2:3], 0, v[0:1]
	s_mov_b32 m0, s65
	ds_read_b128 v[172:175], v197 offset:16384
	ds_read_b128 v[184:187], v197 offset:17408
	ds_read_b128 v[188:191], v197 offset:18432
	ds_read_b128 v[192:195], v197 offset:19456
	ds_read_b128 v[198:201], v197 offset:20480
	ds_read_b128 v[202:205], v197 offset:21504
	ds_read_b128 v[206:209], v197 offset:22528
	ds_read_b128 v[210:213], v197 offset:23552
	global_load_lds_dwordx4 v[176:177], off
	s_add_i32 m0, s65, 0x2000
	s_add_u32 s70, s2, 0x20000
	v_lshl_add_u64 v[180:181], s[2:3], 0, v[150:151]
	s_addc_u32 s71, s3, 0
	s_add_i32 s65, s67, s24
	global_load_lds_dwordx4 v[180:181], off
	v_lshl_add_u64 v[214:215], s[70:71], 0, v[0:1]
	s_mov_b32 m0, s65
	v_lshl_add_u64 v[216:217], s[20:21], 0, v[148:149]
	global_load_lds_dwordx4 v[214:215], off
	v_lshl_add_u64 v[214:215], s[70:71], 0, v[150:151]
	s_add_i32 m0, s65, 0x2000
	s_nop 0
	global_load_lds_dwordx4 v[214:215], off
	v_lshl_add_u64 v[214:215], s[20:21], 0, v[146:147]
	s_mov_b32 m0, s9
	s_nop 0
	global_load_lds_dwordx4 v[214:215], off
	s_mov_b32 m0, s13
	s_nop 0
	global_load_lds_dwordx4 v[216:217], off
	s_waitcnt vmcnt(8)
	s_waitcnt lgkmcnt(0)
	s_barrier
; #define PG8_STAGE(bufoff, gbase, voff) do { _Pragma("unroll") for (int _i = 0; _i < 2; ++_i) \
;         __builtin_amdgcn_global_load_lds((const unsigned*)((const char*)(gbase) + (voff)[_i]), (PG8_LAS unsigned*)(lds + (bufoff) + ldsw + _i * 8192), 16, 0, 0); } while (0)
; #define PG8_LDA(dst, b, h) do { _Pragma("unroll") for (int m = 0; m < 4; ++m) _Pragma("unroll") for (int k = 0; k < 2; ++k) dst[m][k] = *(const PG8_LAS bf16x8*)(lds + PG8_SA(b, h) + aoff + m * 2048 + k * 1024); } while (0)
; #define PG8_LDB(dst, b, h) do { _Pragma("unroll") for (int n = 0; n < 2; ++n) _Pragma("unroll") for (int k = 0; k < 2; ++k) dst[n][k] = *(const PG8_LAS bf16x8*)(lds + PG8_SB(b, h) + boff + n * 2048 + k * 1024); } while (0)
; #define PG8_MMA(ai, bj, At, Bt) do { __builtin_amdgcn_s_setprio(1); _Pragma("unroll") for (int m = 0; m < 4; ++m) _Pragma("unroll") for (int n = 0; n < 2; ++n) _Pragma("unroll") for (int k = 0; k < 2; ++k) \
;         acc[ai][bj][m][n] = __builtin_amdgcn_mfma_f32_16x16x32_bf16(Bt[n][k], At[m][k], acc[ai][bj][m][n], 0, 0, 0); __builtin_amdgcn_s_setprio(0); } while (0)
; #define PG8_WAIT_V(n) asm volatile("s_waitcnt vmcnt(" #n ")" ::: "memory")
; #define PG8_WAIT_L(n) asm volatile("s_waitcnt lgkmcnt(" #n ")" ::: "memory")
; #define PG8_BAR __builtin_amdgcn_s_barrier()
; #define PG8_SCHED __builtin_amdgcn_sched_barrier(0)
; template <class Epi, class Sched, bool ALIGN_EPI = true, bool SP2 = true, bool GS = false>
; __device__ __forceinline__ void gemm_phase(PG8_LAS unsigned char* lds, const Gemm g, const Sched& S, const Epi& E, const float* gs_ss = nullptr) {
;     ...
;             PG8_LDA(At, 0, 1); PG8_STAGE(PG8_SB(0, 0), b2, voffB); PG8_STAGE(PG8_SB(0, 1), b2 + hstep, voffB); PG8_STAGE(PG8_SA(0, 0), a2, voffA);
;             PG8_WAIT_V(8); PG8_WAIT_L(0); PG8_BAR; PG8_MMA(1, 0, At, B0); PG8_MMA(1, 1, At, B1); PG8_BAR; PG8_SCHED;
;             PG8_LDB(B0, 1, 0); PG8_LDB(B1, 1, 1); PG8_SCHED; PG8_LDA(At, 1, 0); PG8_STAGE(PG8_SA(0, 1), a2 + hstep, voffA);
;             PG8_WAIT_V(8); PG8_WAIT_L(0); PG8_BAR; PG8_MMA(0, 0, At, B0); PG8_MMA(0, 1, At, B1); PG8_BAR; PG8_SCHED;
	s_setprio 1
	s_waitcnt lgkmcnt(0)
	v_mfma_f32_16x16x32_bf16 v[62:65], v[122:125], v[172:175], v[62:65]
	v_mfma_f32_16x16x32_bf16 v[58:61], v[138:141], v[172:175], v[58:61]
	v_mfma_f32_16x16x32_bf16 v[46:49], v[122:125], v[188:191], v[46:49]
	v_mfma_f32_16x16x32_bf16 v[42:45], v[138:141], v[188:191], v[42:45]
	v_mfma_f32_16x16x32_bf16 v[30:33], v[122:125], v[198:201], v[30:33]
	v_mfma_f32_16x16x32_bf16 v[26:29], v[138:141], v[198:201], v[26:29]
	v_mfma_f32_16x16x32_bf16 v[14:17], v[122:125], v[206:209], v[14:17]
	v_mfma_f32_16x16x32_bf16 v[10:13], v[138:141], v[206:209], v[10:13]
	v_mfma_f32_16x16x32_bf16 v[62:65], v[130:133], v[184:187], v[62:65]
	v_mfma_f32_16x16x32_bf16 v[58:61], v[142:145], v[184:187], v[58:61]
	v_mfma_f32_16x16x32_bf16 v[46:49], v[130:133], v[192:195], v[46:49]
	v_mfma_f32_16x16x32_bf16 v[42:45], v[142:145], v[192:195], v[42:45]
	v_mfma_f32_16x16x32_bf16 v[30:33], v[130:133], v[202:205], v[30:33]
	v_mfma_f32_16x16x32_bf16 v[26:29], v[142:145], v[202:205], v[26:29]
	v_mfma_f32_16x16x32_bf16 v[14:17], v[130:133], v[210:213], v[14:17]
	v_mfma_f32_16x16x32_bf16 v[10:13], v[142:145], v[210:213], v[10:13]
	s_setprio 0
	s_setprio 1
	v_mfma_f32_16x16x32_bf16 v[54:57], v[156:159], v[172:175], v[54:57]
	v_mfma_f32_16x16x32_bf16 v[50:53], v[164:167], v[172:175], v[50:53]
	v_mfma_f32_16x16x32_bf16 v[38:41], v[156:159], v[188:191], v[38:41]
	v_mfma_f32_16x16x32_bf16 v[34:37], v[164:167], v[188:191], v[34:37]
	v_mfma_f32_16x16x32_bf16 v[22:25], v[156:159], v[198:201], v[22:25]
	v_mfma_f32_16x16x32_bf16 v[18:21], v[164:167], v[198:201], v[18:21]
	v_mfma_f32_16x16x32_bf16 v[6:9], v[156:159], v[206:209], v[6:9]
	v_mfma_f32_16x16x32_bf16 v[2:5], v[164:167], v[206:209], v[2:5]
	v_mfma_f32_16x16x32_bf16 v[54:57], v[160:163], v[184:187], v[54:57]
	v_mfma_f32_16x16x32_bf16 v[50:53], v[168:171], v[184:187], v[50:53]
	v_mfma_f32_16x16x32_bf16 v[38:41], v[160:163], v[192:195], v[38:41]
	v_mfma_f32_16x16x32_bf16 v[34:37], v[168:171], v[192:195], v[34:37]
	v_mfma_f32_16x16x32_bf16 v[22:25], v[160:163], v[202:205], v[22:25]
	v_mfma_f32_16x16x32_bf16 v[18:21], v[168:171], v[202:205], v[18:21]
	v_mfma_f32_16x16x32_bf16 v[6:9], v[160:163], v[210:213], v[6:9]
	v_mfma_f32_16x16x32_bf16 v[2:5], v[168:171], v[210:213], v[2:5]
	s_setprio 0
	s_barrier
	s_add_i32 s65, 0, 0x18000
	s_add_i32 s67, 0, 0x1c000
	v_add_u32_e32 v142, s65, v183
	v_add_u32_e32 v168, s67, v183
	ds_read_b128 v[122:125], v142
	ds_read_b128 v[130:133], v142 offset:1024
	ds_read_b128 v[138:141], v142 offset:2048
	ds_read_b128 v[142:145], v142 offset:3072
	ds_read_b128 v[156:159], v168
	ds_read_b128 v[160:163], v168 offset:1024
	ds_read_b128 v[164:167], v168 offset:2048
	ds_read_b128 v[168:171], v168 offset:3072
	s_add_u32 s20, s20, 0x20000
	s_addc_u32 s21, s21, 0
	s_mov_b32 m0, s25
	v_lshl_add_u64 v[218:219], s[20:21], 0, v[146:147]
	ds_read_b128 v[172:175], v197 offset:32768
	ds_read_b128 v[184:187], v197 offset:33792
	ds_read_b128 v[188:191], v197 offset:34816
	ds_read_b128 v[192:195], v197 offset:35840
	ds_read_b128 v[198:201], v197 offset:36864
	ds_read_b128 v[202:205], v197 offset:37888
	ds_read_b128 v[206:209], v197 offset:38912
	ds_read_b128 v[210:213], v197 offset:39936
	global_load_lds_dwordx4 v[218:219], off
	v_lshl_add_u64 v[218:219], s[20:21], 0, v[148:149]
	s_mov_b32 m0, s30
	s_nop 0
	global_load_lds_dwordx4 v[218:219], off
	s_waitcnt vmcnt(8)
	s_waitcnt lgkmcnt(0)
	s_barrier
	s_setprio 1
	s_waitcnt lgkmcnt(0)
	v_mfma_f32_16x16x32_bf16 v[134:137], v[122:125], v[172:175], v[134:137]
	v_mfma_f32_16x16x32_bf16 v[126:129], v[138:141], v[172:175], v[126:129]
	v_mfma_f32_16x16x32_bf16 v[110:113], v[122:125], v[188:191], v[110:113]
	v_mfma_f32_16x16x32_bf16 v[106:109], v[138:141], v[188:191], v[106:109]
	v_mfma_f32_16x16x32_bf16 v[94:97], v[122:125], v[198:201], v[94:97]
	v_mfma_f32_16x16x32_bf16 v[90:93], v[138:141], v[198:201], v[90:93]
	v_mfma_f32_16x16x32_bf16 v[78:81], v[122:125], v[206:209], v[78:81]
	v_mfma_f32_16x16x32_bf16 v[74:77], v[138:141], v[206:209], v[74:77]
	v_mfma_f32_16x16x32_bf16 v[134:137], v[130:133], v[184:187], v[134:137]
	v_mfma_f32_16x16x32_bf16 v[126:129], v[142:145], v[184:187], v[126:129]
	v_mfma_f32_16x16x32_bf16 v[110:113], v[130:133], v[192:195], v[110:113]
	v_mfma_f32_16x16x32_bf16 v[106:109], v[142:145], v[192:195], v[106:109]
	v_mfma_f32_16x16x32_bf16 v[94:97], v[130:133], v[202:205], v[94:97]
	v_mfma_f32_16x16x32_bf16 v[90:93], v[142:145], v[202:205], v[90:93]
	v_mfma_f32_16x16x32_bf16 v[78:81], v[130:133], v[210:213], v[78:81]
	v_mfma_f32_16x16x32_bf16 v[74:77], v[142:145], v[210:213], v[74:77]
	s_setprio 0
	s_setprio 1
	v_mfma_f32_16x16x32_bf16 v[118:121], v[156:159], v[172:175], v[118:121]
	v_mfma_f32_16x16x32_bf16 v[114:117], v[164:167], v[172:175], v[114:117]
	v_mfma_f32_16x16x32_bf16 v[102:105], v[156:159], v[188:191], v[102:105]
	v_mfma_f32_16x16x32_bf16 v[98:101], v[164:167], v[188:191], v[98:101]
	v_mfma_f32_16x16x32_bf16 v[86:89], v[156:159], v[198:201], v[86:89]
	v_mfma_f32_16x16x32_bf16 v[82:85], v[164:167], v[198:201], v[82:85]
	v_mfma_f32_16x16x32_bf16 v[70:73], v[156:159], v[206:209], v[70:73]
	v_mfma_f32_16x16x32_bf16 v[66:69], v[164:167], v[206:209], v[66:69]
	v_mfma_f32_16x16x32_bf16 v[118:121], v[160:163], v[184:187], v[118:121]
	v_mfma_f32_16x16x32_bf16 v[114:117], v[168:171], v[184:187], v[114:117]
	v_mfma_f32_16x16x32_bf16 v[102:105], v[160:163], v[192:195], v[102:105]
	v_mfma_f32_16x16x32_bf16 v[98:101], v[168:171], v[192:195], v[98:101]
	v_mfma_f32_16x16x32_bf16 v[86:89], v[160:163], v[202:205], v[86:89]
	v_mfma_f32_16x16x32_bf16 v[82:85], v[168:171], v[202:205], v[82:85]
	v_mfma_f32_16x16x32_bf16 v[70:73], v[160:163], v[210:213], v[70:73]
	v_mfma_f32_16x16x32_bf16 v[66:69], v[168:171], v[210:213], v[66:69]
	s_setprio 0
	s_barrier
; #define PG8_STAGE(bufoff, gbase, voff) do { _Pragma("unroll") for (int _i = 0; _i < 2; ++_i) \
;         __builtin_amdgcn_global_load_lds((const unsigned*)((const char*)(gbase) + (voff)[_i]), (PG8_LAS unsigned*)(lds + (bufoff) + ldsw + _i * 8192), 16, 0, 0); } while (0)
; #define PG8_LDA(dst, b, h) do { _Pragma("unroll") for (int m = 0; m < 4; ++m) _Pragma("unroll") for (int k = 0; k < 2; ++k) dst[m][k] = *(const PG8_LAS bf16x8*)(lds + PG8_SA(b, h) + aoff + m * 2048 + k * 1024); } while (0)
; #define PG8_MMA(ai, bj, At, Bt) do { __builtin_amdgcn_s_setprio(1); _Pragma("unroll") for (int m = 0; m < 4; ++m) _Pragma("unroll") for (int n = 0; n < 2; ++n) _Pragma("unroll") for (int k = 0; k < 2; ++k) \
;         acc[ai][bj][m][n] = __builtin_amdgcn_mfma_f32_16x16x32_bf16(Bt[n][k], At[m][k], acc[ai][bj][m][n], 0, 0, 0); __builtin_amdgcn_s_setprio(0); } while (0)
; #define PG8_WAIT_V(n) asm volatile("s_waitcnt vmcnt(" #n ")" ::: "memory")
; #define PG8_WAIT_L(n) asm volatile("s_waitcnt lgkmcnt(" #n ")" ::: "memory")
; #define PG8_BAR __builtin_amdgcn_s_barrier()
; #define PG8_SCHED __builtin_amdgcn_sched_barrier(0)
; template <class Epi, class Sched, bool ALIGN_EPI = true, bool SP2 = true, bool GS = false>
; __device__ __forceinline__ void gemm_phase(PG8_LAS unsigned char* lds, const Gemm g, const Sched& S, const Epi& E, const float* gs_ss = nullptr) {
;     ...
;         for (int t = 0; t < nt; t += 2) {
;     ...
;             PG8_WAIT_V(8); PG8_WAIT_L(0); PG8_BAR; PG8_MMA(0, 0, At, B0); PG8_MMA(0, 1, At, B1); PG8_BAR; PG8_SCHED;
;             PG8_LDA(At, 1, 1); PG8_STAGE(PG8_SB(1, 0), b3, voffB); PG8_STAGE(PG8_SB(1, 1), b3 + hstep, voffB); PG8_STAGE(PG8_SA(1, 0), a3, voffA);
;             PG8_WAIT_V(8); PG8_WAIT_L(0); PG8_BAR; PG8_MMA(1, 0, At, B0); PG8_MMA(1, 1, At, B1); PG8_BAR; PG8_SCHED;
	s_add_i32 s20, s65, s24
	v_lshl_add_u64 v[176:177], v[176:177], 0, s[26:27]
	s_mov_b32 m0, s20
	ds_read_b128 v[172:175], v197 offset:49152
	ds_read_b128 v[184:187], v197 offset:50176
	ds_read_b128 v[188:191], v197 offset:51200
	ds_read_b128 v[192:195], v197 offset:52224
	ds_read_b128 v[198:201], v197 offset:53248
	ds_read_b128 v[202:205], v197 offset:54272
	ds_read_b128 v[206:209], v197 offset:55296
	ds_read_b128 v[210:213], v197 offset:56320
	global_load_lds_dwordx4 v[176:177], off
	s_add_i32 m0, s20, 0x2000
	s_add_u32 s2, s2, 0x20080
	v_lshl_add_u64 v[176:177], v[180:181], 0, s[26:27]
	s_addc_u32 s3, s3, 0
	s_add_i32 s20, s67, s24
	global_load_lds_dwordx4 v[176:177], off
	v_lshl_add_u64 v[176:177], s[2:3], 0, v[0:1]
	s_mov_b32 m0, s20
	s_nop 0
	global_load_lds_dwordx4 v[176:177], off
	v_lshl_add_u64 v[176:177], s[2:3], 0, v[150:151]
	s_add_i32 m0, s20, 0x2000
	s_nop 0
	global_load_lds_dwordx4 v[176:177], off
	v_lshl_add_u64 v[176:177], v[214:215], 0, s[26:27]
	s_mov_b32 m0, s37
	s_nop 0
	global_load_lds_dwordx4 v[176:177], off
	v_lshl_add_u64 v[176:177], v[216:217], 0, s[26:27]
	s_mov_b32 m0, s60
	s_nop 0
	global_load_lds_dwordx4 v[176:177], off
	s_waitcnt vmcnt(8)
	s_waitcnt lgkmcnt(0)
	s_barrier
	s_setprio 1
	s_waitcnt lgkmcnt(0)
	v_mfma_f32_16x16x32_bf16 v[62:65], v[122:125], v[172:175], v[62:65]
	v_mfma_f32_16x16x32_bf16 v[58:61], v[138:141], v[172:175], v[58:61]
	v_mfma_f32_16x16x32_bf16 v[46:49], v[122:125], v[188:191], v[46:49]
	v_mfma_f32_16x16x32_bf16 v[42:45], v[138:141], v[188:191], v[42:45]
	v_mfma_f32_16x16x32_bf16 v[30:33], v[122:125], v[198:201], v[30:33]
	v_mfma_f32_16x16x32_bf16 v[26:29], v[138:141], v[198:201], v[26:29]
	v_mfma_f32_16x16x32_bf16 v[14:17], v[122:125], v[206:209], v[14:17]
	v_mfma_f32_16x16x32_bf16 v[10:13], v[138:141], v[206:209], v[10:13]
	v_mfma_f32_16x16x32_bf16 v[62:65], v[130:133], v[184:187], v[62:65]
	v_mfma_f32_16x16x32_bf16 v[58:61], v[142:145], v[184:187], v[58:61]
	v_mfma_f32_16x16x32_bf16 v[46:49], v[130:133], v[192:195], v[46:49]
	v_mfma_f32_16x16x32_bf16 v[42:45], v[142:145], v[192:195], v[42:45]
	v_mfma_f32_16x16x32_bf16 v[30:33], v[130:133], v[202:205], v[30:33]
	v_mfma_f32_16x16x32_bf16 v[26:29], v[142:145], v[202:205], v[26:29]
	v_mfma_f32_16x16x32_bf16 v[14:17], v[130:133], v[210:213], v[14:17]
	v_mfma_f32_16x16x32_bf16 v[10:13], v[142:145], v[210:213], v[10:13]
	s_setprio 0
	s_setprio 1
	v_mfma_f32_16x16x32_bf16 v[54:57], v[156:159], v[172:175], v[54:57]
	v_mfma_f32_16x16x32_bf16 v[50:53], v[164:167], v[172:175], v[50:53]
	v_mfma_f32_16x16x32_bf16 v[38:41], v[156:159], v[188:191], v[38:41]
	v_mfma_f32_16x16x32_bf16 v[34:37], v[164:167], v[188:191], v[34:37]
	v_mfma_f32_16x16x32_bf16 v[22:25], v[156:159], v[198:201], v[22:25]
	v_mfma_f32_16x16x32_bf16 v[18:21], v[164:167], v[198:201], v[18:21]
	v_mfma_f32_16x16x32_bf16 v[6:9], v[156:159], v[206:209], v[6:9]
	v_mfma_f32_16x16x32_bf16 v[2:5], v[164:167], v[206:209], v[2:5]
	v_mfma_f32_16x16x32_bf16 v[54:57], v[160:163], v[184:187], v[54:57]
	v_mfma_f32_16x16x32_bf16 v[50:53], v[168:171], v[184:187], v[50:53]
	v_mfma_f32_16x16x32_bf16 v[38:41], v[160:163], v[192:195], v[38:41]
	v_mfma_f32_16x16x32_bf16 v[34:37], v[168:171], v[192:195], v[34:37]
	v_mfma_f32_16x16x32_bf16 v[22:25], v[160:163], v[202:205], v[22:25]
	v_mfma_f32_16x16x32_bf16 v[18:21], v[168:171], v[202:205], v[18:21]
	v_mfma_f32_16x16x32_bf16 v[6:9], v[160:163], v[210:213], v[6:9]
	v_mfma_f32_16x16x32_bf16 v[2:5], v[168:171], v[210:213], v[2:5]
	s_setprio 0
	s_add_i32 s64, s64, 2
	s_add_u32 s56, s56, 0x100
	s_addc_u32 s57, s57, 0
	s_add_u32 s58, s58, 0x100
	s_addc_u32 s59, s59, 0
	s_cmp_gt_u32 s64, 5
	s_barrier
	s_cbranch_scc0 .LBB0_1252
	s_and_b64 vcc, exec, s[46:47]
	s_cbranch_vccz .LBB0_1255
	s_barrier

; #define PG8_STAGE(bufoff, gbase, voff) do { _Pragma("unroll") for (int _i = 0; _i < 2; ++_i) \
;         __builtin_amdgcn_global_load_lds((const unsigned*)((const char*)(gbase) + (voff)[_i]), (PG8_LAS unsigned*)(lds + (bufoff) + ldsw + _i * 8192), 16, 0, 0); } while (0)
; #define PG8_LDA(dst, b, h) do { _Pragma("unroll") for (int m = 0; m < 4; ++m) _Pragma("unroll") for (int k = 0; k < 2; ++k) dst[m][k] = *(const PG8_LAS bf16x8*)(lds + PG8_SA(b, h) + aoff + m * 2048 + k * 1024); } while (0)
; #define PG8_LDB(dst, b, h) do { _Pragma("unroll") for (int n = 0; n < 2; ++n) _Pragma("unroll") for (int k = 0; k < 2; ++k) dst[n][k] = *(const PG8_LAS bf16x8*)(lds + PG8_SB(b, h) + boff + n * 2048 + k * 1024); } while (0)
; #define PG8_MMA(ai, bj, At, Bt) do { __builtin_amdgcn_s_setprio(1); _Pragma("unroll") for (int m = 0; m < 4; ++m) _Pragma("unroll") for (int n = 0; n < 2; ++n) _Pragma("unroll") for (int k = 0; k < 2; ++k) \
;         acc[ai][bj][m][n] = __builtin_amdgcn_mfma_f32_16x16x32_bf16(Bt[n][k], At[m][k], acc[ai][bj][m][n], 0, 0, 0); __builtin_amdgcn_s_setprio(0); } while (0)
; #define PG8_WAIT_V(n) asm volatile("s_waitcnt vmcnt(" #n ")" ::: "memory")
; #define PG8_WAIT_L(n) asm volatile("s_waitcnt lgkmcnt(" #n ")" ::: "memory")
; #define PG8_BAR __builtin_amdgcn_s_barrier()
; #define PG8_SCHED __builtin_amdgcn_sched_barrier(0)
; template <class Epi, class Sched, bool ALIGN_EPI = true, bool SP2 = true, bool GS = false>
; __device__ __forceinline__ void gemm_phase(PG8_LAS unsigned char* lds, const Gemm g, const Sched& S, const Epi& E, const float* gs_ss = nullptr) {
;     ...
;         for (int t = 0; t < nt; t += 2) {
;             const bool last = (t == nt - 2);
;             const char* a1 = cA + (size_t)(t + 1) * kstep;
;             const char* a2 = last ? nA : cA + (size_t)(t + 2) * kstep; const char* b2 = last ? nB : cB + (size_t)(t + 2) * kstep;
;             const char* a3 = a2 + kstep; const char* b3 = b2 + kstep;
;             if constexpr (SP2) {
;             PG8_LDB(B0, 0, 0); PG8_LDB(B1, 0, 1); PG8_SCHED; PG8_LDA(At, 0, 0); PG8_STAGE(PG8_SA(1, 1), a1 + hstep, voffA);
;             PG8_WAIT_V(8); PG8_WAIT_L(0); PG8_BAR; PG8_MMA(0, 0, At, B0); PG8_MMA(0, 1, At, B1); PG8_BAR; PG8_SCHED;
;             PG8_LDA(At, 0, 1); PG8_STAGE(PG8_SB(0, 0), b2, voffB); PG8_STAGE(PG8_SB(0, 1), b2 + hstep, voffB); PG8_STAGE(PG8_SA(0, 0), a2, voffA);
.LBB0_1344:
	s_add_i32 s60, 0, 0x10000
	v_add_u32_e32 v140, s60, v143
	s_add_i32 s62, 0, 0x14000
	ds_read_b128 v[146:149], v140
	ds_read_b128 v[150:153], v140 offset:1024
	ds_read_b128 v[154:157], v140 offset:2048
	ds_read_b128 v[158:161], v140 offset:3072
	v_add_u32_e32 v140, s62, v143
	ds_read_b128 v[162:165], v140
	ds_read_b128 v[166:169], v140 offset:1024
	ds_read_b128 v[170:173], v140 offset:2048
	ds_read_b128 v[174:177], v140 offset:3072
	v_lshl_add_u64 v[140:141], s[50:51], 0, v[136:137]
	s_add_i32 m0, s30, 0xc000
	ds_read_b128 v[180:183], v145
	ds_read_b128 v[184:187], v145 offset:1024
	ds_read_b128 v[188:191], v145 offset:2048
	ds_read_b128 v[192:195], v145 offset:3072
	ds_read_b128 v[196:199], v145 offset:4096
	ds_read_b128 v[200:203], v145 offset:5120
	ds_read_b128 v[204:207], v145 offset:6144
	ds_read_b128 v[208:211], v145 offset:7168
	global_load_lds_dwordx4 v[140:141], off
	v_lshl_add_u64 v[140:141], s[50:51], 0, v[138:139]
	s_add_i32 m0, s30, 0xe000
	s_nop 0
	global_load_lds_dwordx4 v[140:141], off
	s_add_u32 s2, s50, 0xfff80080
	s_addc_u32 s3, s51, -1
	s_cmp_eq_u32 s59, 28
	s_cselect_b32 s21, s43, s3
	s_cselect_b32 s20, s57, s2
	s_cselect_b32 s3, s41, s53
	s_cselect_b32 s2, s58, s52
	s_waitcnt vmcnt(8)
	s_waitcnt lgkmcnt(0)
	s_barrier
	s_setprio 1
	s_waitcnt lgkmcnt(0)
	v_mfma_f32_16x16x32_bf16 v[126:129], v[146:149], v[180:183], v[126:129]
	v_mfma_f32_16x16x32_bf16 v[122:125], v[154:157], v[180:183], v[122:125]
	v_mfma_f32_16x16x32_bf16 v[110:113], v[146:149], v[188:191], v[110:113]
	v_mfma_f32_16x16x32_bf16 v[106:109], v[154:157], v[188:191], v[106:109]
	v_mfma_f32_16x16x32_bf16 v[94:97], v[146:149], v[196:199], v[94:97]
	v_mfma_f32_16x16x32_bf16 v[90:93], v[154:157], v[196:199], v[90:93]
	v_mfma_f32_16x16x32_bf16 v[78:81], v[146:149], v[204:207], v[78:81]
	v_mfma_f32_16x16x32_bf16 v[74:77], v[154:157], v[204:207], v[74:77]
	v_mfma_f32_16x16x32_bf16 v[126:129], v[150:153], v[184:187], v[126:129]
	v_mfma_f32_16x16x32_bf16 v[122:125], v[158:161], v[184:187], v[122:125]
	v_mfma_f32_16x16x32_bf16 v[110:113], v[150:153], v[192:195], v[110:113]
	v_mfma_f32_16x16x32_bf16 v[106:109], v[158:161], v[192:195], v[106:109]
	v_mfma_f32_16x16x32_bf16 v[94:97], v[150:153], v[200:203], v[94:97]
	v_mfma_f32_16x16x32_bf16 v[90:93], v[158:161], v[200:203], v[90:93]
	v_mfma_f32_16x16x32_bf16 v[78:81], v[150:153], v[208:211], v[78:81]
	v_mfma_f32_16x16x32_bf16 v[74:77], v[158:161], v[208:211], v[74:77]
	s_setprio 0
	s_setprio 1
	v_mfma_f32_16x16x32_bf16 v[118:121], v[162:165], v[180:183], v[118:121]
	v_mfma_f32_16x16x32_bf16 v[114:117], v[170:173], v[180:183], v[114:117]
	v_mfma_f32_16x16x32_bf16 v[102:105], v[162:165], v[188:191], v[102:105]
	v_mfma_f32_16x16x32_bf16 v[98:101], v[170:173], v[188:191], v[98:101]
	v_mfma_f32_16x16x32_bf16 v[86:89], v[162:165], v[196:199], v[86:89]
	v_mfma_f32_16x16x32_bf16 v[82:85], v[170:173], v[196:199], v[82:85]
	v_mfma_f32_16x16x32_bf16 v[70:73], v[162:165], v[204:207], v[70:73]
	v_mfma_f32_16x16x32_bf16 v[66:69], v[170:173], v[204:207], v[66:69]
	v_mfma_f32_16x16x32_bf16 v[118:121], v[166:169], v[184:187], v[118:121]
	v_mfma_f32_16x16x32_bf16 v[114:117], v[174:177], v[184:187], v[114:117]
	v_mfma_f32_16x16x32_bf16 v[102:105], v[166:169], v[192:195], v[102:105]
	v_mfma_f32_16x16x32_bf16 v[98:101], v[174:177], v[192:195], v[98:101]
	v_mfma_f32_16x16x32_bf16 v[86:89], v[166:169], v[200:203], v[86:89]
	v_mfma_f32_16x16x32_bf16 v[82:85], v[174:177], v[200:203], v[82:85]
	v_mfma_f32_16x16x32_bf16 v[70:73], v[166:169], v[208:211], v[70:73]
	v_mfma_f32_16x16x32_bf16 v[66:69], v[174:177], v[208:211], v[66:69]
	s_setprio 0
	s_barrier
	s_add_i32 s60, s60, s25
	v_lshl_add_u64 v[140:141], s[2:3], 0, v[0:1]
	s_mov_b32 m0, s60
	ds_read_b128 v[180:183], v145 offset:16384
	ds_read_b128 v[184:187], v145 offset:17408
	ds_read_b128 v[188:191], v145 offset:18432
	ds_read_b128 v[192:195], v145 offset:19456
	ds_read_b128 v[196:199], v145 offset:20480
	ds_read_b128 v[200:203], v145 offset:21504
	ds_read_b128 v[204:207], v145 offset:22528
	ds_read_b128 v[208:211], v145 offset:23552
	global_load_lds_dwordx4 v[140:141], off
	s_add_i32 m0, s60, 0x2000
	s_add_u32 s60, s2, 0x80000
	v_lshl_add_u64 v[212:213], s[2:3], 0, v[134:135]
	s_addc_u32 s61, s3, 0
	s_add_i32 s62, s62, s25
	global_load_lds_dwordx4 v[212:213], off
	v_lshl_add_u64 v[214:215], s[60:61], 0, v[0:1]
	s_mov_b32 m0, s62
	v_lshl_add_u64 v[216:217], s[20:21], 0, v[132:133]
	global_load_lds_dwordx4 v[214:215], off
	v_lshl_add_u64 v[214:215], s[60:61], 0, v[134:135]
	s_add_i32 m0, s62, 0x2000
	s_nop 0
	global_load_lds_dwordx4 v[214:215], off
	v_lshl_add_u64 v[214:215], s[20:21], 0, v[130:131]
	s_mov_b32 m0, s30
	s_nop 0
	global_load_lds_dwordx4 v[214:215], off
	s_mov_b32 m0, s36
	s_nop 0
	global_load_lds_dwordx4 v[216:217], off
	s_waitcnt vmcnt(8)
	s_waitcnt lgkmcnt(0)
	s_barrier
; #define PG8_STAGE(bufoff, gbase, voff) do { _Pragma("unroll") for (int _i = 0; _i < 2; ++_i) \
;         __builtin_amdgcn_global_load_lds((const unsigned*)((const char*)(gbase) + (voff)[_i]), (PG8_LAS unsigned*)(lds + (bufoff) + ldsw + _i * 8192), 16, 0, 0); } while (0)
; #define PG8_LDA(dst, b, h) do { _Pragma("unroll") for (int m = 0; m < 4; ++m) _Pragma("unroll") for (int k = 0; k < 2; ++k) dst[m][k] = *(const PG8_LAS bf16x8*)(lds + PG8_SA(b, h) + aoff + m * 2048 + k * 1024); } while (0)
; #define PG8_LDB(dst, b, h) do { _Pragma("unroll") for (int n = 0; n < 2; ++n) _Pragma("unroll") for (int k = 0; k < 2; ++k) dst[n][k] = *(const PG8_LAS bf16x8*)(lds + PG8_SB(b, h) + boff + n * 2048 + k * 1024); } while (0)
; #define PG8_MMA(ai, bj, At, Bt) do { __builtin_amdgcn_s_setprio(1); _Pragma("unroll") for (int m = 0; m < 4; ++m) _Pragma("unroll") for (int n = 0; n < 2; ++n) _Pragma("unroll") for (int k = 0; k < 2; ++k) \
;         acc[ai][bj][m][n] = __builtin_amdgcn_mfma_f32_16x16x32_bf16(Bt[n][k], At[m][k], acc[ai][bj][m][n], 0, 0, 0); __builtin_amdgcn_s_setprio(0); } while (0)
; #define PG8_WAIT_V(n) asm volatile("s_waitcnt vmcnt(" #n ")" ::: "memory")
; #define PG8_WAIT_L(n) asm volatile("s_waitcnt lgkmcnt(" #n ")" ::: "memory")
; #define PG8_BAR __builtin_amdgcn_s_barrier()
; #define PG8_SCHED __builtin_amdgcn_sched_barrier(0)
; template <class Epi, class Sched, bool ALIGN_EPI = true, bool SP2 = true, bool GS = false>
; __device__ __forceinline__ void gemm_phase(PG8_LAS unsigned char* lds, const Gemm g, const Sched& S, const Epi& E, const float* gs_ss = nullptr) {
;     ...
;             PG8_LDA(At, 0, 1); PG8_STAGE(PG8_SB(0, 0), b2, voffB); PG8_STAGE(PG8_SB(0, 1), b2 + hstep, voffB); PG8_STAGE(PG8_SA(0, 0), a2, voffA);
;             PG8_WAIT_V(8); PG8_WAIT_L(0); PG8_BAR; PG8_MMA(1, 0, At, B0); PG8_MMA(1, 1, At, B1); PG8_BAR; PG8_SCHED;
;             PG8_LDB(B0, 1, 0); PG8_LDB(B1, 1, 1); PG8_SCHED; PG8_LDA(At, 1, 0); PG8_STAGE(PG8_SA(0, 1), a2 + hstep, voffA);
;             PG8_WAIT_V(8); PG8_WAIT_L(0); PG8_BAR; PG8_MMA(0, 0, At, B0); PG8_MMA(0, 1, At, B1); PG8_BAR; PG8_SCHED;
	s_setprio 1
	s_waitcnt lgkmcnt(0)
	v_mfma_f32_16x16x32_bf16 v[62:65], v[146:149], v[180:183], v[62:65]
	v_mfma_f32_16x16x32_bf16 v[58:61], v[154:157], v[180:183], v[58:61]
	v_mfma_f32_16x16x32_bf16 v[46:49], v[146:149], v[188:191], v[46:49]
	v_mfma_f32_16x16x32_bf16 v[42:45], v[154:157], v[188:191], v[42:45]
	v_mfma_f32_16x16x32_bf16 v[30:33], v[146:149], v[196:199], v[30:33]
	v_mfma_f32_16x16x32_bf16 v[26:29], v[154:157], v[196:199], v[26:29]
	v_mfma_f32_16x16x32_bf16 v[14:17], v[146:149], v[204:207], v[14:17]
	v_mfma_f32_16x16x32_bf16 v[10:13], v[154:157], v[204:207], v[10:13]
	v_mfma_f32_16x16x32_bf16 v[62:65], v[150:153], v[184:187], v[62:65]
	v_mfma_f32_16x16x32_bf16 v[58:61], v[158:161], v[184:187], v[58:61]
	v_mfma_f32_16x16x32_bf16 v[46:49], v[150:153], v[192:195], v[46:49]
	v_mfma_f32_16x16x32_bf16 v[42:45], v[158:161], v[192:195], v[42:45]
	v_mfma_f32_16x16x32_bf16 v[30:33], v[150:153], v[200:203], v[30:33]
	v_mfma_f32_16x16x32_bf16 v[26:29], v[158:161], v[200:203], v[26:29]
	v_mfma_f32_16x16x32_bf16 v[14:17], v[150:153], v[208:211], v[14:17]
	v_mfma_f32_16x16x32_bf16 v[10:13], v[158:161], v[208:211], v[10:13]
	s_setprio 0
	s_setprio 1
	v_mfma_f32_16x16x32_bf16 v[54:57], v[162:165], v[180:183], v[54:57]
	v_mfma_f32_16x16x32_bf16 v[50:53], v[170:173], v[180:183], v[50:53]
	v_mfma_f32_16x16x32_bf16 v[38:41], v[162:165], v[188:191], v[38:41]
	v_mfma_f32_16x16x32_bf16 v[34:37], v[170:173], v[188:191], v[34:37]
	v_mfma_f32_16x16x32_bf16 v[22:25], v[162:165], v[196:199], v[22:25]
	v_mfma_f32_16x16x32_bf16 v[18:21], v[170:173], v[196:199], v[18:21]
	v_mfma_f32_16x16x32_bf16 v[6:9], v[162:165], v[204:207], v[6:9]
	v_mfma_f32_16x16x32_bf16 v[2:5], v[170:173], v[204:207], v[2:5]
	v_mfma_f32_16x16x32_bf16 v[54:57], v[166:169], v[184:187], v[54:57]
	v_mfma_f32_16x16x32_bf16 v[50:53], v[174:177], v[184:187], v[50:53]
	v_mfma_f32_16x16x32_bf16 v[38:41], v[166:169], v[192:195], v[38:41]
	v_mfma_f32_16x16x32_bf16 v[34:37], v[174:177], v[192:195], v[34:37]
	v_mfma_f32_16x16x32_bf16 v[22:25], v[166:169], v[200:203], v[22:25]
	v_mfma_f32_16x16x32_bf16 v[18:21], v[174:177], v[200:203], v[18:21]
	v_mfma_f32_16x16x32_bf16 v[6:9], v[166:169], v[208:211], v[6:9]
	v_mfma_f32_16x16x32_bf16 v[2:5], v[174:177], v[208:211], v[2:5]
	s_setprio 0
	s_barrier
	s_add_i32 s60, 0, 0x18000
	s_add_i32 s61, 0, 0x1c000
	v_add_u32_e32 v158, s60, v143
	v_add_u32_e32 v174, s61, v143
	ds_read_b128 v[146:149], v158
	ds_read_b128 v[150:153], v158 offset:1024
	ds_read_b128 v[154:157], v158 offset:2048
	ds_read_b128 v[158:161], v158 offset:3072
	ds_read_b128 v[162:165], v174
	ds_read_b128 v[166:169], v174 offset:1024
	ds_read_b128 v[170:173], v174 offset:2048
	ds_read_b128 v[174:177], v174 offset:3072
	s_add_u32 s20, s20, 0x80000
	s_addc_u32 s21, s21, 0
	s_mov_b32 m0, s37
	v_lshl_add_u64 v[218:219], s[20:21], 0, v[130:131]
	ds_read_b128 v[180:183], v145 offset:32768
	ds_read_b128 v[184:187], v145 offset:33792
	ds_read_b128 v[188:191], v145 offset:34816
	ds_read_b128 v[192:195], v145 offset:35840
	ds_read_b128 v[196:199], v145 offset:36864
	ds_read_b128 v[200:203], v145 offset:37888
	ds_read_b128 v[204:207], v145 offset:38912
	ds_read_b128 v[208:211], v145 offset:39936
	global_load_lds_dwordx4 v[218:219], off
	v_lshl_add_u64 v[218:219], s[20:21], 0, v[132:133]
	s_mov_b32 m0, s49
	s_nop 0
	global_load_lds_dwordx4 v[218:219], off
	s_waitcnt vmcnt(8)
	s_waitcnt lgkmcnt(0)
	s_barrier
	s_setprio 1
	s_waitcnt lgkmcnt(0)
	v_mfma_f32_16x16x32_bf16 v[126:129], v[146:149], v[180:183], v[126:129]
	v_mfma_f32_16x16x32_bf16 v[122:125], v[154:157], v[180:183], v[122:125]
	v_mfma_f32_16x16x32_bf16 v[110:113], v[146:149], v[188:191], v[110:113]
	v_mfma_f32_16x16x32_bf16 v[106:109], v[154:157], v[188:191], v[106:109]
	v_mfma_f32_16x16x32_bf16 v[94:97], v[146:149], v[196:199], v[94:97]
	v_mfma_f32_16x16x32_bf16 v[90:93], v[154:157], v[196:199], v[90:93]
	v_mfma_f32_16x16x32_bf16 v[78:81], v[146:149], v[204:207], v[78:81]
	v_mfma_f32_16x16x32_bf16 v[74:77], v[154:157], v[204:207], v[74:77]
	v_mfma_f32_16x16x32_bf16 v[126:129], v[150:153], v[184:187], v[126:129]
	v_mfma_f32_16x16x32_bf16 v[122:125], v[158:161], v[184:187], v[122:125]
	v_mfma_f32_16x16x32_bf16 v[110:113], v[150:153], v[192:195], v[110:113]
	v_mfma_f32_16x16x32_bf16 v[106:109], v[158:161], v[192:195], v[106:109]
	v_mfma_f32_16x16x32_bf16 v[94:97], v[150:153], v[200:203], v[94:97]
	v_mfma_f32_16x16x32_bf16 v[90:93], v[158:161], v[200:203], v[90:93]
	v_mfma_f32_16x16x32_bf16 v[78:81], v[150:153], v[208:211], v[78:81]
	v_mfma_f32_16x16x32_bf16 v[74:77], v[158:161], v[208:211], v[74:77]
	s_setprio 0
	s_setprio 1
	v_mfma_f32_16x16x32_bf16 v[118:121], v[162:165], v[180:183], v[118:121]
	v_mfma_f32_16x16x32_bf16 v[114:117], v[170:173], v[180:183], v[114:117]
	v_mfma_f32_16x16x32_bf16 v[102:105], v[162:165], v[188:191], v[102:105]
	v_mfma_f32_16x16x32_bf16 v[98:101], v[170:173], v[188:191], v[98:101]
	v_mfma_f32_16x16x32_bf16 v[86:89], v[162:165], v[196:199], v[86:89]
	v_mfma_f32_16x16x32_bf16 v[82:85], v[170:173], v[196:199], v[82:85]
	v_mfma_f32_16x16x32_bf16 v[70:73], v[162:165], v[204:207], v[70:73]
	v_mfma_f32_16x16x32_bf16 v[66:69], v[170:173], v[204:207], v[66:69]
	v_mfma_f32_16x16x32_bf16 v[118:121], v[166:169], v[184:187], v[118:121]
	v_mfma_f32_16x16x32_bf16 v[114:117], v[174:177], v[184:187], v[114:117]
	v_mfma_f32_16x16x32_bf16 v[102:105], v[166:169], v[192:195], v[102:105]
	v_mfma_f32_16x16x32_bf16 v[98:101], v[174:177], v[192:195], v[98:101]
	v_mfma_f32_16x16x32_bf16 v[86:89], v[166:169], v[200:203], v[86:89]
	v_mfma_f32_16x16x32_bf16 v[82:85], v[174:177], v[200:203], v[82:85]
	v_mfma_f32_16x16x32_bf16 v[70:73], v[166:169], v[208:211], v[70:73]
	v_mfma_f32_16x16x32_bf16 v[66:69], v[174:177], v[208:211], v[66:69]
	s_setprio 0
	s_barrier
; #define PG8_STAGE(bufoff, gbase, voff) do { _Pragma("unroll") for (int _i = 0; _i < 2; ++_i) \
;         __builtin_amdgcn_global_load_lds((const unsigned*)((const char*)(gbase) + (voff)[_i]), (PG8_LAS unsigned*)(lds + (bufoff) + ldsw + _i * 8192), 16, 0, 0); } while (0)
; #define PG8_LDA(dst, b, h) do { _Pragma("unroll") for (int m = 0; m < 4; ++m) _Pragma("unroll") for (int k = 0; k < 2; ++k) dst[m][k] = *(const PG8_LAS bf16x8*)(lds + PG8_SA(b, h) + aoff + m * 2048 + k * 1024); } while (0)
; #define PG8_MMA(ai, bj, At, Bt) do { __builtin_amdgcn_s_setprio(1); _Pragma("unroll") for (int m = 0; m < 4; ++m) _Pragma("unroll") for (int n = 0; n < 2; ++n) _Pragma("unroll") for (int k = 0; k < 2; ++k) \
;         acc[ai][bj][m][n] = __builtin_amdgcn_mfma_f32_16x16x32_bf16(Bt[n][k], At[m][k], acc[ai][bj][m][n], 0, 0, 0); __builtin_amdgcn_s_setprio(0); } while (0)
; #define PG8_WAIT_V(n) asm volatile("s_waitcnt vmcnt(" #n ")" ::: "memory")
; #define PG8_WAIT_L(n) asm volatile("s_waitcnt lgkmcnt(" #n ")" ::: "memory")
; #define PG8_BAR __builtin_amdgcn_s_barrier()
; #define PG8_SCHED __builtin_amdgcn_sched_barrier(0)
; template <class Epi, class Sched, bool ALIGN_EPI = true, bool SP2 = true, bool GS = false>
; __device__ __forceinline__ void gemm_phase(PG8_LAS unsigned char* lds, const Gemm g, const Sched& S, const Epi& E, const float* gs_ss = nullptr) {
;     ...
;         for (int t = 0; t < nt; t += 2) {
;     ...
;             PG8_WAIT_V(8); PG8_WAIT_L(0); PG8_BAR; PG8_MMA(0, 0, At, B0); PG8_MMA(0, 1, At, B1); PG8_BAR; PG8_SCHED;
;             PG8_LDA(At, 1, 1); PG8_STAGE(PG8_SB(1, 0), b3, voffB); PG8_STAGE(PG8_SB(1, 1), b3 + hstep, voffB); PG8_STAGE(PG8_SA(1, 0), a3, voffA);
;             PG8_WAIT_V(8); PG8_WAIT_L(0); PG8_BAR; PG8_MMA(1, 0, At, B0); PG8_MMA(1, 1, At, B1); PG8_BAR; PG8_SCHED;
	s_add_i32 s20, s60, s25
	v_lshl_add_u64 v[140:141], v[140:141], 0, s[26:27]
	s_mov_b32 m0, s20
	ds_read_b128 v[180:183], v145 offset:49152
	ds_read_b128 v[184:187], v145 offset:50176
	ds_read_b128 v[188:191], v145 offset:51200
	ds_read_b128 v[192:195], v145 offset:52224
	ds_read_b128 v[196:199], v145 offset:53248
	ds_read_b128 v[200:203], v145 offset:54272
	ds_read_b128 v[204:207], v145 offset:55296
	ds_read_b128 v[208:211], v145 offset:56320
	global_load_lds_dwordx4 v[140:141], off
	s_add_i32 m0, s20, 0x2000
	s_add_u32 s2, s2, 0x80080
	v_lshl_add_u64 v[140:141], v[212:213], 0, s[26:27]
	s_addc_u32 s3, s3, 0
	s_add_i32 s20, s61, s25
	global_load_lds_dwordx4 v[140:141], off
	v_lshl_add_u64 v[140:141], s[2:3], 0, v[0:1]
	s_mov_b32 m0, s20
	s_nop 0
	global_load_lds_dwordx4 v[140:141], off
	v_lshl_add_u64 v[140:141], s[2:3], 0, v[134:135]
	s_add_i32 m0, s20, 0x2000
	s_nop 0
	global_load_lds_dwordx4 v[140:141], off
	v_lshl_add_u64 v[140:141], v[214:215], 0, s[26:27]
	s_mov_b32 m0, s18
	s_nop 0
	global_load_lds_dwordx4 v[140:141], off
	v_lshl_add_u64 v[140:141], v[216:217], 0, s[26:27]
	s_mov_b32 m0, s54
	s_nop 0
	global_load_lds_dwordx4 v[140:141], off
	s_waitcnt vmcnt(8)
	s_waitcnt lgkmcnt(0)
	s_barrier
	s_setprio 1
	s_waitcnt lgkmcnt(0)
	v_mfma_f32_16x16x32_bf16 v[62:65], v[146:149], v[180:183], v[62:65]
	v_mfma_f32_16x16x32_bf16 v[58:61], v[154:157], v[180:183], v[58:61]
	v_mfma_f32_16x16x32_bf16 v[46:49], v[146:149], v[188:191], v[46:49]
	v_mfma_f32_16x16x32_bf16 v[42:45], v[154:157], v[188:191], v[42:45]
	v_mfma_f32_16x16x32_bf16 v[30:33], v[146:149], v[196:199], v[30:33]
	v_mfma_f32_16x16x32_bf16 v[26:29], v[154:157], v[196:199], v[26:29]
	v_mfma_f32_16x16x32_bf16 v[14:17], v[146:149], v[204:207], v[14:17]
	v_mfma_f32_16x16x32_bf16 v[10:13], v[154:157], v[204:207], v[10:13]
	v_mfma_f32_16x16x32_bf16 v[62:65], v[150:153], v[184:187], v[62:65]
	v_mfma_f32_16x16x32_bf16 v[58:61], v[158:161], v[184:187], v[58:61]
	v_mfma_f32_16x16x32_bf16 v[46:49], v[150:153], v[192:195], v[46:49]
	v_mfma_f32_16x16x32_bf16 v[42:45], v[158:161], v[192:195], v[42:45]
	v_mfma_f32_16x16x32_bf16 v[30:33], v[150:153], v[200:203], v[30:33]
	v_mfma_f32_16x16x32_bf16 v[26:29], v[158:161], v[200:203], v[26:29]
	v_mfma_f32_16x16x32_bf16 v[14:17], v[150:153], v[208:211], v[14:17]
	v_mfma_f32_16x16x32_bf16 v[10:13], v[158:161], v[208:211], v[10:13]
	s_setprio 0
	s_setprio 1
	v_mfma_f32_16x16x32_bf16 v[54:57], v[162:165], v[180:183], v[54:57]
	v_mfma_f32_16x16x32_bf16 v[50:53], v[170:173], v[180:183], v[50:53]
	v_mfma_f32_16x16x32_bf16 v[38:41], v[162:165], v[188:191], v[38:41]
	v_mfma_f32_16x16x32_bf16 v[34:37], v[170:173], v[188:191], v[34:37]
	v_mfma_f32_16x16x32_bf16 v[22:25], v[162:165], v[196:199], v[22:25]
	v_mfma_f32_16x16x32_bf16 v[18:21], v[170:173], v[196:199], v[18:21]
	v_mfma_f32_16x16x32_bf16 v[6:9], v[162:165], v[204:207], v[6:9]
	v_mfma_f32_16x16x32_bf16 v[2:5], v[170:173], v[204:207], v[2:5]
	v_mfma_f32_16x16x32_bf16 v[54:57], v[166:169], v[184:187], v[54:57]
	v_mfma_f32_16x16x32_bf16 v[50:53], v[174:177], v[184:187], v[50:53]
	v_mfma_f32_16x16x32_bf16 v[38:41], v[166:169], v[192:195], v[38:41]
	v_mfma_f32_16x16x32_bf16 v[34:37], v[174:177], v[192:195], v[34:37]
	v_mfma_f32_16x16x32_bf16 v[22:25], v[166:169], v[200:203], v[22:25]
	v_mfma_f32_16x16x32_bf16 v[18:21], v[174:177], v[200:203], v[18:21]
	v_mfma_f32_16x16x32_bf16 v[6:9], v[166:169], v[208:211], v[6:9]
	v_mfma_f32_16x16x32_bf16 v[2:5], v[174:177], v[208:211], v[2:5]
	s_setprio 0
	s_add_i32 s59, s59, 2
	s_add_u32 s50, s50, 0x100
	s_addc_u32 s51, s51, 0
	s_add_u32 s52, s52, 0x100
	s_addc_u32 s53, s53, 0
	s_cmp_gt_u32 s59, 29
	s_barrier
	s_cbranch_scc0 .LBB0_1344
	s_and_b64 vcc, exec, s[34:35]
	s_cbranch_vccz .LBB0_1347
	s_barrier

; #define PG8_STAGE(bufoff, gbase, voff) do { _Pragma("unroll") for (int _i = 0; _i < 2; ++_i) \
;         __builtin_amdgcn_global_load_lds((const unsigned*)((const char*)(gbase) + (voff)[_i]), (PG8_LAS unsigned*)(lds + (bufoff) + ldsw + _i * 8192), 16, 0, 0); } while (0)
; #define PG8_LDA(dst, b, h) do { _Pragma("unroll") for (int m = 0; m < 4; ++m) _Pragma("unroll") for (int k = 0; k < 2; ++k) dst[m][k] = *(const PG8_LAS bf16x8*)(lds + PG8_SA(b, h) + aoff + m * 2048 + k * 1024); } while (0)
; #define PG8_LDB(dst, b, h) do { _Pragma("unroll") for (int n = 0; n < 2; ++n) _Pragma("unroll") for (int k = 0; k < 2; ++k) dst[n][k] = *(const PG8_LAS bf16x8*)(lds + PG8_SB(b, h) + boff + n * 2048 + k * 1024); } while (0)
; #define PG8_MMA(ai, bj, At, Bt) do { __builtin_amdgcn_s_setprio(1); _Pragma("unroll") for (int m = 0; m < 4; ++m) _Pragma("unroll") for (int n = 0; n < 2; ++n) _Pragma("unroll") for (int k = 0; k < 2; ++k) \
;         acc[ai][bj][m][n] = __builtin_amdgcn_mfma_f32_16x16x32_bf16(Bt[n][k], At[m][k], acc[ai][bj][m][n], 0, 0, 0); __builtin_amdgcn_s_setprio(0); } while (0)
; #define PG8_WAIT_V(n) asm volatile("s_waitcnt vmcnt(" #n ")" ::: "memory")
; #define PG8_WAIT_L(n) asm volatile("s_waitcnt lgkmcnt(" #n ")" ::: "memory")
; #define PG8_BAR __builtin_amdgcn_s_barrier()
; #define PG8_SCHED __builtin_amdgcn_sched_barrier(0)
; template <class Epi, class Sched, bool ALIGN_EPI = true, bool SP2 = true, bool GS = false>
; __device__ __forceinline__ void gemm_phase(PG8_LAS unsigned char* lds, const Gemm g, const Sched& S, const Epi& E, const float* gs_ss = nullptr) {
;     ...
;         for (int t = 0; t < nt; t += 2) {
;             const bool last = (t == nt - 2);
;             const char* a1 = cA + (size_t)(t + 1) * kstep;
;             const char* a2 = last ? nA : cA + (size_t)(t + 2) * kstep; const char* b2 = last ? nB : cB + (size_t)(t + 2) * kstep;
;             const char* a3 = a2 + kstep; const char* b3 = b2 + kstep;
;             if constexpr (SP2) {
;             PG8_LDB(B0, 0, 0); PG8_LDB(B1, 0, 1); PG8_SCHED; PG8_LDA(At, 0, 0); PG8_STAGE(PG8_SA(1, 1), a1 + hstep, voffA);
;             PG8_WAIT_V(8); PG8_WAIT_L(0); PG8_BAR; PG8_MMA(0, 0, At, B0); PG8_MMA(0, 1, At, B1); PG8_BAR; PG8_SCHED;
;             PG8_LDA(At, 0, 1); PG8_STAGE(PG8_SB(0, 0), b2, voffB); PG8_STAGE(PG8_SB(0, 1), b2 + hstep, voffB); PG8_STAGE(PG8_SA(0, 0), a2, voffA);
.LBB0_1422:
	s_add_i32 s65, 0, 0x10000
	s_add_i32 s67, 0, 0x14000
	v_add_u32_e32 v142, s65, v236
	v_add_u32_e32 v170, s67, v236
	ds_read_b128 v[130:133], v142
	ds_read_b128 v[134:137], v142 offset:1024
	ds_read_b128 v[138:141], v142 offset:2048
	ds_read_b128 v[142:145], v142 offset:3072
	ds_read_b128 v[158:161], v170
	ds_read_b128 v[162:165], v170 offset:1024
	ds_read_b128 v[166:169], v170 offset:2048
	ds_read_b128 v[170:173], v170 offset:3072
	v_lshl_add_u64 v[180:181], s[56:57], 0, v[154:155]
	s_add_i32 m0, s9, 0xc000
	ds_read_b128 v[174:177], v238
	ds_read_b128 v[184:187], v238 offset:1024
	ds_read_b128 v[188:191], v238 offset:2048
	ds_read_b128 v[192:195], v238 offset:3072
	ds_read_b128 v[196:199], v238 offset:4096
	ds_read_b128 v[200:203], v238 offset:5120
	ds_read_b128 v[204:207], v238 offset:6144
	ds_read_b128 v[208:211], v238 offset:7168
	global_load_lds_dwordx4 v[180:181], off
	v_lshl_add_u64 v[180:181], s[56:57], 0, v[156:157]
	s_add_i32 m0, s9, 0xe000
	s_nop 0
	global_load_lds_dwordx4 v[180:181], off
	s_add_u32 s2, s56, 0xffe00080
	s_addc_u32 s3, s57, -1
	s_cmpk_eq_i32 s64, 0x7c
	s_cselect_b32 s21, s18, s3
	s_cselect_b32 s20, s51, s2
	s_cselect_b32 s3, s49, s59
	s_cselect_b32 s2, s63, s58
	s_waitcnt vmcnt(8)
	s_waitcnt lgkmcnt(0)
	s_barrier
	s_setprio 1
	s_waitcnt lgkmcnt(0)
	v_mfma_f32_16x16x32_bf16 v[126:129], v[130:133], v[174:177], v[126:129]
	v_mfma_f32_16x16x32_bf16 v[122:125], v[138:141], v[174:177], v[122:125]
	v_mfma_f32_16x16x32_bf16 v[110:113], v[130:133], v[188:191], v[110:113]
	v_mfma_f32_16x16x32_bf16 v[106:109], v[138:141], v[188:191], v[106:109]
	v_mfma_f32_16x16x32_bf16 v[94:97], v[130:133], v[196:199], v[94:97]
	v_mfma_f32_16x16x32_bf16 v[90:93], v[138:141], v[196:199], v[90:93]
	v_mfma_f32_16x16x32_bf16 v[78:81], v[130:133], v[204:207], v[78:81]
	v_mfma_f32_16x16x32_bf16 v[74:77], v[138:141], v[204:207], v[74:77]
	v_mfma_f32_16x16x32_bf16 v[126:129], v[134:137], v[184:187], v[126:129]
	v_mfma_f32_16x16x32_bf16 v[122:125], v[142:145], v[184:187], v[122:125]
	v_mfma_f32_16x16x32_bf16 v[110:113], v[134:137], v[192:195], v[110:113]
	v_mfma_f32_16x16x32_bf16 v[106:109], v[142:145], v[192:195], v[106:109]
	v_mfma_f32_16x16x32_bf16 v[94:97], v[134:137], v[200:203], v[94:97]
	v_mfma_f32_16x16x32_bf16 v[90:93], v[142:145], v[200:203], v[90:93]
	v_mfma_f32_16x16x32_bf16 v[78:81], v[134:137], v[208:211], v[78:81]
	v_mfma_f32_16x16x32_bf16 v[74:77], v[142:145], v[208:211], v[74:77]
	s_setprio 0
	s_setprio 1
	v_mfma_f32_16x16x32_bf16 v[118:121], v[158:161], v[174:177], v[118:121]
	v_mfma_f32_16x16x32_bf16 v[114:117], v[166:169], v[174:177], v[114:117]
	v_mfma_f32_16x16x32_bf16 v[102:105], v[158:161], v[188:191], v[102:105]
	v_mfma_f32_16x16x32_bf16 v[98:101], v[166:169], v[188:191], v[98:101]
	v_mfma_f32_16x16x32_bf16 v[86:89], v[158:161], v[196:199], v[86:89]
	v_mfma_f32_16x16x32_bf16 v[82:85], v[166:169], v[196:199], v[82:85]
	v_mfma_f32_16x16x32_bf16 v[70:73], v[158:161], v[204:207], v[70:73]
	v_mfma_f32_16x16x32_bf16 v[66:69], v[166:169], v[204:207], v[66:69]
	v_mfma_f32_16x16x32_bf16 v[118:121], v[162:165], v[184:187], v[118:121]
	v_mfma_f32_16x16x32_bf16 v[114:117], v[170:173], v[184:187], v[114:117]
	v_mfma_f32_16x16x32_bf16 v[102:105], v[162:165], v[192:195], v[102:105]
	v_mfma_f32_16x16x32_bf16 v[98:101], v[170:173], v[192:195], v[98:101]
	v_mfma_f32_16x16x32_bf16 v[86:89], v[162:165], v[200:203], v[86:89]
	v_mfma_f32_16x16x32_bf16 v[82:85], v[170:173], v[200:203], v[82:85]
	v_mfma_f32_16x16x32_bf16 v[70:73], v[162:165], v[208:211], v[70:73]
	v_mfma_f32_16x16x32_bf16 v[66:69], v[170:173], v[208:211], v[66:69]
	s_setprio 0
	s_barrier
	s_add_i32 s65, s65, s24
	v_lshl_add_u64 v[180:181], s[2:3], 0, v[0:1]
	s_mov_b32 m0, s65
	ds_read_b128 v[174:177], v238 offset:16384
	ds_read_b128 v[184:187], v238 offset:17408
	ds_read_b128 v[188:191], v238 offset:18432
	ds_read_b128 v[192:195], v238 offset:19456
	ds_read_b128 v[196:199], v238 offset:20480
	ds_read_b128 v[200:203], v238 offset:21504
	ds_read_b128 v[204:207], v238 offset:22528
	ds_read_b128 v[208:211], v238 offset:23552
	global_load_lds_dwordx4 v[180:181], off
	s_add_i32 m0, s65, 0x2000
	s_add_u32 s70, s2, 0x200000
	v_lshl_add_u64 v[212:213], s[2:3], 0, v[150:151]
	s_addc_u32 s71, s3, 0
	s_add_i32 s65, s67, s24
	global_load_lds_dwordx4 v[212:213], off
	v_lshl_add_u64 v[214:215], s[70:71], 0, v[0:1]
	s_mov_b32 m0, s65
	v_lshl_add_u64 v[216:217], s[20:21], 0, v[148:149]
	global_load_lds_dwordx4 v[214:215], off
	v_lshl_add_u64 v[214:215], s[70:71], 0, v[150:151]
	s_add_i32 m0, s65, 0x2000
	s_nop 0
	global_load_lds_dwordx4 v[214:215], off
	v_lshl_add_u64 v[214:215], s[20:21], 0, v[146:147]
	s_mov_b32 m0, s9
	s_nop 0
	global_load_lds_dwordx4 v[214:215], off
	s_mov_b32 m0, s13
	s_nop 0
	global_load_lds_dwordx4 v[216:217], off
	s_waitcnt vmcnt(8)
	s_waitcnt lgkmcnt(0)
	s_barrier
; #define PG8_STAGE(bufoff, gbase, voff) do { _Pragma("unroll") for (int _i = 0; _i < 2; ++_i) \
;         __builtin_amdgcn_global_load_lds((const unsigned*)((const char*)(gbase) + (voff)[_i]), (PG8_LAS unsigned*)(lds + (bufoff) + ldsw + _i * 8192), 16, 0, 0); } while (0)
; #define PG8_LDA(dst, b, h) do { _Pragma("unroll") for (int m = 0; m < 4; ++m) _Pragma("unroll") for (int k = 0; k < 2; ++k) dst[m][k] = *(const PG8_LAS bf16x8*)(lds + PG8_SA(b, h) + aoff + m * 2048 + k * 1024); } while (0)
; #define PG8_LDB(dst, b, h) do { _Pragma("unroll") for (int n = 0; n < 2; ++n) _Pragma("unroll") for (int k = 0; k < 2; ++k) dst[n][k] = *(const PG8_LAS bf16x8*)(lds + PG8_SB(b, h) + boff + n * 2048 + k * 1024); } while (0)
; #define PG8_MMA(ai, bj, At, Bt) do { __builtin_amdgcn_s_setprio(1); _Pragma("unroll") for (int m = 0; m < 4; ++m) _Pragma("unroll") for (int n = 0; n < 2; ++n) _Pragma("unroll") for (int k = 0; k < 2; ++k) \
;         acc[ai][bj][m][n] = __builtin_amdgcn_mfma_f32_16x16x32_bf16(Bt[n][k], At[m][k], acc[ai][bj][m][n], 0, 0, 0); __builtin_amdgcn_s_setprio(0); } while (0)
; template <class Epi, class Sched, bool ALIGN_EPI = true, bool SP2 = true, bool GS = false>
; __device__ __forceinline__ void gemm_phase(PG8_LAS unsigned char* lds, const Gemm g, const Sched& S, const Epi& E, const float* gs_ss = nullptr) {
;     ...
;             PG8_LDB(B0, 0, 0); PG8_LDB(B1, 0, 1); PG8_SCHED; PG8_LDA(At, 0, 0); PG8_STAGE(PG8_SA(1, 1), a1 + hstep, voffA);
;             PG8_WAIT_V(8); PG8_WAIT_L(0); PG8_BAR; PG8_MMA(0, 0, At, B0); PG8_MMA(0, 1, At, B1); PG8_BAR; PG8_SCHED;
;             PG8_LDA(At, 0, 1); PG8_STAGE(PG8_SB(0, 0), b2, voffB); PG8_STAGE(PG8_SB(0, 1), b2 + hstep, voffB); PG8_STAGE(PG8_SA(0, 0), a2, voffA);
;             PG8_WAIT_V(8); PG8_WAIT_L(0); PG8_BAR; PG8_MMA(1, 0, At, B0); PG8_MMA(1, 1, At, B1); PG8_BAR; PG8_SCHED;
;             PG8_LDB(B0, 1, 0); PG8_LDB(B1, 1, 1); PG8_SCHED; PG8_LDA(At, 1, 0); PG8_STAGE(PG8_SA(0, 1), a2 + hstep, voffA);
;             PG8_WAIT_V(8); PG8_WAIT_L(0); PG8_BAR; PG8_MMA(0, 0, At, B0); PG8_MMA(0, 1, At, B1); PG8_BAR; PG8_SCHED;
;             PG8_LDA(At, 1, 1); PG8_STAGE(PG8_SB(1, 0), b3, voffB); PG8_STAGE(PG8_SB(1, 1), b3 + hstep, voffB); PG8_STAGE(PG8_SA(1, 0), a3, voffA);
;             PG8_WAIT_V(8); PG8_WAIT_L(0); PG8_BAR; PG8_MMA(1, 0, At, B0); PG8_MMA(1, 1, At, B1); PG8_BAR; PG8_SCHED;
	s_setprio 1
	s_waitcnt lgkmcnt(0)
	v_mfma_f32_16x16x32_bf16 v[62:65], v[130:133], v[174:177], v[62:65]
	v_mfma_f32_16x16x32_bf16 v[58:61], v[138:141], v[174:177], v[58:61]
	v_mfma_f32_16x16x32_bf16 v[46:49], v[130:133], v[188:191], v[46:49]
	v_mfma_f32_16x16x32_bf16 v[42:45], v[138:141], v[188:191], v[42:45]
	v_mfma_f32_16x16x32_bf16 v[30:33], v[130:133], v[196:199], v[30:33]
	v_mfma_f32_16x16x32_bf16 v[26:29], v[138:141], v[196:199], v[26:29]
	v_mfma_f32_16x16x32_bf16 v[14:17], v[130:133], v[204:207], v[14:17]
	v_mfma_f32_16x16x32_bf16 v[10:13], v[138:141], v[204:207], v[10:13]
	v_mfma_f32_16x16x32_bf16 v[62:65], v[134:137], v[184:187], v[62:65]
	v_mfma_f32_16x16x32_bf16 v[58:61], v[142:145], v[184:187], v[58:61]
	v_mfma_f32_16x16x32_bf16 v[46:49], v[134:137], v[192:195], v[46:49]
	v_mfma_f32_16x16x32_bf16 v[42:45], v[142:145], v[192:195], v[42:45]
	v_mfma_f32_16x16x32_bf16 v[30:33], v[134:137], v[200:203], v[30:33]
	v_mfma_f32_16x16x32_bf16 v[26:29], v[142:145], v[200:203], v[26:29]
	v_mfma_f32_16x16x32_bf16 v[14:17], v[134:137], v[208:211], v[14:17]
	v_mfma_f32_16x16x32_bf16 v[10:13], v[142:145], v[208:211], v[10:13]
	s_setprio 0
	s_setprio 1
	v_mfma_f32_16x16x32_bf16 v[54:57], v[158:161], v[174:177], v[54:57]
	v_mfma_f32_16x16x32_bf16 v[50:53], v[166:169], v[174:177], v[50:53]
	v_mfma_f32_16x16x32_bf16 v[38:41], v[158:161], v[188:191], v[38:41]
	v_mfma_f32_16x16x32_bf16 v[34:37], v[166:169], v[188:191], v[34:37]
	v_mfma_f32_16x16x32_bf16 v[22:25], v[158:161], v[196:199], v[22:25]
	v_mfma_f32_16x16x32_bf16 v[18:21], v[166:169], v[196:199], v[18:21]
	v_mfma_f32_16x16x32_bf16 v[6:9], v[158:161], v[204:207], v[6:9]
	v_mfma_f32_16x16x32_bf16 v[2:5], v[166:169], v[204:207], v[2:5]
	v_mfma_f32_16x16x32_bf16 v[54:57], v[162:165], v[184:187], v[54:57]
	v_mfma_f32_16x16x32_bf16 v[50:53], v[170:173], v[184:187], v[50:53]
	v_mfma_f32_16x16x32_bf16 v[38:41], v[162:165], v[192:195], v[38:41]
	v_mfma_f32_16x16x32_bf16 v[34:37], v[170:173], v[192:195], v[34:37]
	v_mfma_f32_16x16x32_bf16 v[22:25], v[162:165], v[200:203], v[22:25]
	v_mfma_f32_16x16x32_bf16 v[18:21], v[170:173], v[200:203], v[18:21]
	v_mfma_f32_16x16x32_bf16 v[6:9], v[162:165], v[208:211], v[6:9]
	v_mfma_f32_16x16x32_bf16 v[2:5], v[170:173], v[208:211], v[2:5]
	s_setprio 0
	s_barrier
	s_add_i32 s65, 0, 0x18000
	s_add_i32 s67, 0, 0x1c000
	v_add_u32_e32 v142, s65, v236
	v_add_u32_e32 v170, s67, v236
	ds_read_b128 v[130:133], v142
	ds_read_b128 v[134:137], v142 offset:1024
	ds_read_b128 v[138:141], v142 offset:2048
	ds_read_b128 v[142:145], v142 offset:3072
	ds_read_b128 v[158:161], v170
	ds_read_b128 v[162:165], v170 offset:1024
	ds_read_b128 v[166:169], v170 offset:2048
	ds_read_b128 v[170:173], v170 offset:3072
	s_add_u32 s20, s20, 0x200000
	s_addc_u32 s21, s21, 0
	s_mov_b32 m0, s25
	v_lshl_add_u64 v[218:219], s[20:21], 0, v[146:147]
	ds_read_b128 v[174:177], v238 offset:32768
	ds_read_b128 v[184:187], v238 offset:33792
	ds_read_b128 v[188:191], v238 offset:34816
	ds_read_b128 v[192:195], v238 offset:35840
	ds_read_b128 v[196:199], v238 offset:36864
	ds_read_b128 v[200:203], v238 offset:37888
	ds_read_b128 v[204:207], v238 offset:38912
	ds_read_b128 v[208:211], v238 offset:39936
	global_load_lds_dwordx4 v[218:219], off
	v_lshl_add_u64 v[218:219], s[20:21], 0, v[148:149]
	s_mov_b32 m0, s30
	s_nop 0
	global_load_lds_dwordx4 v[218:219], off
	s_waitcnt vmcnt(8)
	s_waitcnt lgkmcnt(0)
	s_barrier
	s_setprio 1
	s_waitcnt lgkmcnt(0)
	v_mfma_f32_16x16x32_bf16 v[126:129], v[130:133], v[174:177], v[126:129]
	v_mfma_f32_16x16x32_bf16 v[122:125], v[138:141], v[174:177], v[122:125]
	v_mfma_f32_16x16x32_bf16 v[110:113], v[130:133], v[188:191], v[110:113]
	v_mfma_f32_16x16x32_bf16 v[106:109], v[138:141], v[188:191], v[106:109]
	v_mfma_f32_16x16x32_bf16 v[94:97], v[130:133], v[196:199], v[94:97]
	v_mfma_f32_16x16x32_bf16 v[90:93], v[138:141], v[196:199], v[90:93]
	v_mfma_f32_16x16x32_bf16 v[78:81], v[130:133], v[204:207], v[78:81]
	v_mfma_f32_16x16x32_bf16 v[74:77], v[138:141], v[204:207], v[74:77]
	v_mfma_f32_16x16x32_bf16 v[126:129], v[134:137], v[184:187], v[126:129]
	v_mfma_f32_16x16x32_bf16 v[122:125], v[142:145], v[184:187], v[122:125]
	v_mfma_f32_16x16x32_bf16 v[110:113], v[134:137], v[192:195], v[110:113]
	v_mfma_f32_16x16x32_bf16 v[106:109], v[142:145], v[192:195], v[106:109]
	v_mfma_f32_16x16x32_bf16 v[94:97], v[134:137], v[200:203], v[94:97]
	v_mfma_f32_16x16x32_bf16 v[90:93], v[142:145], v[200:203], v[90:93]
	v_mfma_f32_16x16x32_bf16 v[78:81], v[134:137], v[208:211], v[78:81]
	v_mfma_f32_16x16x32_bf16 v[74:77], v[142:145], v[208:211], v[74:77]
	s_setprio 0
	s_setprio 1
	v_mfma_f32_16x16x32_bf16 v[118:121], v[158:161], v[174:177], v[118:121]
	v_mfma_f32_16x16x32_bf16 v[114:117], v[166:169], v[174:177], v[114:117]
	v_mfma_f32_16x16x32_bf16 v[102:105], v[158:161], v[188:191], v[102:105]
	v_mfma_f32_16x16x32_bf16 v[98:101], v[166:169], v[188:191], v[98:101]
	v_mfma_f32_16x16x32_bf16 v[86:89], v[158:161], v[196:199], v[86:89]
	v_mfma_f32_16x16x32_bf16 v[82:85], v[166:169], v[196:199], v[82:85]
	v_mfma_f32_16x16x32_bf16 v[70:73], v[158:161], v[204:207], v[70:73]
	v_mfma_f32_16x16x32_bf16 v[66:69], v[166:169], v[204:207], v[66:69]
	v_mfma_f32_16x16x32_bf16 v[118:121], v[162:165], v[184:187], v[118:121]
	v_mfma_f32_16x16x32_bf16 v[114:117], v[170:173], v[184:187], v[114:117]
	v_mfma_f32_16x16x32_bf16 v[102:105], v[162:165], v[192:195], v[102:105]
	v_mfma_f32_16x16x32_bf16 v[98:101], v[170:173], v[192:195], v[98:101]
	v_mfma_f32_16x16x32_bf16 v[86:89], v[162:165], v[200:203], v[86:89]
	v_mfma_f32_16x16x32_bf16 v[82:85], v[170:173], v[200:203], v[82:85]
	v_mfma_f32_16x16x32_bf16 v[70:73], v[162:165], v[208:211], v[70:73]
	v_mfma_f32_16x16x32_bf16 v[66:69], v[170:173], v[208:211], v[66:69]
	s_setprio 0
	s_barrier
; #define PG8_STAGE(bufoff, gbase, voff) do { _Pragma("unroll") for (int _i = 0; _i < 2; ++_i) \
;         __builtin_amdgcn_global_load_lds((const unsigned*)((const char*)(gbase) + (voff)[_i]), (PG8_LAS unsigned*)(lds + (bufoff) + ldsw + _i * 8192), 16, 0, 0); } while (0)
; #define PG8_LDA(dst, b, h) do { _Pragma("unroll") for (int m = 0; m < 4; ++m) _Pragma("unroll") for (int k = 0; k < 2; ++k) dst[m][k] = *(const PG8_LAS bf16x8*)(lds + PG8_SA(b, h) + aoff + m * 2048 + k * 1024); } while (0)
; #define PG8_MMA(ai, bj, At, Bt) do { __builtin_amdgcn_s_setprio(1); _Pragma("unroll") for (int m = 0; m < 4; ++m) _Pragma("unroll") for (int n = 0; n < 2; ++n) _Pragma("unroll") for (int k = 0; k < 2; ++k) \
;         acc[ai][bj][m][n] = __builtin_amdgcn_mfma_f32_16x16x32_bf16(Bt[n][k], At[m][k], acc[ai][bj][m][n], 0, 0, 0); __builtin_amdgcn_s_setprio(0); } while (0)
; #define PG8_WAIT_V(n) asm volatile("s_waitcnt vmcnt(" #n ")" ::: "memory")
; #define PG8_WAIT_L(n) asm volatile("s_waitcnt lgkmcnt(" #n ")" ::: "memory")
; #define PG8_BAR __builtin_amdgcn_s_barrier()
; #define PG8_SCHED __builtin_amdgcn_sched_barrier(0)
; template <class Epi, class Sched, bool ALIGN_EPI = true, bool SP2 = true, bool GS = false>
; __device__ __forceinline__ void gemm_phase(PG8_LAS unsigned char* lds, const Gemm g, const Sched& S, const Epi& E, const float* gs_ss = nullptr) {
;     ...
;         for (int t = 0; t < nt; t += 2) {
;             const bool last = (t == nt - 2);
;             const char* a1 = cA + (size_t)(t + 1) * kstep;
;             const char* a2 = last ? nA : cA + (size_t)(t + 2) * kstep; const char* b2 = last ? nB : cB + (size_t)(t + 2) * kstep;
;             const char* a3 = a2 + kstep; const char* b3 = b2 + kstep;
;     ...
;             PG8_LDA(At, 1, 1); PG8_STAGE(PG8_SB(1, 0), b3, voffB); PG8_STAGE(PG8_SB(1, 1), b3 + hstep, voffB); PG8_STAGE(PG8_SA(1, 0), a3, voffA);
;             PG8_WAIT_V(8); PG8_WAIT_L(0); PG8_BAR; PG8_MMA(1, 0, At, B0); PG8_MMA(1, 1, At, B1); PG8_BAR; PG8_SCHED;
	s_add_i32 s20, s65, s24
	v_lshl_add_u64 v[180:181], v[180:181], 0, s[26:27]
	s_mov_b32 m0, s20
	ds_read_b128 v[174:177], v238 offset:49152
	ds_read_b128 v[184:187], v238 offset:50176
	ds_read_b128 v[188:191], v238 offset:51200
	ds_read_b128 v[192:195], v238 offset:52224
	ds_read_b128 v[196:199], v238 offset:53248
	ds_read_b128 v[200:203], v238 offset:54272
	ds_read_b128 v[204:207], v238 offset:55296
	ds_read_b128 v[208:211], v238 offset:56320
	global_load_lds_dwordx4 v[180:181], off
	s_add_i32 m0, s20, 0x2000
	s_add_u32 s2, s2, 0x200080
	v_lshl_add_u64 v[180:181], v[212:213], 0, s[26:27]
	s_addc_u32 s3, s3, 0
	s_add_i32 s20, s67, s24
	global_load_lds_dwordx4 v[180:181], off
	v_lshl_add_u64 v[180:181], s[2:3], 0, v[0:1]
	s_mov_b32 m0, s20
	s_nop 0
	global_load_lds_dwordx4 v[180:181], off
	v_lshl_add_u64 v[180:181], s[2:3], 0, v[150:151]
	s_add_i32 m0, s20, 0x2000
	s_nop 0
	global_load_lds_dwordx4 v[180:181], off
	v_lshl_add_u64 v[180:181], v[214:215], 0, s[26:27]
	s_mov_b32 m0, s37
	s_nop 0
	global_load_lds_dwordx4 v[180:181], off
	v_lshl_add_u64 v[180:181], v[216:217], 0, s[26:27]
	s_mov_b32 m0, s60
	s_nop 0
	global_load_lds_dwordx4 v[180:181], off
	s_waitcnt vmcnt(8)
	s_waitcnt lgkmcnt(0)
	s_barrier
	s_setprio 1
	s_waitcnt lgkmcnt(0)
	v_mfma_f32_16x16x32_bf16 v[62:65], v[130:133], v[174:177], v[62:65]
	v_mfma_f32_16x16x32_bf16 v[58:61], v[138:141], v[174:177], v[58:61]
	v_mfma_f32_16x16x32_bf16 v[46:49], v[130:133], v[188:191], v[46:49]
	v_mfma_f32_16x16x32_bf16 v[42:45], v[138:141], v[188:191], v[42:45]
	v_mfma_f32_16x16x32_bf16 v[30:33], v[130:133], v[196:199], v[30:33]
	v_mfma_f32_16x16x32_bf16 v[26:29], v[138:141], v[196:199], v[26:29]
	v_mfma_f32_16x16x32_bf16 v[14:17], v[130:133], v[204:207], v[14:17]
	v_mfma_f32_16x16x32_bf16 v[10:13], v[138:141], v[204:207], v[10:13]
	v_mfma_f32_16x16x32_bf16 v[62:65], v[134:137], v[184:187], v[62:65]
	v_mfma_f32_16x16x32_bf16 v[58:61], v[142:145], v[184:187], v[58:61]
	v_mfma_f32_16x16x32_bf16 v[46:49], v[134:137], v[192:195], v[46:49]
	v_mfma_f32_16x16x32_bf16 v[42:45], v[142:145], v[192:195], v[42:45]
	v_mfma_f32_16x16x32_bf16 v[30:33], v[134:137], v[200:203], v[30:33]
	v_mfma_f32_16x16x32_bf16 v[26:29], v[142:145], v[200:203], v[26:29]
	v_mfma_f32_16x16x32_bf16 v[14:17], v[134:137], v[208:211], v[14:17]
	v_mfma_f32_16x16x32_bf16 v[10:13], v[142:145], v[208:211], v[10:13]
	s_setprio 0
	s_setprio 1
	v_mfma_f32_16x16x32_bf16 v[54:57], v[158:161], v[174:177], v[54:57]
	v_mfma_f32_16x16x32_bf16 v[50:53], v[166:169], v[174:177], v[50:53]
	v_mfma_f32_16x16x32_bf16 v[38:41], v[158:161], v[188:191], v[38:41]
	v_mfma_f32_16x16x32_bf16 v[34:37], v[166:169], v[188:191], v[34:37]
	v_mfma_f32_16x16x32_bf16 v[22:25], v[158:161], v[196:199], v[22:25]
	v_mfma_f32_16x16x32_bf16 v[18:21], v[166:169], v[196:199], v[18:21]
	v_mfma_f32_16x16x32_bf16 v[6:9], v[158:161], v[204:207], v[6:9]
	v_mfma_f32_16x16x32_bf16 v[2:5], v[166:169], v[204:207], v[2:5]
	v_mfma_f32_16x16x32_bf16 v[54:57], v[162:165], v[184:187], v[54:57]
	v_mfma_f32_16x16x32_bf16 v[50:53], v[170:173], v[184:187], v[50:53]
	v_mfma_f32_16x16x32_bf16 v[38:41], v[162:165], v[192:195], v[38:41]
	v_mfma_f32_16x16x32_bf16 v[34:37], v[170:173], v[192:195], v[34:37]
	v_mfma_f32_16x16x32_bf16 v[22:25], v[162:165], v[200:203], v[22:25]
	v_mfma_f32_16x16x32_bf16 v[18:21], v[170:173], v[200:203], v[18:21]
	v_mfma_f32_16x16x32_bf16 v[6:9], v[162:165], v[208:211], v[6:9]
	v_mfma_f32_16x16x32_bf16 v[2:5], v[170:173], v[208:211], v[2:5]
	s_setprio 0
	s_add_i32 s64, s64, 2
	s_add_u32 s56, s56, 0x100
	s_addc_u32 s57, s57, 0
	s_add_u32 s58, s58, 0x100
	s_addc_u32 s59, s59, 0
	s_cmpk_gt_u32 s64, 0x7d
	s_barrier
	s_cbranch_scc0 .LBB0_1422
	s_and_b64 vcc, exec, s[46:47]
	s_cbranch_vccz .LBB0_1425
	s_barrier
